# hand-scheduled scan-wave chunk body, scan-wave priority, merge-phase partial loads hoisted (on top of LoRA staging batch)
# speedup vs baseline: 1.0500x; 1.0040x over previous
; template <int NI>
; DEVINL void gemm_kloop(const bf16_t* __restrict__ A, int lda, const bf16_t* __restrict__ Bt, int ldb, int K, int m0, int n0,
;                        unsigned char* lds, f32x16 (&acc)[NI][2]) {
;     const int tid = TID, lane = tid & 63, w = tid >> 6, wm = w & 3, wn = w >> 2, r = lane & 31, h = lane >> 5;
;     const int lrow = tid >> 3, cg = (tid & 7) ^ ((tid >> 4) & 7);
;     const bf16_t* ga = A + (size_t)(m0 + lrow) * lda + cg * 8;
;     const bf16_t* gb = Bt + (size_t)(n0 + lrow) * ldb + cg * 8;
;     unsigned char* da = lds + tid * 16;
;     unsigned char* db = lds + A_ST + tid * 16;
;     ...
;     const int nt = K >> 6;
;     asm volatile("s_waitcnt lgkmcnt(0)" ::: "memory");
;     __builtin_amdgcn_s_barrier();
;     GEMM_ISSUE(0, 0);
;     if (nt > 1) GEMM_ISSUE(1, 1);
;     const int sw = (r >> 1) & 7;
;     int o4[4];
; #pragma unroll
;     for (int ks = 0; ks < 4; ++ks) o4[ks] = ((ks * 2 + h) ^ sw) * 16;
;     int cur = 0;
;     auto compute = [&](int st_) {
;         const unsigned char* pa = lds + st_ * STAGE + (wm * 64 + r) * 128;
;         const unsigned char* pb = lds + st_ * STAGE + A_ST + (wn * 32 * NI + r) * 128;
;         bf16x8 af[2][2], bfr[2][NI];
; #pragma unroll
;         for (int i = 0; i < 2; ++i) af[0][i] = *(const bf16x8*)(pa + i * 32 * 128 + o4[0]);
; #pragma unroll
;         for (int i = 0; i < NI; ++i) bfr[0][i] = *(const bf16x8*)(pb + i * 32 * 128 + o4[0]);
; #pragma unroll
;         for (int ks = 0; ks < 4; ++ks) {
;             if (ks < 3) {
; #pragma unroll
;                 for (int i = 0; i < 2; ++i) af[(ks + 1) & 1][i] = *(const bf16x8*)(pa + i * 32 * 128 + o4[ks + 1]);
; #pragma unroll
;                 for (int i = 0; i < NI; ++i) bfr[(ks + 1) & 1][i] = *(const bf16x8*)(pb + i * 32 * 128 + o4[ks + 1]);
;             }
; #pragma unroll
;             for (int ni = 0; ni < NI; ++ni)
; #pragma unroll
;                 for (int mi = 0; mi < 2; ++mi) acc[ni][mi] = MFMA32(bfr[ks & 1][ni], af[ks & 1][mi], acc[ni][mi]);
;         }
;     };
;     int t = 0;
;     for (; t + 2 < nt; ++t) {
;         if (NI == 2) asm volatile("s_waitcnt vmcnt(6)" ::: "memory"); else asm volatile("s_waitcnt vmcnt(5)" ::: "memory");
;         __builtin_amdgcn_s_barrier();
;         { const int s2 = (cur >= 1) ? cur - 1 : 2; GEMM_ISSUE(s2, t + 2); }
;         compute(cur);
;         cur = (cur == 2) ? 0 : cur + 1;
;     }
.LBB0_89:
	s_mul_hi_i32 s4, s1, 0x78787879
	s_lshr_b32 s5, s4, 31
	s_ashr_i32 s4, s4, 8
	s_add_i32 s4, s4, s5
	s_mul_i32 s5, s4, 0xfffffde0
	s_add_i32 s5, s1, s5
	s_ashr_i32 s6, s5, 31
	s_lshr_b32 s6, s6, 29
	s_add_i32 s6, s5, s6
	s_and_b32 s7, s6, 0x1fffff8
	s_lshl_b32 s6, s6, 5
	s_waitcnt vmcnt(0)
	v_mov_b32_e32 v0, v160
	v_mov_b32_e32 v1, v160
	s_and_b32 s6, s6, 0xffffff00
	v_mov_b32_e32 v6, v160
	v_and_b32_e32 v2, 0xc0, v1
	v_or_b32_e32 v74, s6, v2
	v_and_or_b32 v75, v0, 31, v74
	v_lshrrev_b32_e32 v0, 3, v0
	v_and_b32_e32 v80, 4, v0
	v_ashrrev_i32_e32 v1, 2, v1
	v_ashrrev_i32_e32 v2, 3, v6
	v_lshrrev_b32_e32 v0, 4, v6
	v_xor_b32_e32 v3, v0, v6
	v_add_u32_e32 v0, s6, v2
	s_sub_i32 s5, s5, s7
	v_and_b32_e32 v81, 0xffffffc0, v1
	v_ashrrev_i32_e32 v1, 31, v0
	s_lshl_b32 s4, s4, 10
	s_lshl_b32 s5, s5, 7
	v_lshlrev_b64 v[0:1], 10, v[0:1]
	v_lshlrev_b32_e32 v3, 4, v3
	s_add_i32 s4, s5, s4
	v_lshl_add_u64 v[0:1], s[36:37], 0, v[0:1]
	v_and_b32_e32 v64, 0x70, v3
	v_lshl_add_u64 v[76:77], v[0:1], 0, v[64:65]
	v_add_u32_e32 v0, s4, v2
	v_ashrrev_i32_e32 v1, 31, v0
	v_lshlrev_b64 v[0:1], 10, v[0:1]
	v_lshl_add_u64 v[2:3], s[52:53], 0, v[0:1]
	v_lshl_add_u32 v0, v6, 4, 0
	v_add_u32_e32 v7, 0x2000, v0
	v_readfirstlane_b32 s16, v0
	s_mov_b32 m0, s16
	v_readfirstlane_b32 s15, v7
	v_add_u32_e32 v7, 0x4000, v0
	s_waitcnt lgkmcnt(0)
	s_barrier
	global_load_lds_dwordx4 v[76:77], off
	v_lshl_add_u64 v[4:5], v[76:77], 0, s[74:75]
	s_mov_b32 m0, s15
	v_readfirstlane_b32 s14, v7
	v_add_u32_e32 v7, 0x6000, v0
	v_add_u32_e32 v1, 0x8000, v0
	global_load_lds_dwordx4 v[4:5], off
	v_lshl_add_u64 v[4:5], v[76:77], 0, s[68:69]
	s_mov_b32 m0, s14
	s_mov_b64 s[6:7], 0x30000
	v_readfirstlane_b32 s13, v7
	global_load_lds_dwordx4 v[4:5], off
	v_lshl_add_u64 v[4:5], v[76:77], 0, s[6:7]
	s_mov_b32 m0, s13
	v_readfirstlane_b32 s12, v1
	v_add_u32_e32 v1, 0xa000, v0
	global_load_lds_dwordx4 v[4:5], off
	v_lshl_add_u64 v[78:79], v[2:3], 0, v[64:65]
	s_mov_b32 m0, s12
	v_readfirstlane_b32 s11, v1
	v_add_u32_e32 v1, 0xc000, v0
	global_load_lds_dwordx4 v[78:79], off
	v_lshl_add_u64 v[2:3], v[78:79], 0, s[74:75]
	s_mov_b32 m0, s11
	v_readfirstlane_b32 s10, v1
	v_add_u32_e32 v1, 0xe000, v0
	global_load_lds_dwordx4 v[2:3], off
	v_lshl_add_u64 v[2:3], v[76:77], 0, s[92:93]
	s_mov_b32 m0, s10
	v_readfirstlane_b32 s9, v1
	v_add_u32_e32 v1, 0x10000, v0
	global_load_lds_dwordx4 v[2:3], off
	v_lshl_add_u64 v[2:3], v[76:77], 0, s[76:77]
	s_mov_b32 m0, s9
	v_readfirstlane_b32 s8, v1
	global_load_lds_dwordx4 v[2:3], off
	v_lshl_add_u64 v[2:3], v[76:77], 0, s[60:61]
	s_mov_b32 m0, s8
	s_mov_b64 s[6:7], 0x30080
	v_add_u32_e32 v1, 0x12000, v0
	global_load_lds_dwordx4 v[2:3], off
	v_lshl_add_u64 v[2:3], v[76:77], 0, s[6:7]
	v_readfirstlane_b32 s7, v1
	v_add_u32_e32 v1, 0x14000, v0
	s_mov_b32 m0, s7
	v_readfirstlane_b32 s6, v1
	v_add_u32_e32 v1, 0x16000, v0
	global_load_lds_dwordx4 v[2:3], off
	v_lshl_add_u64 v[2:3], v[78:79], 0, s[92:93]
	s_mov_b32 m0, s6
	v_readfirstlane_b32 s5, v1
	global_load_lds_dwordx4 v[2:3], off
	v_lshl_add_u64 v[2:3], v[78:79], 0, s[76:77]
	s_mov_b32 m0, s5
	v_lshrrev_b32_e32 v1, 5, v6
	global_load_lds_dwordx4 v[2:3], off
	v_bfe_u32 v2, v6, 5, 1
	v_bfe_u32 v3, v6, 1, 3
	v_bitop3_b32 v4, v2, v3, 6 bitop3:0x36
	v_bitop3_b32 v1, v1, v3, 1 bitop3:0x6c
	v_lshlrev_b32_e32 v90, 4, v4
	v_bitop3_b32 v4, v2, v3, 4 bitop3:0x36
	v_bitop3_b32 v2, v2, v3, 2 bitop3:0x36
	v_lshlrev_b32_e32 v94, 4, v1
	v_lshlrev_b32_e32 v1, 7, v6
	v_lshlrev_b32_e32 v93, 4, v2
	v_and_b32_e32 v2, 0xf80, v1
	v_and_b32_e32 v96, 0x6f80, v1
	v_lshlrev_b32_e32 v1, 5, v6
	v_and_or_b32 v95, v1, s55, v2
	v_add_u32_e32 v1, 0x18000, v0
	v_lshl_add_u64 v[2:3], v[76:77], 0, s[84:85]
	v_readfirstlane_b32 s19, v1
	v_add_u32_e32 v1, 0x1a000, v0
	s_mov_b32 m0, s19
	v_readfirstlane_b32 s18, v1
	s_waitcnt vmcnt(6)
	s_barrier
	global_load_lds_dwordx4 v[2:3], off
	v_lshl_add_u64 v[2:3], v[76:77], 0, s[78:79]
	s_mov_b32 m0, s18
	s_mov_b64 s[20:21], 0x20100
	v_add_u32_e32 v1, 0x1c000, v0
	global_load_lds_dwordx4 v[2:3], off
	v_lshl_add_u64 v[2:3], v[76:77], 0, s[20:21]
	v_readfirstlane_b32 s20, v1
	v_add_u32_e32 v1, 0x1e000, v0
	s_mov_b32 m0, s20
	s_mov_b64 s[24:25], 0x30100
	v_readfirstlane_b32 s21, v1
	v_add_u32_e32 v1, 0x20000, v0
	global_load_lds_dwordx4 v[2:3], off
	v_lshl_add_u64 v[2:3], v[76:77], 0, s[24:25]
	s_mov_b32 m0, s21
	v_readfirstlane_b32 s24, v1
	v_add_u32_e32 v0, 0x22000, v0
	global_load_lds_dwordx4 v[2:3], off
	v_lshl_add_u64 v[2:3], v[78:79], 0, s[84:85]
	s_mov_b32 m0, s24
	v_readfirstlane_b32 s17, v0
	global_load_lds_dwordx4 v[2:3], off
	v_lshl_add_u64 v[2:3], v[78:79], 0, s[78:79]
	s_mov_b32 m0, s17
	v_add_u32_e32 v87, 0, v96
	v_add_u32_e32 v88, 0, v95
	global_load_lds_dwordx4 v[2:3], off
	v_add_u32_e32 v64, v87, v94
	v_add_u32_e32 v82, v88, v94
	v_lshlrev_b32_e32 v91, 4, v4
	ds_read_b128 v[4:7], v64
	ds_read_b128 v[0:3], v64 offset:4096
	ds_read_b128 v[8:11], v82 offset:32768
	ds_read_b128 v[12:15], v82 offset:36864
	s_waitcnt lgkmcnt(0)
	v_mfma_f32_32x32x16_bf16 v[48:63], v[8:11], v[4:7], 0
	v_add_u32_e32 v83, v87, v93
	v_add_u32_e32 v84, v88, v93
	ds_read_b128 v[66:69], v83
	ds_read_b128 v[70:73], v83 offset:4096
	ds_read_b128 v[98:101], v84 offset:32768
	ds_read_b128 v[102:105], v84 offset:36864
	v_add_u32_e32 v85, v87, v91
	v_add_u32_e32 v86, v88, v91
	ds_read_b128 v[106:109], v85
	ds_read_b128 v[110:113], v85 offset:4096
	v_mfma_f32_32x32x16_bf16 v[32:47], v[12:15], v[4:7], 0
	ds_read_b128 v[114:117], v86 offset:32768
	ds_read_b128 v[118:121], v86 offset:36864
	v_add_u32_e32 v87, v87, v90
	v_add_u32_e32 v88, v88, v90
	s_mov_b32 m0, s16
	s_mov_b64 vcc, 0x30180
	s_add_i32 s25, 0, 0x14000
	v_add_u32_e32 v97, s25, v95
	v_mfma_f32_32x32x16_bf16 v[16:31], v[8:11], v[0:3], 0
	v_add_u32_e32 v89, v97, v94
	v_add_u32_e32 v92, v97, v93
	s_add_i32 s25, 0, 0x18000
	v_add_u32_e32 v128, s25, v96
	v_add_u32_e32 v129, s42, v95
	s_add_i32 s1, s1, s70
	s_cmp_ge_i32 s1, s54
	v_mfma_f32_32x32x16_bf16 v[0:15], v[12:15], v[0:3], 0
	s_waitcnt lgkmcnt(0)
	v_mfma_f32_32x32x16_bf16 v[48:63], v[98:101], v[66:69], v[48:63]
	v_mfma_f32_32x32x16_bf16 v[32:47], v[102:105], v[66:69], v[32:47]
	v_mfma_f32_32x32x16_bf16 v[16:31], v[98:101], v[70:73], v[16:31]
	v_mfma_f32_32x32x16_bf16 v[0:15], v[102:105], v[70:73], v[0:15]
	ds_read_b128 v[66:69], v87
	ds_read_b128 v[70:73], v87 offset:4096
	ds_read_b128 v[98:101], v88 offset:32768
	ds_read_b128 v[102:105], v88 offset:36864
	s_waitcnt vmcnt(6)
	s_barrier
; #define MFMA32(a, b, c) __builtin_amdgcn_mfma_f32_32x32x16_bf16((a), (b), (c), 0, 0, 0)
; template <int NI>
; DEVINL void gemm_kloop(const bf16_t* __restrict__ A, int lda, const bf16_t* __restrict__ Bt, int ldb, int K, int m0, int n0,
;                        unsigned char* lds, f32x16 (&acc)[NI][2]) {
;     ...
;     auto compute = [&](int st_) {
;         const unsigned char* pa = lds + st_ * STAGE + (wm * 64 + r) * 128;
;         const unsigned char* pb = lds + st_ * STAGE + A_ST + (wn * 32 * NI + r) * 128;
;         bf16x8 af[2][2], bfr[2][NI];
; #pragma unroll
;         for (int i = 0; i < 2; ++i) af[0][i] = *(const bf16x8*)(pa + i * 32 * 128 + o4[0]);
; #pragma unroll
;         for (int i = 0; i < NI; ++i) bfr[0][i] = *(const bf16x8*)(pb + i * 32 * 128 + o4[0]);
; #pragma unroll
;         for (int ks = 0; ks < 4; ++ks) {
;             if (ks < 3) {
; #pragma unroll
;                 for (int i = 0; i < 2; ++i) af[(ks + 1) & 1][i] = *(const bf16x8*)(pa + i * 32 * 128 + o4[ks + 1]);
; #pragma unroll
;                 for (int i = 0; i < NI; ++i) bfr[(ks + 1) & 1][i] = *(const bf16x8*)(pb + i * 32 * 128 + o4[ks + 1]);
;             }
; #pragma unroll
;             for (int ni = 0; ni < NI; ++ni)
; #pragma unroll
;                 for (int mi = 0; mi < 2; ++mi) acc[ni][mi] = MFMA32(bfr[ks & 1][ni], af[ks & 1][mi], acc[ni][mi]);
;         }
;     };
;     int t = 0;
;     for (; t + 2 < nt; ++t) {
;         if (NI == 2) asm volatile("s_waitcnt vmcnt(6)" ::: "memory"); else asm volatile("s_waitcnt vmcnt(5)" ::: "memory");
;         __builtin_amdgcn_s_barrier();
;         { const int s2 = (cur >= 1) ? cur - 1 : 2; GEMM_ISSUE(s2, t + 2); }
;         compute(cur);
;         cur = (cur == 2) ? 0 : cur + 1;
;     }
	v_mfma_f32_32x32x16_bf16 v[48:63], v[114:117], v[106:109], v[48:63]
	v_mfma_f32_32x32x16_bf16 v[32:47], v[118:121], v[106:109], v[32:47]
	v_mfma_f32_32x32x16_bf16 v[16:31], v[114:117], v[110:113], v[16:31]
	v_mfma_f32_32x32x16_bf16 v[0:15], v[118:121], v[110:113], v[0:15]
	s_waitcnt lgkmcnt(0)
	v_mfma_f32_32x32x16_bf16 v[48:63], v[98:101], v[66:69], v[48:63]
	v_mfma_f32_32x32x16_bf16 v[32:47], v[102:105], v[66:69], v[32:47]
	v_lshl_add_u64 v[66:67], v[76:77], 0, s[88:89]
	global_load_lds_dwordx4 v[66:67], off
	v_lshl_add_u64 v[66:67], v[76:77], 0, s[80:81]
	s_mov_b32 m0, s15
	s_nop 0
	global_load_lds_dwordx4 v[66:67], off
	v_lshl_add_u64 v[66:67], v[76:77], 0, s[56:57]
	s_mov_b32 m0, s14
	v_mfma_f32_32x32x16_bf16 v[16:31], v[98:101], v[70:73], v[16:31]
	global_load_lds_dwordx4 v[66:67], off
	v_lshl_add_u64 v[66:67], v[76:77], 0, vcc
	s_mov_b32 m0, s13
	s_mov_b64 vcc, 0x30200
	global_load_lds_dwordx4 v[66:67], off
	v_lshl_add_u64 v[66:67], v[78:79], 0, s[88:89]
	s_mov_b32 m0, s12
	v_mfma_f32_32x32x16_bf16 v[0:15], v[102:105], v[70:73], v[0:15]
	global_load_lds_dwordx4 v[66:67], off
	v_lshl_add_u64 v[66:67], v[78:79], 0, s[80:81]
	s_mov_b32 m0, s11
	s_nop 0
	global_load_lds_dwordx4 v[66:67], off
	ds_read_b128 v[70:73], v64 offset:49152
	ds_read_b128 v[66:69], v64 offset:53248
	ds_read_b128 v[98:101], v89
	ds_read_b128 v[102:105], v89 offset:4096
	ds_read_b128 v[106:109], v83 offset:49152
	ds_read_b128 v[110:113], v83 offset:53248
	s_waitcnt lgkmcnt(0)
	v_mfma_f32_32x32x16_bf16 v[48:63], v[98:101], v[70:73], v[48:63]
	ds_read_b128 v[114:117], v92
	ds_read_b128 v[118:121], v92 offset:4096
	s_mov_b32 m0, s10
	v_mfma_f32_32x32x16_bf16 v[32:47], v[102:105], v[70:73], v[32:47]
	v_mfma_f32_32x32x16_bf16 v[16:31], v[98:101], v[66:69], v[16:31]
	ds_read_b128 v[70:73], v85 offset:49152
	ds_read_b128 v[98:101], v85 offset:53248
	v_mfma_f32_32x32x16_bf16 v[0:15], v[102:105], v[66:69], v[0:15]
	v_add_u32_e32 v68, v97, v91
	ds_read_b128 v[102:105], v68
	ds_read_b128 v[122:125], v68 offset:4096
	v_add_u32_e32 v69, v97, v90
	v_lshl_add_u64 v[66:67], v[76:77], 0, s[58:59]
	s_waitcnt lgkmcnt(0)
	v_mfma_f32_32x32x16_bf16 v[48:63], v[114:117], v[106:109], v[48:63]
	v_mfma_f32_32x32x16_bf16 v[32:47], v[118:121], v[106:109], v[32:47]
	v_mfma_f32_32x32x16_bf16 v[16:31], v[114:117], v[110:113], v[16:31]
	v_mfma_f32_32x32x16_bf16 v[0:15], v[118:121], v[110:113], v[0:15]
	ds_read_b128 v[106:109], v87 offset:49152
	ds_read_b128 v[110:113], v87 offset:53248
	ds_read_b128 v[114:117], v69
	ds_read_b128 v[118:121], v69 offset:4096
	s_waitcnt vmcnt(6)
	s_barrier
	global_load_lds_dwordx4 v[66:67], off
	v_lshl_add_u64 v[66:67], v[76:77], 0, s[82:83]
	v_mfma_f32_32x32x16_bf16 v[48:63], v[102:105], v[70:73], v[48:63]
	s_mov_b32 m0, s9
	s_nop 0
	global_load_lds_dwordx4 v[66:67], off
	v_lshl_add_u64 v[66:67], v[76:77], 0, s[96:97]
	s_mov_b32 m0, s8
	v_mfma_f32_32x32x16_bf16 v[32:47], v[122:125], v[70:73], v[32:47]
	global_load_lds_dwordx4 v[66:67], off
	v_lshl_add_u64 v[66:67], v[76:77], 0, vcc
	s_mov_b32 m0, s7
	v_add_u32_e32 v70, v128, v93
	global_load_lds_dwordx4 v[66:67], off
	v_mfma_f32_32x32x16_bf16 v[16:31], v[102:105], v[98:101], v[16:31]
	v_lshl_add_u64 v[66:67], v[78:79], 0, s[58:59]
	s_mov_b32 m0, s6
	v_add_u32_e32 v71, v129, v93
	global_load_lds_dwordx4 v[66:67], off
	v_lshl_add_u64 v[66:67], v[78:79], 0, s[82:83]
	s_mov_b32 m0, s5
	v_mfma_f32_32x32x16_bf16 v[0:15], v[122:125], v[98:101], v[0:15]
	global_load_lds_dwordx4 v[66:67], off
	v_add_u32_e32 v66, v128, v94
	v_add_u32_e32 v67, v129, v94
	ds_read_b128 v[96:99], v66
	ds_read_b128 v[100:103], v66 offset:4096
	v_add_u32_e32 v72, v128, v91
	v_add_u32_e32 v73, v129, v91
	s_waitcnt lgkmcnt(0)
	v_mfma_f32_32x32x16_bf16 v[48:63], v[114:117], v[106:109], v[48:63]
	v_add_u32_e32 v91, v128, v90
	v_add_u32_e32 v90, v129, v90
	s_mov_b32 m0, s19
	v_mfma_f32_32x32x16_bf16 v[32:47], v[118:121], v[106:109], v[32:47]
	v_mfma_f32_32x32x16_bf16 v[16:31], v[114:117], v[110:113], v[16:31]
	v_mfma_f32_32x32x16_bf16 v[0:15], v[118:121], v[110:113], v[0:15]
	ds_read_b128 v[104:107], v67
	ds_read_b128 v[108:111], v67 offset:4096
	ds_read_b128 v[112:115], v70
	ds_read_b128 v[116:119], v70 offset:4096
	ds_read_b128 v[120:123], v71
	ds_read_b128 v[124:127], v71 offset:4096
	s_waitcnt lgkmcnt(0)
	v_mfma_f32_32x32x16_bf16 v[48:63], v[104:107], v[96:99], v[48:63]
	v_mfma_f32_32x32x16_bf16 v[32:47], v[108:111], v[96:99], v[32:47]
	v_mfma_f32_32x32x16_bf16 v[16:31], v[104:107], v[100:103], v[16:31]
	v_mfma_f32_32x32x16_bf16 v[0:15], v[108:111], v[100:103], v[0:15]
	ds_read_b128 v[94:97], v72
	ds_read_b128 v[98:101], v72 offset:4096
	ds_read_b128 v[102:105], v73
	ds_read_b128 v[106:109], v73 offset:4096
	v_mfma_f32_32x32x16_bf16 v[48:63], v[120:123], v[112:115], v[48:63]
	v_mfma_f32_32x32x16_bf16 v[32:47], v[124:127], v[112:115], v[32:47]
	v_mfma_f32_32x32x16_bf16 v[16:31], v[120:123], v[116:119], v[16:31]
	v_mfma_f32_32x32x16_bf16 v[0:15], v[124:127], v[116:119], v[0:15]
	ds_read_b128 v[110:113], v91
	ds_read_b128 v[114:117], v91 offset:4096
	ds_read_b128 v[118:121], v90
	ds_read_b128 v[122:125], v90 offset:4096
	s_waitcnt vmcnt(6)
	s_barrier
; #define MFMA32(a, b, c) __builtin_amdgcn_mfma_f32_32x32x16_bf16((a), (b), (c), 0, 0, 0)
; template <int NI>
; DEVINL void gemm_kloop(const bf16_t* __restrict__ A, int lda, const bf16_t* __restrict__ Bt, int ldb, int K, int m0, int n0,
;                        unsigned char* lds, f32x16 (&acc)[NI][2]) {
;     ...
;     auto compute = [&](int st_) {
;         const unsigned char* pa = lds + st_ * STAGE + (wm * 64 + r) * 128;
;         const unsigned char* pb = lds + st_ * STAGE + A_ST + (wn * 32 * NI + r) * 128;
;         bf16x8 af[2][2], bfr[2][NI];
; #pragma unroll
;         for (int i = 0; i < 2; ++i) af[0][i] = *(const bf16x8*)(pa + i * 32 * 128 + o4[0]);
; #pragma unroll
;         for (int i = 0; i < NI; ++i) bfr[0][i] = *(const bf16x8*)(pb + i * 32 * 128 + o4[0]);
; #pragma unroll
;         for (int ks = 0; ks < 4; ++ks) {
;             if (ks < 3) {
; #pragma unroll
;                 for (int i = 0; i < 2; ++i) af[(ks + 1) & 1][i] = *(const bf16x8*)(pa + i * 32 * 128 + o4[ks + 1]);
; #pragma unroll
;                 for (int i = 0; i < NI; ++i) bfr[(ks + 1) & 1][i] = *(const bf16x8*)(pb + i * 32 * 128 + o4[ks + 1]);
;             }
; #pragma unroll
;             for (int ni = 0; ni < NI; ++ni)
; #pragma unroll
;                 for (int mi = 0; mi < 2; ++mi) acc[ni][mi] = MFMA32(bfr[ks & 1][ni], af[ks & 1][mi], acc[ni][mi]);
;         }
;     };
;     int t = 0;
;     for (; t + 2 < nt; ++t) {
;         if (NI == 2) asm volatile("s_waitcnt vmcnt(6)" ::: "memory"); else asm volatile("s_waitcnt vmcnt(5)" ::: "memory");
;         __builtin_amdgcn_s_barrier();
;         { const int s2 = (cur >= 1) ? cur - 1 : 2; GEMM_ISSUE(s2, t + 2); }
;         compute(cur);
;         cur = (cur == 2) ? 0 : cur + 1;
;     }
	s_waitcnt lgkmcnt(0)
	v_mfma_f32_32x32x16_bf16 v[48:63], v[102:105], v[94:97], v[48:63]
	v_mfma_f32_32x32x16_bf16 v[32:47], v[106:109], v[94:97], v[32:47]
	v_lshl_add_u64 v[94:95], v[76:77], 0, s[64:65]
	global_load_lds_dwordx4 v[94:95], off
	v_lshl_add_u64 v[94:95], v[76:77], 0, s[22:23]
	s_mov_b32 m0, s18
	s_mov_b64 s[18:19], 0x30280
	global_load_lds_dwordx4 v[94:95], off
	v_mfma_f32_32x32x16_bf16 v[16:31], v[102:105], v[98:101], v[16:31]
	v_lshl_add_u64 v[94:95], v[76:77], 0, s[62:63]
	s_mov_b32 m0, s20
	s_nop 0
	global_load_lds_dwordx4 v[94:95], off
	v_lshl_add_u64 v[94:95], v[76:77], 0, s[18:19]
	s_mov_b32 m0, s21
	v_mfma_f32_32x32x16_bf16 v[0:15], v[106:109], v[98:101], v[0:15]
	global_load_lds_dwordx4 v[94:95], off
	v_lshl_add_u64 v[94:95], v[78:79], 0, s[64:65]
	s_mov_b32 m0, s24
	s_nop 0
	global_load_lds_dwordx4 v[94:95], off
	v_mfma_f32_32x32x16_bf16 v[48:63], v[118:121], v[110:113], v[48:63]
	v_lshl_add_u64 v[94:95], v[78:79], 0, s[22:23]
	s_mov_b32 m0, s17
	s_nop 0
	global_load_lds_dwordx4 v[94:95], off
	s_mov_b32 m0, s16
	v_mfma_f32_32x32x16_bf16 v[32:47], v[122:125], v[110:113], v[32:47]
	v_mfma_f32_32x32x16_bf16 v[16:31], v[118:121], v[114:117], v[16:31]
	v_mfma_f32_32x32x16_bf16 v[0:15], v[122:125], v[114:117], v[0:15]
	ds_read_b128 v[94:97], v64
	ds_read_b128 v[98:101], v64 offset:4096
	ds_read_b128 v[102:105], v82 offset:32768
	ds_read_b128 v[106:109], v82 offset:36864
	ds_read_b128 v[110:113], v83
	ds_read_b128 v[114:117], v83 offset:4096
	ds_read_b128 v[118:121], v84 offset:32768
	ds_read_b128 v[122:125], v84 offset:36864
	s_waitcnt lgkmcnt(0)
	v_mfma_f32_32x32x16_bf16 v[48:63], v[102:105], v[94:97], v[48:63]
	v_mfma_f32_32x32x16_bf16 v[32:47], v[106:109], v[94:97], v[32:47]
	v_mfma_f32_32x32x16_bf16 v[16:31], v[102:105], v[98:101], v[16:31]
	v_mfma_f32_32x32x16_bf16 v[0:15], v[106:109], v[98:101], v[0:15]
	ds_read_b128 v[94:97], v85
	ds_read_b128 v[98:101], v85 offset:4096
	ds_read_b128 v[102:105], v86 offset:32768
	ds_read_b128 v[106:109], v86 offset:36864
	v_mfma_f32_32x32x16_bf16 v[48:63], v[118:121], v[110:113], v[48:63]
	v_mfma_f32_32x32x16_bf16 v[32:47], v[122:125], v[110:113], v[32:47]
	v_mfma_f32_32x32x16_bf16 v[16:31], v[118:121], v[114:117], v[16:31]
	v_mfma_f32_32x32x16_bf16 v[0:15], v[122:125], v[114:117], v[0:15]
	ds_read_b128 v[110:113], v87
	ds_read_b128 v[114:117], v87 offset:4096
	ds_read_b128 v[118:121], v88 offset:32768
	ds_read_b128 v[122:125], v88 offset:36864
	s_waitcnt vmcnt(6)
	s_barrier
	s_waitcnt lgkmcnt(0)
	v_mfma_f32_32x32x16_bf16 v[48:63], v[102:105], v[94:97], v[48:63]
	v_mfma_f32_32x32x16_bf16 v[32:47], v[106:109], v[94:97], v[32:47]
	v_lshl_add_u64 v[94:95], v[76:77], 0, s[2:3]
	global_load_lds_dwordx4 v[94:95], off
	v_lshl_add_u64 v[94:95], v[76:77], 0, s[26:27]
	s_mov_b32 m0, s15
	s_nop 0
	global_load_lds_dwordx4 v[94:95], off
	v_mfma_f32_32x32x16_bf16 v[16:31], v[102:105], v[98:101], v[16:31]
	v_lshl_add_u64 v[94:95], v[76:77], 0, s[90:91]
	s_mov_b32 m0, s14
	s_mov_b64 s[14:15], 0x30300
	global_load_lds_dwordx4 v[94:95], off
	v_lshl_add_u64 v[94:95], v[76:77], 0, s[14:15]
	s_mov_b32 m0, s13
	v_mfma_f32_32x32x16_bf16 v[0:15], v[106:109], v[98:101], v[0:15]
	global_load_lds_dwordx4 v[94:95], off
	v_lshl_add_u64 v[94:95], v[78:79], 0, s[2:3]
	s_mov_b32 m0, s12
	s_nop 0
	global_load_lds_dwordx4 v[94:95], off
	v_mfma_f32_32x32x16_bf16 v[48:63], v[118:121], v[110:113], v[48:63]
	v_lshl_add_u64 v[94:95], v[78:79], 0, s[26:27]
	s_mov_b32 m0, s11
	s_nop 0
	global_load_lds_dwordx4 v[94:95], off
	s_mov_b32 m0, s10
	v_mfma_f32_32x32x16_bf16 v[32:47], v[122:125], v[110:113], v[32:47]
	v_mfma_f32_32x32x16_bf16 v[16:31], v[118:121], v[114:117], v[16:31]
	v_mfma_f32_32x32x16_bf16 v[0:15], v[122:125], v[114:117], v[0:15]
	ds_read_b128 v[94:97], v64 offset:49152
	ds_read_b128 v[98:101], v64 offset:53248
	ds_read_b128 v[102:105], v89
	ds_read_b128 v[106:109], v89 offset:4096
	ds_read_b128 v[110:113], v83 offset:49152
	ds_read_b128 v[114:117], v83 offset:53248
	ds_read_b128 v[118:121], v92
	ds_read_b128 v[122:125], v92 offset:4096
	s_waitcnt lgkmcnt(0)
	v_mfma_f32_32x32x16_bf16 v[48:63], v[102:105], v[94:97], v[48:63]
	v_mfma_f32_32x32x16_bf16 v[32:47], v[106:109], v[94:97], v[32:47]
	v_mfma_f32_32x32x16_bf16 v[16:31], v[102:105], v[98:101], v[16:31]
	v_mfma_f32_32x32x16_bf16 v[0:15], v[106:109], v[98:101], v[0:15]
	ds_read_b128 v[94:97], v85 offset:49152
	ds_read_b128 v[98:101], v85 offset:53248
	ds_read_b128 v[102:105], v68
	ds_read_b128 v[106:109], v68 offset:4096
	v_mfma_f32_32x32x16_bf16 v[48:63], v[118:121], v[110:113], v[48:63]
	v_mfma_f32_32x32x16_bf16 v[32:47], v[122:125], v[110:113], v[32:47]
	v_mfma_f32_32x32x16_bf16 v[16:31], v[118:121], v[114:117], v[16:31]
	v_mfma_f32_32x32x16_bf16 v[0:15], v[122:125], v[114:117], v[0:15]
	ds_read_b128 v[110:113], v87 offset:49152
	ds_read_b128 v[114:117], v87 offset:53248
	ds_read_b128 v[118:121], v69
	ds_read_b128 v[122:125], v69 offset:4096
	s_waitcnt vmcnt(6)
	s_barrier
; template <int NI>
; DEVINL void gemm_kloop(const bf16_t* __restrict__ A, int lda, const bf16_t* __restrict__ Bt, int ldb, int K, int m0, int n0,
;                        unsigned char* lds, f32x16 (&acc)[NI][2]) {
;     ...
;     for (; t + 2 < nt; ++t) {
;         if (NI == 2) asm volatile("s_waitcnt vmcnt(6)" ::: "memory"); else asm volatile("s_waitcnt vmcnt(5)" ::: "memory");
;         __builtin_amdgcn_s_barrier();
;         { const int s2 = (cur >= 1) ? cur - 1 : 2; GEMM_ISSUE(s2, t + 2); }
;         compute(cur);
;         cur = (cur == 2) ? 0 : cur + 1;
;     }
;     if (nt >= 2) {
;         if (NI == 2) asm volatile("s_waitcnt vmcnt(6)" ::: "memory"); else asm volatile("s_waitcnt vmcnt(5)" ::: "memory");
;         __builtin_amdgcn_s_barrier();
;         compute(cur);
;         cur = (cur == 2) ? 0 : cur + 1;
;     }
;     asm volatile("s_waitcnt vmcnt(0)" ::: "memory");
;     __builtin_amdgcn_s_barrier();
;     compute(cur);
	s_waitcnt lgkmcnt(0)
	v_mfma_f32_32x32x16_bf16 v[48:63], v[102:105], v[94:97], v[48:63]
	v_mfma_f32_32x32x16_bf16 v[32:47], v[106:109], v[94:97], v[32:47]
	v_lshl_add_u64 v[94:95], v[76:77], 0, s[40:41]
	global_load_lds_dwordx4 v[94:95], off
	v_lshl_add_u64 v[94:95], v[76:77], 0, s[44:45]
	s_mov_b32 m0, s9
	s_nop 0
	global_load_lds_dwordx4 v[94:95], off
	v_mfma_f32_32x32x16_bf16 v[16:31], v[102:105], v[98:101], v[16:31]
	v_lshl_add_u64 v[94:95], v[76:77], 0, s[72:73]
	s_mov_b32 m0, s8
	v_lshl_add_u64 v[76:77], v[76:77], 0, s[94:95]
	global_load_lds_dwordx4 v[94:95], off
	s_mov_b32 m0, s7
	v_mfma_f32_32x32x16_bf16 v[0:15], v[106:109], v[98:101], v[0:15]
	global_load_lds_dwordx4 v[76:77], off
	v_lshl_add_u64 v[76:77], v[78:79], 0, s[40:41]
	s_mov_b32 m0, s6
	s_nop 0
	global_load_lds_dwordx4 v[76:77], off
	v_mfma_f32_32x32x16_bf16 v[48:63], v[118:121], v[110:113], v[48:63]
	v_lshl_add_u64 v[76:77], v[78:79], 0, s[44:45]
	s_mov_b32 m0, s5
	s_nop 0
	global_load_lds_dwordx4 v[76:77], off
	v_mfma_f32_32x32x16_bf16 v[32:47], v[122:125], v[110:113], v[32:47]
	v_mfma_f32_32x32x16_bf16 v[16:31], v[118:121], v[114:117], v[16:31]
	v_mfma_f32_32x32x16_bf16 v[0:15], v[122:125], v[114:117], v[0:15]
	ds_read_b128 v[76:79], v66
	ds_read_b128 v[94:97], v66 offset:4096
	ds_read_b128 v[98:101], v67
	ds_read_b128 v[102:105], v67 offset:4096
	ds_read_b128 v[106:109], v70
	ds_read_b128 v[110:113], v70 offset:4096
	ds_read_b128 v[114:117], v71
	ds_read_b128 v[118:121], v71 offset:4096
	v_add_u32_e32 v66, s4, v81
	v_ashrrev_i32_e32 v67, 31, v66
	s_waitcnt lgkmcnt(0)
	v_mfma_f32_32x32x16_bf16 v[48:63], v[98:101], v[76:79], v[48:63]
	v_mfma_f32_32x32x16_bf16 v[32:47], v[102:105], v[76:79], v[32:47]
	v_mfma_f32_32x32x16_bf16 v[16:31], v[98:101], v[94:97], v[16:31]
	v_mfma_f32_32x32x16_bf16 v[0:15], v[102:105], v[94:97], v[0:15]
	ds_read_b128 v[76:79], v72
	ds_read_b128 v[94:97], v72 offset:4096
	ds_read_b128 v[98:101], v73
	ds_read_b128 v[70:73], v73 offset:4096
	v_mfma_f32_32x32x16_bf16 v[48:63], v[114:117], v[106:109], v[48:63]
	v_mfma_f32_32x32x16_bf16 v[32:47], v[118:121], v[106:109], v[32:47]
	v_mfma_f32_32x32x16_bf16 v[16:31], v[114:117], v[110:113], v[16:31]
	v_mfma_f32_32x32x16_bf16 v[0:15], v[118:121], v[110:113], v[0:15]
	ds_read_b128 v[102:105], v91
	ds_read_b128 v[106:109], v91 offset:4096
	ds_read_b128 v[110:113], v90
	ds_read_b128 v[114:117], v90 offset:4096
	s_waitcnt vmcnt(6)
	s_barrier
	s_waitcnt lgkmcnt(0)
	v_mfma_f32_32x32x16_bf16 v[48:63], v[98:101], v[76:79], v[48:63]
	v_mfma_f32_32x32x16_bf16 v[32:47], v[70:73], v[76:79], v[32:47]
	v_mfma_f32_32x32x16_bf16 v[16:31], v[98:101], v[94:97], v[16:31]
	v_mfma_f32_32x32x16_bf16 v[0:15], v[70:73], v[94:97], v[0:15]
	v_mfma_f32_32x32x16_bf16 v[48:63], v[110:113], v[102:105], v[48:63]
	v_mfma_f32_32x32x16_bf16 v[32:47], v[114:117], v[102:105], v[32:47]
	v_mfma_f32_32x32x16_bf16 v[16:31], v[110:113], v[106:109], v[16:31]
	v_mfma_f32_32x32x16_bf16 v[0:15], v[114:117], v[106:109], v[0:15]
	ds_read_b128 v[70:73], v64
	ds_read_b128 v[76:79], v64 offset:4096
	ds_read_b128 v[94:97], v82 offset:32768
	ds_read_b128 v[98:101], v82 offset:36864
	ds_read_b128 v[102:105], v83
	ds_read_b128 v[106:109], v83 offset:4096
	ds_read_b128 v[110:113], v84 offset:32768
	ds_read_b128 v[114:117], v84 offset:36864
	s_waitcnt lgkmcnt(0)
	v_mfma_f32_32x32x16_bf16 v[48:63], v[94:97], v[70:73], v[48:63]
	v_mfma_f32_32x32x16_bf16 v[32:47], v[98:101], v[70:73], v[32:47]
	v_mfma_f32_32x32x16_bf16 v[16:31], v[94:97], v[76:79], v[16:31]
	v_mfma_f32_32x32x16_bf16 v[0:15], v[98:101], v[76:79], v[0:15]
	ds_read_b128 v[70:73], v85
	ds_read_b128 v[76:79], v85 offset:4096
	ds_read_b128 v[94:97], v86 offset:32768
	ds_read_b128 v[98:101], v86 offset:36864
	v_mfma_f32_32x32x16_bf16 v[48:63], v[110:113], v[102:105], v[48:63]
	v_mfma_f32_32x32x16_bf16 v[32:47], v[114:117], v[102:105], v[32:47]
	v_mfma_f32_32x32x16_bf16 v[16:31], v[110:113], v[106:109], v[16:31]
	v_mfma_f32_32x32x16_bf16 v[0:15], v[114:117], v[106:109], v[0:15]
	ds_read_b128 v[102:105], v87
	ds_read_b128 v[106:109], v87 offset:4096
	ds_read_b128 v[110:113], v88 offset:32768
	ds_read_b128 v[114:117], v88 offset:36864
	s_waitcnt vmcnt(0)
	s_barrier
	s_waitcnt lgkmcnt(0)
	v_mfma_f32_32x32x16_bf16 v[48:63], v[94:97], v[70:73], v[48:63]
	v_mfma_f32_32x32x16_bf16 v[32:47], v[98:101], v[70:73], v[32:47]
	v_mfma_f32_32x32x16_bf16 v[16:31], v[94:97], v[76:79], v[16:31]
	v_mfma_f32_32x32x16_bf16 v[0:15], v[98:101], v[76:79], v[0:15]
	v_mfma_f32_32x32x16_bf16 v[48:63], v[110:113], v[102:105], v[48:63]
	v_mfma_f32_32x32x16_bf16 v[32:47], v[114:117], v[102:105], v[32:47]
	v_mfma_f32_32x32x16_bf16 v[16:31], v[110:113], v[106:109], v[16:31]
	v_mfma_f32_32x32x16_bf16 v[0:15], v[114:117], v[106:109], v[0:15]
	ds_read_b128 v[70:73], v64 offset:49152
	ds_read_b128 v[76:79], v64 offset:53248
	ds_read_b128 v[94:97], v89
	ds_read_b128 v[88:91], v89 offset:4096
	ds_read_b128 v[98:101], v83 offset:49152
	ds_read_b128 v[102:105], v83 offset:53248
	ds_read_b128 v[106:109], v92
	ds_read_b128 v[110:113], v92 offset:4096
	v_lshlrev_b32_e32 v64, 1, v80
	s_waitcnt lgkmcnt(0)
	v_mfma_f32_32x32x16_bf16 v[48:63], v[94:97], v[70:73], v[48:63]
	v_mfma_f32_32x32x16_bf16 v[32:47], v[88:91], v[70:73], v[32:47]
	v_mfma_f32_32x32x16_bf16 v[16:31], v[94:97], v[76:79], v[16:31]
	v_mfma_f32_32x32x16_bf16 v[0:15], v[88:91], v[76:79], v[0:15]
	ds_read_b128 v[70:73], v85 offset:49152
	ds_read_b128 v[76:79], v85 offset:53248
	ds_read_b128 v[82:85], v68
	ds_read_b128 v[88:91], v68 offset:4096
	v_mfma_f32_32x32x16_bf16 v[48:63], v[106:109], v[98:101], v[48:63]
	v_mfma_f32_32x32x16_bf16 v[32:47], v[110:113], v[98:101], v[32:47]
	v_mfma_f32_32x32x16_bf16 v[16:31], v[106:109], v[102:105], v[16:31]
	v_mfma_f32_32x32x16_bf16 v[0:15], v[110:113], v[102:105], v[0:15]
	ds_read_b128 v[92:95], v87 offset:49152
	ds_read_b128 v[96:99], v87 offset:53248
	ds_read_b128 v[100:103], v69
	ds_read_b128 v[104:107], v69 offset:4096
	v_mov_b64_e32 v[68:69], s[28:29]
	v_or_b32_e32 v112, 32, v75
	s_waitcnt lgkmcnt(0)
;     DEVINL bf16_t* Z() const { return (bf16_t*)(ws + OFF_Z); }
; DEVINL float bflo(unsigned u) { return __uint_as_float(u << 16); }
; DEVINL float bfhi(unsigned u) { return __uint_as_float(u & 0xffff0000u); }
; DEVINL float* mp_row(const Ctx& c, int t) { return (float*)(c.Z() + (size_t)t * ZW); }
; template <int NI, int MODE>
; DEVINL void merge_tile(const Ctx& c, unsigned char* lds, int m0, int n0) {
;     ...
;         for (int mi = 0; mi < 2; ++mi) {
;             const bf16_t* gp = c.Z() + (size_t)(mbase + mi * 32 + r) * ZW + Z_GZ + br * DM + nbase;
; #pragma unroll
;             for (int ni = 0; ni < NI; ++ni)
; #pragma unroll
;                 for (int g = 0; g < 4; ++g) {
;                     const u32x2 gg = *(const u32x2*)(gp + ni * 32 + 8 * g + 4 * h);
;                     mer[ni][mi][4 * g + 0] += bflo(gg[0]) * acc[ni][mi][4 * g + 0];
;                     mer[ni][mi][4 * g + 1] += bfhi(gg[0]) * acc[ni][mi][4 * g + 1];
;                     mer[ni][mi][4 * g + 2] += bflo(gg[1]) * acc[ni][mi][4 * g + 2];
;                     mer[ni][mi][4 * g + 3] += bfhi(gg[1]) * acc[ni][mi][4 * g + 3];
;                 }
;     ...
; #pragma unroll
;     for (int mi = 0; mi < 2; ++mi) {
;         const float* pp = mp_row(c, mbase + mi * 32 + r) + nbase;
; #pragma unroll
;         for (int ni = 0; ni < NI; ++ni)
; #pragma unroll
;             for (int g = 0; g < 4; ++g) {
;                 const f32x4 v = *(const f32x4*)(pp + ni * 32 + 8 * g + 4 * h);
; #pragma unroll
;                 for (int j = 0; j < 4; ++j) mer[ni][mi][4 * g + j] += v[j];
;             }
	v_mfma_f32_32x32x16_bf16 v[48:63], v[82:85], v[70:73], v[48:63]
	v_mfma_f32_32x32x16_bf16 v[32:47], v[88:91], v[70:73], v[32:47]
	v_mad_i64_i32 v[70:71], s[4:5], v75, s49, v[68:69]
	v_lshlrev_b64 v[72:73], 1, v[66:67]
	v_lshl_add_u64 v[70:71], v[70:71], 0, v[72:73]
	v_lshl_add_u64 v[70:71], v[70:71], 0, v[64:65]
	v_mad_i64_i32 v[68:69], s[4:5], v112, s49, v[68:69]
	v_mfma_f32_32x32x16_bf16 v[16:31], v[82:85], v[76:79], v[16:31]
	v_lshl_add_u64 v[68:69], v[68:69], 0, v[72:73]
	v_lshl_add_u64 v[68:69], v[68:69], 0, v[64:65]
	v_lshl_add_u64 v[66:67], v[66:67], 2, s[30:31]
	v_lshlrev_b32_e32 v64, 2, v80
	v_lshl_add_u64 v[80:81], v[66:67], 0, v[64:65]
	v_mad_i64_i32 v[108:109], s[4:5], v75, s49, v[80:81]
	v_mad_i64_i32 v[232:233], s[4:5], v112, s49, v[80:81]
	global_load_dwordx4 v[168:171], v[108:109], off
	global_load_dwordx4 v[172:175], v[108:109], off offset:32
	global_load_dwordx4 v[176:179], v[108:109], off offset:64
	global_load_dwordx4 v[180:183], v[108:109], off offset:96
	global_load_dwordx4 v[184:187], v[108:109], off offset:128
	global_load_dwordx4 v[188:191], v[108:109], off offset:160
	global_load_dwordx4 v[192:195], v[108:109], off offset:192
	global_load_dwordx4 v[196:199], v[108:109], off offset:224
	global_load_dwordx4 v[200:203], v[232:233], off
	global_load_dwordx4 v[204:207], v[232:233], off offset:32
	global_load_dwordx4 v[208:211], v[232:233], off offset:64
	global_load_dwordx4 v[212:215], v[232:233], off offset:96
	global_load_dwordx4 v[216:219], v[232:233], off offset:128
	global_load_dwordx4 v[220:223], v[232:233], off offset:160
	global_load_dwordx4 v[224:227], v[232:233], off offset:192
	global_load_dwordx4 v[228:231], v[232:233], off offset:224
	v_mfma_f32_32x32x16_bf16 v[0:15], v[88:91], v[76:79], v[0:15]
	v_lshl_add_u64 v[76:77], v[70:71], 0, s[50:51]
	v_add_co_u32_e32 v70, vcc, s38, v70
	v_ashrrev_i32_e32 v75, 31, v74
	s_nop 0
	v_addc_co_u32_e32 v71, vcc, 0, v71, vcc
	global_load_dwordx2 v[70:71], v[70:71], off offset:768
	s_nop 0
	global_load_dwordx2 v[78:79], v[76:77], off offset:16
	global_load_dwordx2 v[82:83], v[76:77], off offset:32
	global_load_dwordx2 v[84:85], v[76:77], off offset:48
	global_load_dwordx2 v[86:87], v[76:77], off offset:64
	global_load_dwordx2 v[88:89], v[76:77], off offset:80
	global_load_dwordx2 v[90:91], v[76:77], off offset:96
	s_nop 0
	global_load_dwordx2 v[76:77], v[76:77], off offset:112
	v_mfma_f32_32x32x16_bf16 v[48:63], v[100:103], v[92:95], v[48:63]
	s_waitcnt vmcnt(0)
	v_lshlrev_b32_e32 v110, 16, v70
	v_mfma_f32_32x32x16_bf16 v[32:47], v[104:107], v[92:95], v[32:47]
	v_lshl_add_u64 v[92:93], v[68:69], 0, s[50:51]
	v_add_co_u32_e32 v68, vcc, s38, v68
	v_and_b32_e32 v111, 0xffff0000, v70
	s_nop 0
	v_addc_co_u32_e32 v69, vcc, 0, v69, vcc
	s_nop 3
	v_fma_f32 v48, v48, v110, 0
	v_fma_f32 v49, v49, v111, 0
	v_mfma_f32_32x32x16_bf16 v[16:31], v[100:103], v[96:99], v[16:31]
	v_lshlrev_b32_e32 v70, 16, v78
	v_mfma_f32_32x32x16_bf16 v[0:15], v[104:107], v[96:99], v[0:15]
	global_load_dwordx2 v[94:95], v[68:69], off offset:768
	global_load_dwordx2 v[96:97], v[92:93], off offset:16
	global_load_dwordx2 v[98:99], v[92:93], off offset:32
	global_load_dwordx2 v[100:101], v[92:93], off offset:48
	global_load_dwordx2 v[102:103], v[92:93], off offset:64
	global_load_dwordx2 v[104:105], v[92:93], off offset:80
	global_load_dwordx2 v[106:107], v[92:93], off offset:96
	s_nop 0
	global_load_dwordx2 v[92:93], v[92:93], off offset:112
	s_nop 0
	v_mov_b64_e32 v[66:67], v[168:169]
	v_mov_b64_e32 v[68:69], v[170:171]
	s_waitcnt vmcnt(0)
	v_pk_add_f32 v[66:67], v[48:49], v[66:67]
	v_lshlrev_b32_e32 v48, 16, v71
	v_and_b32_e32 v49, 0xffff0000, v71
	v_pk_fma_f32 v[48:49], v[50:51], v[48:49], 0 op_sel_hi:[1,1,0]
	v_and_b32_e32 v71, 0xffff0000, v78
	v_pk_add_f32 v[68:69], v[48:49], v[68:69]
	v_mov_b64_e32 v[48:49], v[172:173]
	v_mov_b64_e32 v[50:51], v[174:175]
	v_pk_fma_f32 v[52:53], v[52:53], v[70:71], 0 op_sel_hi:[1,1,0]
	v_lshlrev_b32_e32 v70, 16, v82
	v_and_b32_e32 v71, 0xffff0000, v82
	v_pk_fma_f32 v[56:57], v[56:57], v[70:71], 0 op_sel_hi:[1,1,0]
	v_lshlrev_b32_e32 v70, 16, v84
	v_and_b32_e32 v71, 0xffff0000, v84
	v_pk_fma_f32 v[60:61], v[60:61], v[70:71], 0 op_sel_hi:[1,1,0]
	v_lshlrev_b32_e32 v70, 16, v86
	v_and_b32_e32 v71, 0xffff0000, v86
	v_pk_fma_f32 v[32:33], v[32:33], v[70:71], 0 op_sel_hi:[1,1,0]
	v_lshlrev_b32_e32 v70, 16, v88
	v_and_b32_e32 v71, 0xffff0000, v88
	v_pk_fma_f32 v[36:37], v[36:37], v[70:71], 0 op_sel_hi:[1,1,0]
	v_lshlrev_b32_e32 v70, 16, v90
	v_and_b32_e32 v71, 0xffff0000, v90
	v_pk_fma_f32 v[40:41], v[40:41], v[70:71], 0 op_sel_hi:[1,1,0]
	v_lshlrev_b32_e32 v70, 16, v76
	v_and_b32_e32 v71, 0xffff0000, v76
	v_pk_fma_f32 v[44:45], v[44:45], v[70:71], 0 op_sel_hi:[1,1,0]
	v_mad_i64_i32 v[70:71], s[4:5], v112, s49, v[80:81]
	v_lshlrev_b32_e32 v76, 16, v94
	s_nop 0
	v_pk_add_f32 v[52:53], v[52:53], v[48:49]
	v_lshlrev_b32_e32 v48, 16, v79
	v_and_b32_e32 v49, 0xffff0000, v79
	v_pk_fma_f32 v[48:49], v[54:55], v[48:49], 0 op_sel_hi:[1,1,0]
	s_nop 0
	v_pk_add_f32 v[54:55], v[48:49], v[50:51]
	v_mov_b64_e32 v[48:49], v[176:177]
	v_mov_b64_e32 v[50:51], v[178:179]
	s_nop 0
	v_pk_add_f32 v[56:57], v[56:57], v[48:49]
	v_lshlrev_b32_e32 v48, 16, v83
	v_and_b32_e32 v49, 0xffff0000, v83
	v_pk_fma_f32 v[48:49], v[58:59], v[48:49], 0 op_sel_hi:[1,1,0]
	s_nop 0
	v_pk_add_f32 v[58:59], v[48:49], v[50:51]
	v_mov_b64_e32 v[48:49], v[180:181]
	v_mov_b64_e32 v[50:51], v[182:183]
	s_nop 0
	v_pk_add_f32 v[60:61], v[60:61], v[48:49]
	v_lshlrev_b32_e32 v48, 16, v85
	v_and_b32_e32 v49, 0xffff0000, v85
	v_pk_fma_f32 v[48:49], v[62:63], v[48:49], 0 op_sel_hi:[1,1,0]
	s_nop 0
	v_pk_add_f32 v[62:63], v[48:49], v[50:51]
;     DEVINL bf16_t* M() const { return (bf16_t*)(ws + OFF_RW + 2 * SZ_A512); }
; DEVINL unsigned cvt_pk_bf16(float lo, float hi) { const f32x2 v = {lo, hi}; return __builtin_bit_cast(unsigned, __builtin_convertvector(v, bf16x2v)); }
; DEVINL float* mp_row(const Ctx& c, int t) { return (float*)(c.Z() + (size_t)t * ZW); }
; template <int NI, int MODE>
; DEVINL void merge_tile(const Ctx& c, unsigned char* lds, int m0, int n0) {
;     ...
; #pragma unroll
;     for (int mi = 0; mi < 2; ++mi) {
;         const float* pp = mp_row(c, mbase + mi * 32 + r) + nbase;
; #pragma unroll
;         for (int ni = 0; ni < NI; ++ni)
; #pragma unroll
;             for (int g = 0; g < 4; ++g) {
;                 const f32x4 v = *(const f32x4*)(pp + ni * 32 + 8 * g + 4 * h);
; #pragma unroll
;                 for (int j = 0; j < 4; ++j) mer[ni][mi][4 * g + j] += v[j];
;             }
;     }
;     if (NI == 2) {
;         u32x2 pkm[2][2][4];
; #pragma unroll
;         for (int mi = 0; mi < 2; ++mi)
; #pragma unroll
;             for (int ni = 0; ni < 2; ++ni)
; #pragma unroll
;                 for (int g = 0; g < 4; ++g) { pkm[mi][ni][g][0] = cvt_pk_bf16(mer[ni % NI][mi][4 * g], mer[ni % NI][mi][4 * g + 1]); pkm[mi][ni][g][1] = cvt_pk_bf16(mer[ni % NI][mi][4 * g + 2], mer[ni % NI][mi][4 * g + 3]); }
;         store_rows_via_lds(lds, pkm, c.M() + (size_t)mbase * DM + nbase, DM);
	v_mov_b64_e32 v[48:49], v[184:185]
	v_mov_b64_e32 v[50:51], v[186:187]
	s_nop 0
	v_pk_add_f32 v[48:49], v[32:33], v[48:49]
	v_lshlrev_b32_e32 v32, 16, v87
	v_and_b32_e32 v33, 0xffff0000, v87
	v_pk_fma_f32 v[32:33], v[34:35], v[32:33], 0 op_sel_hi:[1,1,0]
	s_nop 0
	v_pk_add_f32 v[50:51], v[32:33], v[50:51]
	v_mov_b64_e32 v[32:33], v[188:189]
	v_mov_b64_e32 v[34:35], v[190:191]
	s_nop 0
	v_pk_add_f32 v[36:37], v[36:37], v[32:33]
	v_lshlrev_b32_e32 v32, 16, v89
	v_and_b32_e32 v33, 0xffff0000, v89
	v_pk_fma_f32 v[32:33], v[38:39], v[32:33], 0 op_sel_hi:[1,1,0]
	s_nop 0
	v_pk_add_f32 v[38:39], v[32:33], v[34:35]
	v_mov_b64_e32 v[32:33], v[192:193]
	v_mov_b64_e32 v[34:35], v[194:195]
	s_nop 0
	v_pk_add_f32 v[40:41], v[40:41], v[32:33]
	v_lshlrev_b32_e32 v32, 16, v91
	v_and_b32_e32 v33, 0xffff0000, v91
	v_pk_fma_f32 v[32:33], v[42:43], v[32:33], 0 op_sel_hi:[1,1,0]
	s_nop 0
	v_pk_add_f32 v[42:43], v[32:33], v[34:35]
	v_mov_b64_e32 v[32:33], v[196:197]
	v_mov_b64_e32 v[34:35], v[198:199]
	s_nop 0
	v_pk_add_f32 v[44:45], v[44:45], v[32:33]
	v_lshlrev_b32_e32 v32, 16, v77
	v_and_b32_e32 v33, 0xffff0000, v77
	v_pk_fma_f32 v[32:33], v[46:47], v[32:33], 0 op_sel_hi:[1,1,0]
	v_and_b32_e32 v77, 0xffff0000, v94
	v_pk_add_f32 v[46:47], v[32:33], v[34:35]
	v_mov_b64_e32 v[32:33], v[200:201]
	v_mov_b64_e32 v[34:35], v[202:203]
	v_pk_fma_f32 v[16:17], v[16:17], v[76:77], 0 op_sel_hi:[1,1,0]
	v_lshlrev_b32_e32 v76, 16, v96
	v_and_b32_e32 v77, 0xffff0000, v96
	v_pk_fma_f32 v[20:21], v[20:21], v[76:77], 0 op_sel_hi:[1,1,0]
	v_lshlrev_b32_e32 v76, 16, v98
	v_and_b32_e32 v77, 0xffff0000, v98
	v_pk_fma_f32 v[24:25], v[24:25], v[76:77], 0 op_sel_hi:[1,1,0]
	v_lshlrev_b32_e32 v76, 16, v100
	v_and_b32_e32 v77, 0xffff0000, v100
	v_pk_fma_f32 v[28:29], v[28:29], v[76:77], 0 op_sel_hi:[1,1,0]
	v_lshlrev_b32_e32 v76, 16, v102
	v_and_b32_e32 v77, 0xffff0000, v102
	v_pk_fma_f32 v[0:1], v[0:1], v[76:77], 0 op_sel_hi:[1,1,0]
	s_nop 0
	v_pk_add_f32 v[32:33], v[16:17], v[32:33]
	v_lshlrev_b32_e32 v16, 16, v95
	v_and_b32_e32 v17, 0xffff0000, v95
	v_pk_fma_f32 v[16:17], v[18:19], v[16:17], 0 op_sel_hi:[1,1,0]
	s_nop 0
	v_pk_add_f32 v[34:35], v[16:17], v[34:35]
	v_mov_b64_e32 v[16:17], v[204:205]
	v_mov_b64_e32 v[18:19], v[206:207]
	s_nop 0
	v_pk_add_f32 v[20:21], v[20:21], v[16:17]
	v_lshlrev_b32_e32 v16, 16, v97
	v_and_b32_e32 v17, 0xffff0000, v97
	v_pk_fma_f32 v[16:17], v[22:23], v[16:17], 0 op_sel_hi:[1,1,0]
	s_nop 0
	v_pk_add_f32 v[22:23], v[16:17], v[18:19]
	v_mov_b64_e32 v[16:17], v[208:209]
	v_mov_b64_e32 v[18:19], v[210:211]
	s_nop 0
	v_pk_add_f32 v[24:25], v[24:25], v[16:17]
	v_lshlrev_b32_e32 v16, 16, v99
	v_and_b32_e32 v17, 0xffff0000, v99
	v_pk_fma_f32 v[16:17], v[26:27], v[16:17], 0 op_sel_hi:[1,1,0]
	s_nop 0
	v_pk_add_f32 v[26:27], v[16:17], v[18:19]
	v_mov_b64_e32 v[16:17], v[212:213]
	v_mov_b64_e32 v[18:19], v[214:215]
	s_nop 0
	v_pk_add_f32 v[28:29], v[28:29], v[16:17]
	v_lshlrev_b32_e32 v16, 16, v101
	v_and_b32_e32 v17, 0xffff0000, v101
	v_pk_fma_f32 v[16:17], v[30:31], v[16:17], 0 op_sel_hi:[1,1,0]
	s_nop 0
	v_pk_add_f32 v[30:31], v[16:17], v[18:19]
	v_mov_b64_e32 v[16:17], v[216:217]
	v_mov_b64_e32 v[18:19], v[218:219]
	s_nop 0
	v_pk_add_f32 v[76:77], v[0:1], v[16:17]
	v_lshlrev_b32_e32 v0, 16, v103
	v_and_b32_e32 v1, 0xffff0000, v103
	v_pk_fma_f32 v[0:1], v[2:3], v[0:1], 0 op_sel_hi:[1,1,0]
	v_lshlrev_b32_e32 v16, 16, v104
	v_pk_add_f32 v[78:79], v[0:1], v[18:19]
	v_mov_b64_e32 v[0:1], v[220:221]
	v_mov_b64_e32 v[2:3], v[222:223]
	v_and_b32_e32 v17, 0xffff0000, v104
	v_pk_fma_f32 v[4:5], v[4:5], v[16:17], 0 op_sel_hi:[1,1,0]
	v_cvt_pk_bf16_f32 v16, v44, v45
	v_cvt_pk_bf16_f32 v17, v46, v47
	v_cvt_pk_bf16_f32 v18, v20, v21
	v_cvt_pk_bf16_f32 v19, v22, v23
	v_cvt_pk_bf16_f32 v20, v24, v25
	v_cvt_pk_bf16_f32 v21, v26, v27
	v_cvt_pk_bf16_f32 v22, v28, v29
	v_cvt_pk_bf16_f32 v23, v30, v31
	v_cvt_pk_bf16_f32 v24, v76, v77
	v_cvt_pk_bf16_f32 v25, v78, v79
	v_lshlrev_b64 v[30:31], 11, v[74:75]
	v_lshl_add_u64 v[30:31], s[34:35], 0, v[30:31]
	v_lshl_add_u64 v[30:31], v[30:31], 0, v[72:73]
	s_nop 0
	v_pk_add_f32 v[80:81], v[4:5], v[0:1]
	v_lshlrev_b32_e32 v0, 16, v105
	v_and_b32_e32 v1, 0xffff0000, v105
	v_pk_fma_f32 v[0:1], v[6:7], v[0:1], 0 op_sel_hi:[1,1,0]
	v_lshlrev_b32_e32 v4, 16, v106
	v_pk_add_f32 v[82:83], v[0:1], v[2:3]
	v_mov_b64_e32 v[0:1], v[224:225]
	v_mov_b64_e32 v[2:3], v[226:227]
	v_and_b32_e32 v5, 0xffff0000, v106
	v_pk_fma_f32 v[4:5], v[8:9], v[4:5], 0 op_sel_hi:[1,1,0]
	v_cvt_pk_bf16_f32 v6, v60, v61
	v_cvt_pk_bf16_f32 v7, v62, v63
	v_cvt_pk_bf16_f32 v8, v48, v49
	v_cvt_pk_bf16_f32 v9, v50, v51
	v_cvt_pk_bf16_f32 v26, v80, v81
	v_cvt_pk_bf16_f32 v27, v82, v83
	s_nop 0
	v_pk_add_f32 v[84:85], v[4:5], v[0:1]
	v_lshlrev_b32_e32 v0, 16, v107
	v_and_b32_e32 v1, 0xffff0000, v107
	v_pk_fma_f32 v[0:1], v[10:11], v[0:1], 0 op_sel_hi:[1,1,0]
	v_lshlrev_b32_e32 v4, 16, v92
	v_pk_add_f32 v[86:87], v[0:1], v[2:3]
	v_mov_b64_e32 v[0:1], v[228:229]
	v_mov_b64_e32 v[2:3], v[230:231]
	v_and_b32_e32 v5, 0xffff0000, v92
	v_pk_fma_f32 v[4:5], v[12:13], v[4:5], 0 op_sel_hi:[1,1,0]
	v_cvt_pk_bf16_f32 v10, v36, v37
	v_cvt_pk_bf16_f32 v11, v38, v39
	v_cvt_pk_bf16_f32 v12, v40, v41
	v_cvt_pk_bf16_f32 v13, v42, v43
	v_cvt_pk_bf16_f32 v28, v84, v85
	v_cvt_pk_bf16_f32 v29, v86, v87
	s_nop 0
	v_pk_add_f32 v[70:71], v[4:5], v[0:1]
	v_lshlrev_b32_e32 v0, 16, v93
	v_and_b32_e32 v1, 0xffff0000, v93
	v_pk_fma_f32 v[0:1], v[14:15], v[0:1], 0 op_sel_hi:[1,1,0]
	v_cvt_pk_bf16_f32 v15, v34, v35
	v_mov_b32_e32 v34, v160
	v_pk_add_f32 v[88:89], v[0:1], v[2:3]
	v_lshrrev_b32_e32 v35, 6, v34
	v_and_b32_e32 v36, 31, v34
	v_mul_lo_u32 v35, v35, s66
	v_lshrrev_b32_e32 v37, 2, v34
	v_add_u32_e32 v35, 0, v35
	v_mul_u32_u24_e32 v36, 0x90, v36
	v_and_b32_e32 v37, 8, v37
	v_cvt_pk_bf16_f32 v0, v66, v67
	v_cvt_pk_bf16_f32 v1, v68, v69
	v_cvt_pk_bf16_f32 v2, v52, v53
	v_cvt_pk_bf16_f32 v3, v54, v55
	v_add3_u32 v36, v35, v36, v37
	v_cvt_pk_bf16_f32 v4, v56, v57
	v_cvt_pk_bf16_f32 v5, v58, v59
	v_cvt_pk_bf16_f32 v14, v32, v33
	s_barrier
; #define TID (opq_v((int)threadIdx.x))
; DEVINL void store_rows_via_lds(unsigned char* lds, const u32x2 (&pk)[2][2][4], bf16_t* out_row0, int ld) {
;     const int tid = TID, lane = tid & 63, w = tid >> 6, r = lane & 31, h = lane >> 5;
;     unsigned char* reg = lds + w * (64 * 144);
;     __syncthreads();
; #pragma unroll
;     for (int mi = 0; mi < 2; ++mi)
; #pragma unroll
;         for (int ni = 0; ni < 2; ++ni)
; #pragma unroll
;             for (int g = 0; g < 4; ++g) *(u32x2*)(reg + (mi * 32 + r) * 144 + (ni * 32 + 8 * g + 4 * h) * 2) = pk[mi][ni][g];
;     __syncthreads();
; #pragma unroll
;     for (int it = 0; it < 8; ++it) {
;         const int idx = it * 64 + lane, row = idx >> 3, c16 = idx & 7;
;         const u32x4 v = *(const u32x4*)(reg + row * 144 + c16 * 16);
;         *(u32x4*)(out_row0 + (size_t)row * ld + c16 * 8) = v;
;     }
	ds_write2_b64 v36, v[0:1], v[2:3] offset1:2
	ds_write2_b64 v36, v[4:5], v[6:7] offset0:4 offset1:6
	ds_write2_b64 v36, v[8:9], v[10:11] offset0:8 offset1:10
	ds_write2_b64 v36, v[12:13], v[16:17] offset0:12 offset1:14
	v_add_u32_e32 v0, 0x1000, v36
	v_cvt_pk_bf16_f32 v32, v70, v71
	v_cvt_pk_bf16_f32 v33, v88, v89
	ds_write2_b64 v0, v[14:15], v[18:19] offset0:64 offset1:66
	ds_write2_b64 v0, v[20:21], v[22:23] offset0:68 offset1:70
	ds_write2_b64 v0, v[24:25], v[26:27] offset0:72 offset1:74
	ds_write2_b64 v0, v[28:29], v[32:33] offset0:76 offset1:78
	v_lshlrev_b32_e32 v0, 4, v34
	v_bfe_u32 v6, v34, 3, 3
	v_and_b32_e32 v64, 0x70, v0
	v_mul_u32_u24_e32 v2, 0x90, v6
	v_add3_u32 v8, v35, v64, v2
	s_waitcnt lgkmcnt(0)
	s_barrier
	ds_read_b128 v[2:5], v8
	v_lshl_add_u64 v[0:1], v[30:31], 0, v[64:65]
	v_lshlrev_b32_e32 v64, 11, v6
	v_lshl_add_u64 v[6:7], v[0:1], 0, v[64:65]
	s_waitcnt lgkmcnt(0)
	global_store_dwordx4 v[6:7], v[2:5], off
	ds_read_b128 v[2:5], v8 offset:1152
	v_or_b32_e32 v6, 0x4000, v64
	v_mov_b32_e32 v7, v65
	v_lshl_add_u64 v[6:7], v[0:1], 0, v[6:7]
	s_waitcnt lgkmcnt(0)
	global_store_dwordx4 v[6:7], v[2:5], off
	ds_read_b128 v[2:5], v8 offset:2304
	v_or_b32_e32 v6, 0x8000, v64
	v_mov_b32_e32 v7, v65
	v_lshl_add_u64 v[6:7], v[0:1], 0, v[6:7]
	s_waitcnt lgkmcnt(0)
	global_store_dwordx4 v[6:7], v[2:5], off
	ds_read_b128 v[2:5], v8 offset:3456
	v_or_b32_e32 v6, 0xc000, v64
	v_mov_b32_e32 v7, v65
	v_lshl_add_u64 v[6:7], v[0:1], 0, v[6:7]
	s_waitcnt lgkmcnt(0)
	global_store_dwordx4 v[6:7], v[2:5], off
	ds_read_b128 v[2:5], v8 offset:4608
	v_or_b32_e32 v6, 0x10000, v64
	v_mov_b32_e32 v7, v65
	v_lshl_add_u64 v[6:7], v[0:1], 0, v[6:7]
	s_waitcnt lgkmcnt(0)
	global_store_dwordx4 v[6:7], v[2:5], off
	ds_read_b128 v[2:5], v8 offset:5760
	v_or_b32_e32 v6, 0x14000, v64
	v_mov_b32_e32 v7, v65
	v_lshl_add_u64 v[6:7], v[0:1], 0, v[6:7]
	s_waitcnt lgkmcnt(0)
	global_store_dwordx4 v[6:7], v[2:5], off
	ds_read_b128 v[2:5], v8 offset:6912
	v_or_b32_e32 v6, 0x18000, v64
	v_mov_b32_e32 v7, v65
	v_lshl_add_u64 v[6:7], v[0:1], 0, v[6:7]
	v_or_b32_e32 v64, 0x1c000, v64
	s_waitcnt lgkmcnt(0)
	global_store_dwordx4 v[6:7], v[2:5], off
	ds_read_b128 v[2:5], v8 offset:8064
	v_lshl_add_u64 v[0:1], v[0:1], 0, v[64:65]
	s_waitcnt lgkmcnt(0)
	global_store_dwordx4 v[0:1], v[2:5], off
	s_cbranch_scc0 .LBB0_89

;     DEVINL bf16_t* RW() const { return (bf16_t*)(ws + OFF_RW); }
;     DEVINL bf16_t* Y() const { return (bf16_t*)(ws + OFF_Y); }
; #define TID (opq_v((int)threadIdx.x))
; DEVINL void rwkv_scan(const Ctx& c, int layer, int b, int hd, const unsigned* cnt3, int nP, float* lds) {
;     float* sy = lds + 3 * STG;
;     const int tid = TID, lane = tid & 63, w = tid >> 6;
;     const bf16_t* rwbase = c.RW();
;     const bf16_t* GG = c.RW() + (size_t)6 * T * 512;
;     bf16_t* Y = c.Y() + (size_t)2 * T * 512;
;     const int rp = lane >> 3, jo = lane & 7, i0 = 16 * (w & 3) + 2 * rp;
;     f32x2 S0[4], S1[4];
; #pragma unroll
;     for (int j = 0; j < 4; ++j) { S0[j] = (f32x2){0.f, 0.f}; S1[j] = (f32x2){0.f, 0.f}; }
;     const float lng = c.in[I_LNG][layer * 512 + hd * 64 + lane], lnb = c.in[I_LNB][layer * 512 + hd * 64 + lane], rkv = c.in[I_RK][layer * 512 + hd * 64 + lane];
;     __syncthreads();
;     unsigned have = (unsigned)(layer * 16 + 1);
;     rw_wait_ready(cnt3, have, nP);
.LBB0_293:
	s_and_b64 vcc, exec, s[0:1]
	s_cbranch_vccz .LBB0_352
	v_readfirstlane_b32 s0, v160
	s_nop 3
	s_cmp_lt_u32 s0, 256
	s_cbranch_scc0 .Lscan_prio_done
	s_setprio 1
.Lscan_prio_done:
	s_mul_i32 s0, s95, 3
	s_ashr_i32 s1, s0, 31
	s_lshl_b64 s[0:1], s[0:1], 2
	v_readlane_b32 s4, v247, 28
	s_add_u32 s30, s4, s0
	v_readlane_b32 s0, v247, 29
	s_addc_u32 s31, s0, s1
	v_readlane_b32 s0, v245, 32
	s_cmp_lt_i32 s95, 32
	v_readlane_b32 s1, v245, 33
	s_cselect_b32 s34, 3, 2
	s_mov_b32 s20, s0
	s_lshl_b32 s1, s0, 9
	s_lshl_b32 s0, s95, 6
	v_mov_b32_e32 v146, v160
	s_and_b32 s0, s0, 0x1c0
	s_or_b32 s1, s0, s1
	v_and_b32_e32 v20, 63, v146
	s_waitcnt vmcnt(0)
	v_or_b32_e32 v0, s1, v20
	v_ashrrev_i32_e32 v1, 31, v0
	v_readlane_b32 s4, v246, 59
	v_lshlrev_b64 v[0:1], 2, v[0:1]
	v_readlane_b32 s14, v245, 5
	v_readlane_b32 s15, v245, 6
	v_readlane_b32 s12, v245, 3
	v_readlane_b32 s13, v245, 4
	v_readlane_b32 s16, v245, 7
	v_readlane_b32 s17, v245, 8
	v_lshl_add_u64 v[2:3], s[14:15], 0, v[0:1]
	global_load_dword v147, v[2:3], off
	v_lshl_add_u64 v[2:3], s[16:17], 0, v[0:1]
	v_lshl_add_u64 v[0:1], s[12:13], 0, v[0:1]
	global_load_dword v148, v[2:3], off
	global_load_dword v149, v[0:1], off
	v_readlane_b32 s10, v245, 1
	v_readlane_b32 s11, v245, 2
	s_lshl_b32 s10, s20, 4
	s_mov_b32 s66, 0
	s_mov_b32 s11, 0x1100000
	v_readlane_b32 s5, v246, 60
	v_readlane_b32 s6, v246, 61
	v_readlane_b32 s7, v246, 62
	v_readlane_b32 s8, v246, 63
	v_readlane_b32 s9, v245, 0
	v_readlane_b32 s18, v245, 9
	v_readlane_b32 s19, v245, 10
	s_waitcnt vmcnt(0)
	s_barrier
	s_branch .LBB0_296

; DEVINL void rw_load_ops(RwOps& o, const float* buf, int tt, int jo, int i0) {
;     const float* p = buf + tt * 64 + jo * 8;
; #pragma unroll
;     for (int q = 0; q < 2; ++q) {
;         o.r[q] = *(const f32x4*)(p + q * 4); o.w[q] = *(const f32x4*)(p + TC * 64 + q * 4); o.k[q] = *(const f32x4*)(p + 2 * TC * 64 + q * 4);
;         o.kk[q] = *(const f32x4*)(p + 4 * TC * 64 + q * 4); o.b[q] = *(const f32x4*)(p + 5 * TC * 64 + q * 4);
;     }
;     o.v = *(const f32x2*)(buf + 3 * TC * 64 + tt * 64 + i0);
; }
; DEVINL float oct_sum(float v) { v += DPPF(v, 0xB1); v += DPPF(v, 0x4E); v += DPPF(v, 0x141); return v; }
; DEVINL f32x2 rw_step(f32x2 (&S0)[4], f32x2 (&S1)[4], const RwOps& o) {
;     f32x2 a0 = {0.f, 0.f}, a1 = {0.f, 0.f};
; #pragma unroll
;     for (int p = 0; p < 4; ++p) { const f32x2 kk2 = {o.kk[p >> 1][(p & 1) * 2], o.kk[p >> 1][(p & 1) * 2 + 1]}; a0 += S0[p] * kk2; a1 += S1[p] * kk2; }
;     const float sa0 = oct_sum(a0[0] + a0[1]), sa1 = oct_sum(a1[0] + a1[1]);
;     const f32x2 n0 = {-sa0, -sa0}, n1 = {-sa1, -sa1}, v0 = {o.v[0], o.v[0]}, v1 = {o.v[1], o.v[1]};
;     f32x2 y0 = {0.f, 0.f}, y1 = {0.f, 0.f};
; #pragma unroll
;     for (int p = 0; p < 4; ++p) {
;         const int q = p >> 1, e = (p & 1) * 2;
;         const f32x2 k2 = {o.k[q][e], o.k[q][e + 1]}, b2 = {o.b[q][e], o.b[q][e + 1]}, w2 = {o.w[q][e], o.w[q][e + 1]}, r2 = {o.r[q][e], o.r[q][e + 1]};
;         S0[p] = S0[p] * w2 + (v0 * k2 + n0 * b2);
;         S1[p] = S1[p] * w2 + (v1 * k2 + n1 * b2);
;         y0 += S0[p] * r2; y1 += S1[p] * r2;
;     }
;     f32x2 y = {oct_sum(y0[0] + y0[1]), oct_sum(y1[0] + y1[1])};
;     return y;
; }
; DEVINL void rwkv_scan(const Ctx& c, int layer, int b, int hd, const unsigned* cnt3, int nP, float* lds) {
;     ...
;         if (w < 4) {
;             if (ch < NCH) {
;                 const float* buf = lds + (ch % 3) * STG;
;                 float* syw = sy + (ch & 1) * TC * 64;
;                 RwOps ops[3];
;                 rw_load_ops(ops[0], buf, 0, jo, i0);
;                 rw_load_ops(ops[1], buf, 1, jo, i0);
; #pragma unroll
;                 for (int tt = 0; tt < TC; ++tt) {
;                     if (tt + 2 < TC) rw_load_ops(ops[(tt + 2) % 3], buf, tt + 2, jo, i0);
;                     const f32x2 y = rw_step(S0, S1, ops[tt % 3]);
;                     *(f32x2*)(syw + tt * 64 + i0) = y;
;                 }
.LBB0_338:
	s_or_saveexec_b64 s[24:25], s[24:25]
	v_readlane_b32 s70, v245, 27
	v_readlane_b32 s71, v245, 30
	s_xor_b64 exec, exec, s[24:25]
	s_cbranch_execz .LBB0_316
	s_cmpk_eq_i32 s38, 0x88
	s_cbranch_scc1 .LBB0_316
	s_mul_i32 s26, s38, 0xab
	s_bfe_u32 s26, s26, 0x70009
	s_mul_i32 s26, s26, 3
	s_sub_i32 s26, s38, s26
	s_and_b32 s26, s26, 0xff
	s_mulk_i32 s26, 0x7000
	s_add_i32 s26, s26, 0
	v_lshl_add_u32 v172, v152, 2, s26
	v_lshl_add_u32 v173, v153, 2, s26
	v_add_u32_e32 v216, 0x3000, v173
	s_lshl_b32 s26, s38, 12
	s_and_b32 s26, s26, 0x1000
	v_add_u32_e32 v64, s26, v154
	v_readlane_b32 s71, v245, 30
	ds_read_b128 v[66:69], v172 offset:0
	ds_read_b128 v[70:73], v172 offset:16
	ds_read_b128 v[74:77], v172 offset:4096
	ds_read_b128 v[78:81], v172 offset:4112
	ds_read_b128 v[82:85], v172 offset:8192
	ds_read_b128 v[86:89], v172 offset:8208
	ds_read_b128 v[90:93], v172 offset:16384
	ds_read_b128 v[94:97], v172 offset:16400
	ds_read_b128 v[98:101], v172 offset:20480
	ds_read_b128 v[102:105], v172 offset:20496
	ds_read_b64 v[106:107], v216
	ds_read_b128 v[174:177], v172 offset:256
	ds_read_b128 v[178:181], v172 offset:272
	ds_read_b128 v[182:185], v172 offset:4352
	ds_read_b128 v[186:189], v172 offset:4368
	ds_read_b128 v[190:193], v172 offset:8448
	ds_read_b128 v[194:197], v172 offset:8464
	ds_read_b128 v[198:201], v172 offset:16640
	ds_read_b128 v[202:205], v172 offset:16656
	ds_read_b128 v[206:209], v172 offset:20736
	ds_read_b128 v[210:213], v172 offset:20752
	ds_read_b64 v[214:215], v216 offset:256
	s_waitcnt lgkmcnt(11)
	v_pk_fma_f32 v[16:17], v[24:25], v[90:91], 0 op_sel_hi:[1,1,0]
	v_pk_fma_f32 v[18:19], v[44:45], v[90:91], 0 op_sel_hi:[1,1,0]
	v_pk_fma_f32 v[16:17], v[46:47], v[92:93], v[16:17]
	v_pk_fma_f32 v[18:19], v[42:43], v[92:93], v[18:19]
	v_pk_fma_f32 v[16:17], v[60:61], v[94:95], v[16:17]
	v_pk_fma_f32 v[18:19], v[40:41], v[94:95], v[18:19]
	v_pk_fma_f32 v[16:17], v[28:29], v[96:97], v[16:17]
	v_pk_fma_f32 v[18:19], v[26:27], v[96:97], v[18:19]
	v_add_f32_e32 v20, v16, v17
	v_add_f32_e32 v21, v18, v19
	s_nop 0
	v_add_f32_dpp v20, v20, v20 quad_perm:[1,0,3,2] row_mask:0xf bank_mask:0xf bound_ctrl:1
	v_add_f32_dpp v21, v21, v21 quad_perm:[1,0,3,2] row_mask:0xf bank_mask:0xf bound_ctrl:1
	s_nop 0
	v_add_f32_dpp v20, v20, v20 quad_perm:[2,3,0,1] row_mask:0xf bank_mask:0xf bound_ctrl:1
	v_add_f32_dpp v21, v21, v21 quad_perm:[2,3,0,1] row_mask:0xf bank_mask:0xf bound_ctrl:1
	s_nop 0
	v_add_f32_dpp v20, v20, v20 row_half_mirror row_mask:0xf bank_mask:0xf bound_ctrl:1
	v_add_f32_dpp v38, v21, v21 row_half_mirror row_mask:0xf bank_mask:0xf bound_ctrl:1
	v_pk_mul_f32 v[34:35], v[98:99], v[20:21] op_sel_hi:[1,0] neg_lo:[0,1] neg_hi:[0,1]
	v_pk_mul_f32 v[36:37], v[98:99], v[38:39] op_sel_hi:[1,0] neg_lo:[0,1] neg_hi:[0,1]
	v_pk_mul_f32 v[48:49], v[100:101], v[20:21] op_sel_hi:[1,0] neg_lo:[0,1] neg_hi:[0,1]
	v_pk_mul_f32 v[50:51], v[100:101], v[38:39] op_sel_hi:[1,0] neg_lo:[0,1] neg_hi:[0,1]
	v_pk_mul_f32 v[52:53], v[102:103], v[20:21] op_sel_hi:[1,0] neg_lo:[0,1] neg_hi:[0,1]
	v_pk_mul_f32 v[54:55], v[102:103], v[38:39] op_sel_hi:[1,0] neg_lo:[0,1] neg_hi:[0,1]
	v_pk_mul_f32 v[56:57], v[104:105], v[20:21] op_sel_hi:[1,0] neg_lo:[0,1] neg_hi:[0,1]
	v_pk_mul_f32 v[58:59], v[104:105], v[38:39] op_sel_hi:[1,0] neg_lo:[0,1] neg_hi:[0,1]
	v_pk_fma_f32 v[34:35], v[82:83], v[106:107], v[34:35] op_sel_hi:[1,0,1]
	v_pk_fma_f32 v[36:37], v[82:83], v[106:107], v[36:37] op_sel:[0,1,0]
	v_pk_fma_f32 v[48:49], v[84:85], v[106:107], v[48:49] op_sel_hi:[1,0,1]
	v_pk_fma_f32 v[50:51], v[84:85], v[106:107], v[50:51] op_sel:[0,1,0]
	v_pk_fma_f32 v[52:53], v[86:87], v[106:107], v[52:53] op_sel_hi:[1,0,1]
	v_pk_fma_f32 v[54:55], v[86:87], v[106:107], v[54:55] op_sel:[0,1,0]
	v_pk_fma_f32 v[56:57], v[88:89], v[106:107], v[56:57] op_sel_hi:[1,0,1]
	v_pk_fma_f32 v[58:59], v[88:89], v[106:107], v[58:59] op_sel:[0,1,0]
	v_pk_fma_f32 v[24:25], v[74:75], v[24:25], v[34:35]
	v_pk_fma_f32 v[44:45], v[74:75], v[44:45], v[36:37]
	v_pk_fma_f32 v[46:47], v[76:77], v[46:47], v[48:49]
	v_pk_fma_f32 v[42:43], v[76:77], v[42:43], v[50:51]
	v_pk_fma_f32 v[60:61], v[78:79], v[60:61], v[52:53]
	v_pk_fma_f32 v[40:41], v[78:79], v[40:41], v[54:55]
	v_pk_fma_f32 v[28:29], v[80:81], v[28:29], v[56:57]
	v_pk_fma_f32 v[26:27], v[80:81], v[26:27], v[58:59]
	v_pk_fma_f32 v[22:23], v[66:67], v[24:25], 0 op_sel_hi:[1,1,0]
	v_pk_fma_f32 v[30:31], v[66:67], v[44:45], 0 op_sel_hi:[1,1,0]
	v_pk_fma_f32 v[22:23], v[68:69], v[46:47], v[22:23]
	v_pk_fma_f32 v[30:31], v[68:69], v[42:43], v[30:31]
	v_pk_fma_f32 v[22:23], v[70:71], v[60:61], v[22:23]
	v_pk_fma_f32 v[30:31], v[70:71], v[40:41], v[30:31]
	v_pk_fma_f32 v[22:23], v[72:73], v[28:29], v[22:23]
	v_pk_fma_f32 v[30:31], v[72:73], v[26:27], v[30:31]
	v_add_f32_e32 v32, v22, v23
	v_add_f32_e32 v33, v30, v31
	ds_read_b128 v[66:69], v172 offset:512
	ds_read_b128 v[70:73], v172 offset:528
	ds_read_b128 v[74:77], v172 offset:4608
	ds_read_b128 v[78:81], v172 offset:4624
	ds_read_b128 v[82:85], v172 offset:8704
	ds_read_b128 v[86:89], v172 offset:8720
	ds_read_b128 v[90:93], v172 offset:16896
	ds_read_b128 v[94:97], v172 offset:16912
	ds_read_b128 v[98:101], v172 offset:20992
	ds_read_b128 v[102:105], v172 offset:21008
	ds_read_b64 v[106:107], v216 offset:512
	s_waitcnt lgkmcnt(11)
; DEVINL float oct_sum(float v) { v += DPPF(v, 0xB1); v += DPPF(v, 0x4E); v += DPPF(v, 0x141); return v; }
; DEVINL f32x2 rw_step(f32x2 (&S0)[4], f32x2 (&S1)[4], const RwOps& o) {
;     f32x2 a0 = {0.f, 0.f}, a1 = {0.f, 0.f};
; #pragma unroll
;     for (int p = 0; p < 4; ++p) { const f32x2 kk2 = {o.kk[p >> 1][(p & 1) * 2], o.kk[p >> 1][(p & 1) * 2 + 1]}; a0 += S0[p] * kk2; a1 += S1[p] * kk2; }
;     const float sa0 = oct_sum(a0[0] + a0[1]), sa1 = oct_sum(a1[0] + a1[1]);
;     const f32x2 n0 = {-sa0, -sa0}, n1 = {-sa1, -sa1}, v0 = {o.v[0], o.v[0]}, v1 = {o.v[1], o.v[1]};
;     f32x2 y0 = {0.f, 0.f}, y1 = {0.f, 0.f};
; #pragma unroll
;     for (int p = 0; p < 4; ++p) {
;         const int q = p >> 1, e = (p & 1) * 2;
;         const f32x2 k2 = {o.k[q][e], o.k[q][e + 1]}, b2 = {o.b[q][e], o.b[q][e + 1]}, w2 = {o.w[q][e], o.w[q][e + 1]}, r2 = {o.r[q][e], o.r[q][e + 1]};
;         S0[p] = S0[p] * w2 + (v0 * k2 + n0 * b2);
;         S1[p] = S1[p] * w2 + (v1 * k2 + n1 * b2);
;         y0 += S0[p] * r2; y1 += S1[p] * r2;
;     }
;     f32x2 y = {oct_sum(y0[0] + y0[1]), oct_sum(y1[0] + y1[1])};
;     return y;
; }
; DEVINL void rwkv_scan(const Ctx& c, int layer, int b, int hd, const unsigned* cnt3, int nP, float* lds) {
;     ...
;                 for (int tt = 0; tt < TC; ++tt) {
;                     if (tt + 2 < TC) rw_load_ops(ops[(tt + 2) % 3], buf, tt + 2, jo, i0);
;                     const f32x2 y = rw_step(S0, S1, ops[tt % 3]);
;                     *(f32x2*)(syw + tt * 64 + i0) = y;
	v_pk_fma_f32 v[16:17], v[24:25], v[198:199], 0 op_sel_hi:[1,1,0]
	v_pk_fma_f32 v[18:19], v[44:45], v[198:199], 0 op_sel_hi:[1,1,0]
	v_pk_fma_f32 v[16:17], v[46:47], v[200:201], v[16:17]
	v_pk_fma_f32 v[18:19], v[42:43], v[200:201], v[18:19]
	v_pk_fma_f32 v[16:17], v[60:61], v[202:203], v[16:17]
	v_pk_fma_f32 v[18:19], v[40:41], v[202:203], v[18:19]
	v_pk_fma_f32 v[16:17], v[28:29], v[204:205], v[16:17]
	v_pk_fma_f32 v[18:19], v[26:27], v[204:205], v[18:19]
	v_add_f32_e32 v20, v16, v17
	v_add_f32_e32 v21, v18, v19
	v_add_f32_dpp v32, v32, v32 quad_perm:[1,0,3,2] row_mask:0xf bank_mask:0xf bound_ctrl:1
	v_add_f32_dpp v33, v33, v33 quad_perm:[1,0,3,2] row_mask:0xf bank_mask:0xf bound_ctrl:1
	v_add_f32_dpp v20, v20, v20 quad_perm:[1,0,3,2] row_mask:0xf bank_mask:0xf bound_ctrl:1
	v_add_f32_dpp v21, v21, v21 quad_perm:[1,0,3,2] row_mask:0xf bank_mask:0xf bound_ctrl:1
	v_add_f32_dpp v32, v32, v32 quad_perm:[2,3,0,1] row_mask:0xf bank_mask:0xf bound_ctrl:1
	v_add_f32_dpp v33, v33, v33 quad_perm:[2,3,0,1] row_mask:0xf bank_mask:0xf bound_ctrl:1
	v_add_f32_dpp v20, v20, v20 quad_perm:[2,3,0,1] row_mask:0xf bank_mask:0xf bound_ctrl:1
	v_add_f32_dpp v21, v21, v21 quad_perm:[2,3,0,1] row_mask:0xf bank_mask:0xf bound_ctrl:1
	v_add_f32_dpp v32, v32, v32 row_half_mirror row_mask:0xf bank_mask:0xf bound_ctrl:1
	v_add_f32_dpp v33, v33, v33 row_half_mirror row_mask:0xf bank_mask:0xf bound_ctrl:1
	v_add_f32_dpp v20, v20, v20 row_half_mirror row_mask:0xf bank_mask:0xf bound_ctrl:1
	v_add_f32_dpp v38, v21, v21 row_half_mirror row_mask:0xf bank_mask:0xf bound_ctrl:1
	ds_write_b64 v64, v[32:33]
	v_pk_mul_f32 v[34:35], v[206:207], v[20:21] op_sel_hi:[1,0] neg_lo:[0,1] neg_hi:[0,1]
	v_pk_mul_f32 v[36:37], v[206:207], v[38:39] op_sel_hi:[1,0] neg_lo:[0,1] neg_hi:[0,1]
	v_pk_mul_f32 v[48:49], v[208:209], v[20:21] op_sel_hi:[1,0] neg_lo:[0,1] neg_hi:[0,1]
	v_pk_mul_f32 v[50:51], v[208:209], v[38:39] op_sel_hi:[1,0] neg_lo:[0,1] neg_hi:[0,1]
	v_pk_mul_f32 v[52:53], v[210:211], v[20:21] op_sel_hi:[1,0] neg_lo:[0,1] neg_hi:[0,1]
	v_pk_mul_f32 v[54:55], v[210:211], v[38:39] op_sel_hi:[1,0] neg_lo:[0,1] neg_hi:[0,1]
	v_pk_mul_f32 v[56:57], v[212:213], v[20:21] op_sel_hi:[1,0] neg_lo:[0,1] neg_hi:[0,1]
	v_pk_mul_f32 v[58:59], v[212:213], v[38:39] op_sel_hi:[1,0] neg_lo:[0,1] neg_hi:[0,1]
	v_pk_fma_f32 v[34:35], v[190:191], v[214:215], v[34:35] op_sel_hi:[1,0,1]
	v_pk_fma_f32 v[36:37], v[190:191], v[214:215], v[36:37] op_sel:[0,1,0]
	v_pk_fma_f32 v[48:49], v[192:193], v[214:215], v[48:49] op_sel_hi:[1,0,1]
	v_pk_fma_f32 v[50:51], v[192:193], v[214:215], v[50:51] op_sel:[0,1,0]
	v_pk_fma_f32 v[52:53], v[194:195], v[214:215], v[52:53] op_sel_hi:[1,0,1]
	v_pk_fma_f32 v[54:55], v[194:195], v[214:215], v[54:55] op_sel:[0,1,0]
	v_pk_fma_f32 v[56:57], v[196:197], v[214:215], v[56:57] op_sel_hi:[1,0,1]
	v_pk_fma_f32 v[58:59], v[196:197], v[214:215], v[58:59] op_sel:[0,1,0]
	v_pk_fma_f32 v[24:25], v[182:183], v[24:25], v[34:35]
	v_pk_fma_f32 v[44:45], v[182:183], v[44:45], v[36:37]
	v_pk_fma_f32 v[46:47], v[184:185], v[46:47], v[48:49]
	v_pk_fma_f32 v[42:43], v[184:185], v[42:43], v[50:51]
	v_pk_fma_f32 v[60:61], v[186:187], v[60:61], v[52:53]
	v_pk_fma_f32 v[40:41], v[186:187], v[40:41], v[54:55]
	v_pk_fma_f32 v[28:29], v[188:189], v[28:29], v[56:57]
	v_pk_fma_f32 v[26:27], v[188:189], v[26:27], v[58:59]
	v_pk_fma_f32 v[22:23], v[174:175], v[24:25], 0 op_sel_hi:[1,1,0]
	v_pk_fma_f32 v[30:31], v[174:175], v[44:45], 0 op_sel_hi:[1,1,0]
	v_pk_fma_f32 v[22:23], v[176:177], v[46:47], v[22:23]
	v_pk_fma_f32 v[30:31], v[176:177], v[42:43], v[30:31]
	v_pk_fma_f32 v[22:23], v[178:179], v[60:61], v[22:23]
	v_pk_fma_f32 v[30:31], v[178:179], v[40:41], v[30:31]
	v_pk_fma_f32 v[22:23], v[180:181], v[28:29], v[22:23]
	v_pk_fma_f32 v[30:31], v[180:181], v[26:27], v[30:31]
	v_add_f32_e32 v32, v22, v23
	v_add_f32_e32 v33, v30, v31
	ds_read_b128 v[174:177], v172 offset:768
	ds_read_b128 v[178:181], v172 offset:784
	ds_read_b128 v[182:185], v172 offset:4864
	ds_read_b128 v[186:189], v172 offset:4880
	ds_read_b128 v[190:193], v172 offset:8960
	ds_read_b128 v[194:197], v172 offset:8976
	ds_read_b128 v[198:201], v172 offset:17152
	ds_read_b128 v[202:205], v172 offset:17168
	ds_read_b128 v[206:209], v172 offset:21248
	ds_read_b128 v[210:213], v172 offset:21264
	ds_read_b64 v[214:215], v216 offset:768
	s_waitcnt lgkmcnt(12)
; DEVINL float oct_sum(float v) { v += DPPF(v, 0xB1); v += DPPF(v, 0x4E); v += DPPF(v, 0x141); return v; }
; DEVINL f32x2 rw_step(f32x2 (&S0)[4], f32x2 (&S1)[4], const RwOps& o) {
;     f32x2 a0 = {0.f, 0.f}, a1 = {0.f, 0.f};
; #pragma unroll
;     for (int p = 0; p < 4; ++p) { const f32x2 kk2 = {o.kk[p >> 1][(p & 1) * 2], o.kk[p >> 1][(p & 1) * 2 + 1]}; a0 += S0[p] * kk2; a1 += S1[p] * kk2; }
;     const float sa0 = oct_sum(a0[0] + a0[1]), sa1 = oct_sum(a1[0] + a1[1]);
;     const f32x2 n0 = {-sa0, -sa0}, n1 = {-sa1, -sa1}, v0 = {o.v[0], o.v[0]}, v1 = {o.v[1], o.v[1]};
;     f32x2 y0 = {0.f, 0.f}, y1 = {0.f, 0.f};
; #pragma unroll
;     for (int p = 0; p < 4; ++p) {
;         const int q = p >> 1, e = (p & 1) * 2;
;         const f32x2 k2 = {o.k[q][e], o.k[q][e + 1]}, b2 = {o.b[q][e], o.b[q][e + 1]}, w2 = {o.w[q][e], o.w[q][e + 1]}, r2 = {o.r[q][e], o.r[q][e + 1]};
;         S0[p] = S0[p] * w2 + (v0 * k2 + n0 * b2);
;         S1[p] = S1[p] * w2 + (v1 * k2 + n1 * b2);
;         y0 += S0[p] * r2; y1 += S1[p] * r2;
;     }
;     f32x2 y = {oct_sum(y0[0] + y0[1]), oct_sum(y1[0] + y1[1])};
;     return y;
; }
; DEVINL void rwkv_scan(const Ctx& c, int layer, int b, int hd, const unsigned* cnt3, int nP, float* lds) {
;     ...
;                 for (int tt = 0; tt < TC; ++tt) {
;                     if (tt + 2 < TC) rw_load_ops(ops[(tt + 2) % 3], buf, tt + 2, jo, i0);
;                     const f32x2 y = rw_step(S0, S1, ops[tt % 3]);
;                     *(f32x2*)(syw + tt * 64 + i0) = y;
	v_pk_fma_f32 v[16:17], v[24:25], v[90:91], 0 op_sel_hi:[1,1,0]
	v_pk_fma_f32 v[18:19], v[44:45], v[90:91], 0 op_sel_hi:[1,1,0]
	v_pk_fma_f32 v[16:17], v[46:47], v[92:93], v[16:17]
	v_pk_fma_f32 v[18:19], v[42:43], v[92:93], v[18:19]
	v_pk_fma_f32 v[16:17], v[60:61], v[94:95], v[16:17]
	v_pk_fma_f32 v[18:19], v[40:41], v[94:95], v[18:19]
	v_pk_fma_f32 v[16:17], v[28:29], v[96:97], v[16:17]
	v_pk_fma_f32 v[18:19], v[26:27], v[96:97], v[18:19]
	v_add_f32_e32 v20, v16, v17
	v_add_f32_e32 v21, v18, v19
	v_add_f32_dpp v32, v32, v32 quad_perm:[1,0,3,2] row_mask:0xf bank_mask:0xf bound_ctrl:1
	v_add_f32_dpp v33, v33, v33 quad_perm:[1,0,3,2] row_mask:0xf bank_mask:0xf bound_ctrl:1
	v_add_f32_dpp v20, v20, v20 quad_perm:[1,0,3,2] row_mask:0xf bank_mask:0xf bound_ctrl:1
	v_add_f32_dpp v21, v21, v21 quad_perm:[1,0,3,2] row_mask:0xf bank_mask:0xf bound_ctrl:1
	v_add_f32_dpp v32, v32, v32 quad_perm:[2,3,0,1] row_mask:0xf bank_mask:0xf bound_ctrl:1
	v_add_f32_dpp v33, v33, v33 quad_perm:[2,3,0,1] row_mask:0xf bank_mask:0xf bound_ctrl:1
	v_add_f32_dpp v20, v20, v20 quad_perm:[2,3,0,1] row_mask:0xf bank_mask:0xf bound_ctrl:1
	v_add_f32_dpp v21, v21, v21 quad_perm:[2,3,0,1] row_mask:0xf bank_mask:0xf bound_ctrl:1
	v_add_f32_dpp v32, v32, v32 row_half_mirror row_mask:0xf bank_mask:0xf bound_ctrl:1
	v_add_f32_dpp v33, v33, v33 row_half_mirror row_mask:0xf bank_mask:0xf bound_ctrl:1
	v_add_f32_dpp v20, v20, v20 row_half_mirror row_mask:0xf bank_mask:0xf bound_ctrl:1
	v_add_f32_dpp v38, v21, v21 row_half_mirror row_mask:0xf bank_mask:0xf bound_ctrl:1
	ds_write_b64 v64, v[32:33] offset:256
	v_pk_mul_f32 v[34:35], v[98:99], v[20:21] op_sel_hi:[1,0] neg_lo:[0,1] neg_hi:[0,1]
	v_pk_mul_f32 v[36:37], v[98:99], v[38:39] op_sel_hi:[1,0] neg_lo:[0,1] neg_hi:[0,1]
	v_pk_mul_f32 v[48:49], v[100:101], v[20:21] op_sel_hi:[1,0] neg_lo:[0,1] neg_hi:[0,1]
	v_pk_mul_f32 v[50:51], v[100:101], v[38:39] op_sel_hi:[1,0] neg_lo:[0,1] neg_hi:[0,1]
	v_pk_mul_f32 v[52:53], v[102:103], v[20:21] op_sel_hi:[1,0] neg_lo:[0,1] neg_hi:[0,1]
	v_pk_mul_f32 v[54:55], v[102:103], v[38:39] op_sel_hi:[1,0] neg_lo:[0,1] neg_hi:[0,1]
	v_pk_mul_f32 v[56:57], v[104:105], v[20:21] op_sel_hi:[1,0] neg_lo:[0,1] neg_hi:[0,1]
	v_pk_mul_f32 v[58:59], v[104:105], v[38:39] op_sel_hi:[1,0] neg_lo:[0,1] neg_hi:[0,1]
	v_pk_fma_f32 v[34:35], v[82:83], v[106:107], v[34:35] op_sel_hi:[1,0,1]
	v_pk_fma_f32 v[36:37], v[82:83], v[106:107], v[36:37] op_sel:[0,1,0]
	v_pk_fma_f32 v[48:49], v[84:85], v[106:107], v[48:49] op_sel_hi:[1,0,1]
	v_pk_fma_f32 v[50:51], v[84:85], v[106:107], v[50:51] op_sel:[0,1,0]
	v_pk_fma_f32 v[52:53], v[86:87], v[106:107], v[52:53] op_sel_hi:[1,0,1]
	v_pk_fma_f32 v[54:55], v[86:87], v[106:107], v[54:55] op_sel:[0,1,0]
	v_pk_fma_f32 v[56:57], v[88:89], v[106:107], v[56:57] op_sel_hi:[1,0,1]
	v_pk_fma_f32 v[58:59], v[88:89], v[106:107], v[58:59] op_sel:[0,1,0]
	v_pk_fma_f32 v[24:25], v[74:75], v[24:25], v[34:35]
	v_pk_fma_f32 v[44:45], v[74:75], v[44:45], v[36:37]
	v_pk_fma_f32 v[46:47], v[76:77], v[46:47], v[48:49]
	v_pk_fma_f32 v[42:43], v[76:77], v[42:43], v[50:51]
	v_pk_fma_f32 v[60:61], v[78:79], v[60:61], v[52:53]
	v_pk_fma_f32 v[40:41], v[78:79], v[40:41], v[54:55]
	v_pk_fma_f32 v[28:29], v[80:81], v[28:29], v[56:57]
	v_pk_fma_f32 v[26:27], v[80:81], v[26:27], v[58:59]
	v_pk_fma_f32 v[22:23], v[66:67], v[24:25], 0 op_sel_hi:[1,1,0]
	v_pk_fma_f32 v[30:31], v[66:67], v[44:45], 0 op_sel_hi:[1,1,0]
	v_pk_fma_f32 v[22:23], v[68:69], v[46:47], v[22:23]
	v_pk_fma_f32 v[30:31], v[68:69], v[42:43], v[30:31]
	v_pk_fma_f32 v[22:23], v[70:71], v[60:61], v[22:23]
	v_pk_fma_f32 v[30:31], v[70:71], v[40:41], v[30:31]
	v_pk_fma_f32 v[22:23], v[72:73], v[28:29], v[22:23]
	v_pk_fma_f32 v[30:31], v[72:73], v[26:27], v[30:31]
	v_add_f32_e32 v32, v22, v23
	v_add_f32_e32 v33, v30, v31
	ds_read_b128 v[66:69], v172 offset:1024
	ds_read_b128 v[70:73], v172 offset:1040
	ds_read_b128 v[74:77], v172 offset:5120
	ds_read_b128 v[78:81], v172 offset:5136
	ds_read_b128 v[82:85], v172 offset:9216
	ds_read_b128 v[86:89], v172 offset:9232
	ds_read_b128 v[90:93], v172 offset:17408
	ds_read_b128 v[94:97], v172 offset:17424
	ds_read_b128 v[98:101], v172 offset:21504
	ds_read_b128 v[102:105], v172 offset:21520
	ds_read_b64 v[106:107], v216 offset:1024
	s_waitcnt lgkmcnt(12)
; DEVINL float oct_sum(float v) { v += DPPF(v, 0xB1); v += DPPF(v, 0x4E); v += DPPF(v, 0x141); return v; }
; DEVINL f32x2 rw_step(f32x2 (&S0)[4], f32x2 (&S1)[4], const RwOps& o) {
;     f32x2 a0 = {0.f, 0.f}, a1 = {0.f, 0.f};
; #pragma unroll
;     for (int p = 0; p < 4; ++p) { const f32x2 kk2 = {o.kk[p >> 1][(p & 1) * 2], o.kk[p >> 1][(p & 1) * 2 + 1]}; a0 += S0[p] * kk2; a1 += S1[p] * kk2; }
;     const float sa0 = oct_sum(a0[0] + a0[1]), sa1 = oct_sum(a1[0] + a1[1]);
;     const f32x2 n0 = {-sa0, -sa0}, n1 = {-sa1, -sa1}, v0 = {o.v[0], o.v[0]}, v1 = {o.v[1], o.v[1]};
;     f32x2 y0 = {0.f, 0.f}, y1 = {0.f, 0.f};
; #pragma unroll
;     for (int p = 0; p < 4; ++p) {
;         const int q = p >> 1, e = (p & 1) * 2;
;         const f32x2 k2 = {o.k[q][e], o.k[q][e + 1]}, b2 = {o.b[q][e], o.b[q][e + 1]}, w2 = {o.w[q][e], o.w[q][e + 1]}, r2 = {o.r[q][e], o.r[q][e + 1]};
;         S0[p] = S0[p] * w2 + (v0 * k2 + n0 * b2);
;         S1[p] = S1[p] * w2 + (v1 * k2 + n1 * b2);
;         y0 += S0[p] * r2; y1 += S1[p] * r2;
;     }
;     f32x2 y = {oct_sum(y0[0] + y0[1]), oct_sum(y1[0] + y1[1])};
;     return y;
; }
; DEVINL void rwkv_scan(const Ctx& c, int layer, int b, int hd, const unsigned* cnt3, int nP, float* lds) {
;     ...
;                 for (int tt = 0; tt < TC; ++tt) {
;                     if (tt + 2 < TC) rw_load_ops(ops[(tt + 2) % 3], buf, tt + 2, jo, i0);
;                     const f32x2 y = rw_step(S0, S1, ops[tt % 3]);
;                     *(f32x2*)(syw + tt * 64 + i0) = y;
	v_pk_fma_f32 v[16:17], v[24:25], v[198:199], 0 op_sel_hi:[1,1,0]
	v_pk_fma_f32 v[18:19], v[44:45], v[198:199], 0 op_sel_hi:[1,1,0]
	v_pk_fma_f32 v[16:17], v[46:47], v[200:201], v[16:17]
	v_pk_fma_f32 v[18:19], v[42:43], v[200:201], v[18:19]
	v_pk_fma_f32 v[16:17], v[60:61], v[202:203], v[16:17]
	v_pk_fma_f32 v[18:19], v[40:41], v[202:203], v[18:19]
	v_pk_fma_f32 v[16:17], v[28:29], v[204:205], v[16:17]
	v_pk_fma_f32 v[18:19], v[26:27], v[204:205], v[18:19]
	v_add_f32_e32 v20, v16, v17
	v_add_f32_e32 v21, v18, v19
	v_add_f32_dpp v32, v32, v32 quad_perm:[1,0,3,2] row_mask:0xf bank_mask:0xf bound_ctrl:1
	v_add_f32_dpp v33, v33, v33 quad_perm:[1,0,3,2] row_mask:0xf bank_mask:0xf bound_ctrl:1
	v_add_f32_dpp v20, v20, v20 quad_perm:[1,0,3,2] row_mask:0xf bank_mask:0xf bound_ctrl:1
	v_add_f32_dpp v21, v21, v21 quad_perm:[1,0,3,2] row_mask:0xf bank_mask:0xf bound_ctrl:1
	v_add_f32_dpp v32, v32, v32 quad_perm:[2,3,0,1] row_mask:0xf bank_mask:0xf bound_ctrl:1
	v_add_f32_dpp v33, v33, v33 quad_perm:[2,3,0,1] row_mask:0xf bank_mask:0xf bound_ctrl:1
	v_add_f32_dpp v20, v20, v20 quad_perm:[2,3,0,1] row_mask:0xf bank_mask:0xf bound_ctrl:1
	v_add_f32_dpp v21, v21, v21 quad_perm:[2,3,0,1] row_mask:0xf bank_mask:0xf bound_ctrl:1
	v_add_f32_dpp v32, v32, v32 row_half_mirror row_mask:0xf bank_mask:0xf bound_ctrl:1
	v_add_f32_dpp v33, v33, v33 row_half_mirror row_mask:0xf bank_mask:0xf bound_ctrl:1
	v_add_f32_dpp v20, v20, v20 row_half_mirror row_mask:0xf bank_mask:0xf bound_ctrl:1
	v_add_f32_dpp v38, v21, v21 row_half_mirror row_mask:0xf bank_mask:0xf bound_ctrl:1
	ds_write_b64 v64, v[32:33] offset:512
	v_pk_mul_f32 v[34:35], v[206:207], v[20:21] op_sel_hi:[1,0] neg_lo:[0,1] neg_hi:[0,1]
	v_pk_mul_f32 v[36:37], v[206:207], v[38:39] op_sel_hi:[1,0] neg_lo:[0,1] neg_hi:[0,1]
	v_pk_mul_f32 v[48:49], v[208:209], v[20:21] op_sel_hi:[1,0] neg_lo:[0,1] neg_hi:[0,1]
	v_pk_mul_f32 v[50:51], v[208:209], v[38:39] op_sel_hi:[1,0] neg_lo:[0,1] neg_hi:[0,1]
	v_pk_mul_f32 v[52:53], v[210:211], v[20:21] op_sel_hi:[1,0] neg_lo:[0,1] neg_hi:[0,1]
	v_pk_mul_f32 v[54:55], v[210:211], v[38:39] op_sel_hi:[1,0] neg_lo:[0,1] neg_hi:[0,1]
	v_pk_mul_f32 v[56:57], v[212:213], v[20:21] op_sel_hi:[1,0] neg_lo:[0,1] neg_hi:[0,1]
	v_pk_mul_f32 v[58:59], v[212:213], v[38:39] op_sel_hi:[1,0] neg_lo:[0,1] neg_hi:[0,1]
	v_pk_fma_f32 v[34:35], v[190:191], v[214:215], v[34:35] op_sel_hi:[1,0,1]
	v_pk_fma_f32 v[36:37], v[190:191], v[214:215], v[36:37] op_sel:[0,1,0]
	v_pk_fma_f32 v[48:49], v[192:193], v[214:215], v[48:49] op_sel_hi:[1,0,1]
	v_pk_fma_f32 v[50:51], v[192:193], v[214:215], v[50:51] op_sel:[0,1,0]
	v_pk_fma_f32 v[52:53], v[194:195], v[214:215], v[52:53] op_sel_hi:[1,0,1]
	v_pk_fma_f32 v[54:55], v[194:195], v[214:215], v[54:55] op_sel:[0,1,0]
	v_pk_fma_f32 v[56:57], v[196:197], v[214:215], v[56:57] op_sel_hi:[1,0,1]
	v_pk_fma_f32 v[58:59], v[196:197], v[214:215], v[58:59] op_sel:[0,1,0]
	v_pk_fma_f32 v[24:25], v[182:183], v[24:25], v[34:35]
	v_pk_fma_f32 v[44:45], v[182:183], v[44:45], v[36:37]
	v_pk_fma_f32 v[46:47], v[184:185], v[46:47], v[48:49]
	v_pk_fma_f32 v[42:43], v[184:185], v[42:43], v[50:51]
	v_pk_fma_f32 v[60:61], v[186:187], v[60:61], v[52:53]
	v_pk_fma_f32 v[40:41], v[186:187], v[40:41], v[54:55]
	v_pk_fma_f32 v[28:29], v[188:189], v[28:29], v[56:57]
	v_pk_fma_f32 v[26:27], v[188:189], v[26:27], v[58:59]
	v_pk_fma_f32 v[22:23], v[174:175], v[24:25], 0 op_sel_hi:[1,1,0]
	v_pk_fma_f32 v[30:31], v[174:175], v[44:45], 0 op_sel_hi:[1,1,0]
	v_pk_fma_f32 v[22:23], v[176:177], v[46:47], v[22:23]
	v_pk_fma_f32 v[30:31], v[176:177], v[42:43], v[30:31]
	v_pk_fma_f32 v[22:23], v[178:179], v[60:61], v[22:23]
	v_pk_fma_f32 v[30:31], v[178:179], v[40:41], v[30:31]
	v_pk_fma_f32 v[22:23], v[180:181], v[28:29], v[22:23]
	v_pk_fma_f32 v[30:31], v[180:181], v[26:27], v[30:31]
	v_add_f32_e32 v32, v22, v23
	v_add_f32_e32 v33, v30, v31
	ds_read_b128 v[174:177], v172 offset:1280
	ds_read_b128 v[178:181], v172 offset:1296
	ds_read_b128 v[182:185], v172 offset:5376
	ds_read_b128 v[186:189], v172 offset:5392
	ds_read_b128 v[190:193], v172 offset:9472
	ds_read_b128 v[194:197], v172 offset:9488
	ds_read_b128 v[198:201], v172 offset:17664
	ds_read_b128 v[202:205], v172 offset:17680
	ds_read_b128 v[206:209], v172 offset:21760
	ds_read_b128 v[210:213], v172 offset:21776
	ds_read_b64 v[214:215], v216 offset:1280
	s_waitcnt lgkmcnt(12)
; DEVINL float oct_sum(float v) { v += DPPF(v, 0xB1); v += DPPF(v, 0x4E); v += DPPF(v, 0x141); return v; }
; DEVINL f32x2 rw_step(f32x2 (&S0)[4], f32x2 (&S1)[4], const RwOps& o) {
;     f32x2 a0 = {0.f, 0.f}, a1 = {0.f, 0.f};
; #pragma unroll
;     for (int p = 0; p < 4; ++p) { const f32x2 kk2 = {o.kk[p >> 1][(p & 1) * 2], o.kk[p >> 1][(p & 1) * 2 + 1]}; a0 += S0[p] * kk2; a1 += S1[p] * kk2; }
;     const float sa0 = oct_sum(a0[0] + a0[1]), sa1 = oct_sum(a1[0] + a1[1]);
;     const f32x2 n0 = {-sa0, -sa0}, n1 = {-sa1, -sa1}, v0 = {o.v[0], o.v[0]}, v1 = {o.v[1], o.v[1]};
;     f32x2 y0 = {0.f, 0.f}, y1 = {0.f, 0.f};
; #pragma unroll
;     for (int p = 0; p < 4; ++p) {
;         const int q = p >> 1, e = (p & 1) * 2;
;         const f32x2 k2 = {o.k[q][e], o.k[q][e + 1]}, b2 = {o.b[q][e], o.b[q][e + 1]}, w2 = {o.w[q][e], o.w[q][e + 1]}, r2 = {o.r[q][e], o.r[q][e + 1]};
;         S0[p] = S0[p] * w2 + (v0 * k2 + n0 * b2);
;         S1[p] = S1[p] * w2 + (v1 * k2 + n1 * b2);
;         y0 += S0[p] * r2; y1 += S1[p] * r2;
;     }
;     f32x2 y = {oct_sum(y0[0] + y0[1]), oct_sum(y1[0] + y1[1])};
;     return y;
; }
; DEVINL void rwkv_scan(const Ctx& c, int layer, int b, int hd, const unsigned* cnt3, int nP, float* lds) {
;     ...
;                 for (int tt = 0; tt < TC; ++tt) {
;                     if (tt + 2 < TC) rw_load_ops(ops[(tt + 2) % 3], buf, tt + 2, jo, i0);
;                     const f32x2 y = rw_step(S0, S1, ops[tt % 3]);
;                     *(f32x2*)(syw + tt * 64 + i0) = y;
	v_pk_fma_f32 v[16:17], v[24:25], v[90:91], 0 op_sel_hi:[1,1,0]
	v_pk_fma_f32 v[18:19], v[44:45], v[90:91], 0 op_sel_hi:[1,1,0]
	v_pk_fma_f32 v[16:17], v[46:47], v[92:93], v[16:17]
	v_pk_fma_f32 v[18:19], v[42:43], v[92:93], v[18:19]
	v_pk_fma_f32 v[16:17], v[60:61], v[94:95], v[16:17]
	v_pk_fma_f32 v[18:19], v[40:41], v[94:95], v[18:19]
	v_pk_fma_f32 v[16:17], v[28:29], v[96:97], v[16:17]
	v_pk_fma_f32 v[18:19], v[26:27], v[96:97], v[18:19]
	v_add_f32_e32 v20, v16, v17
	v_add_f32_e32 v21, v18, v19
	v_add_f32_dpp v32, v32, v32 quad_perm:[1,0,3,2] row_mask:0xf bank_mask:0xf bound_ctrl:1
	v_add_f32_dpp v33, v33, v33 quad_perm:[1,0,3,2] row_mask:0xf bank_mask:0xf bound_ctrl:1
	v_add_f32_dpp v20, v20, v20 quad_perm:[1,0,3,2] row_mask:0xf bank_mask:0xf bound_ctrl:1
	v_add_f32_dpp v21, v21, v21 quad_perm:[1,0,3,2] row_mask:0xf bank_mask:0xf bound_ctrl:1
	v_add_f32_dpp v32, v32, v32 quad_perm:[2,3,0,1] row_mask:0xf bank_mask:0xf bound_ctrl:1
	v_add_f32_dpp v33, v33, v33 quad_perm:[2,3,0,1] row_mask:0xf bank_mask:0xf bound_ctrl:1
	v_add_f32_dpp v20, v20, v20 quad_perm:[2,3,0,1] row_mask:0xf bank_mask:0xf bound_ctrl:1
	v_add_f32_dpp v21, v21, v21 quad_perm:[2,3,0,1] row_mask:0xf bank_mask:0xf bound_ctrl:1
	v_add_f32_dpp v32, v32, v32 row_half_mirror row_mask:0xf bank_mask:0xf bound_ctrl:1
	v_add_f32_dpp v33, v33, v33 row_half_mirror row_mask:0xf bank_mask:0xf bound_ctrl:1
	v_add_f32_dpp v20, v20, v20 row_half_mirror row_mask:0xf bank_mask:0xf bound_ctrl:1
	v_add_f32_dpp v38, v21, v21 row_half_mirror row_mask:0xf bank_mask:0xf bound_ctrl:1
	ds_write_b64 v64, v[32:33] offset:768
	v_pk_mul_f32 v[34:35], v[98:99], v[20:21] op_sel_hi:[1,0] neg_lo:[0,1] neg_hi:[0,1]
	v_pk_mul_f32 v[36:37], v[98:99], v[38:39] op_sel_hi:[1,0] neg_lo:[0,1] neg_hi:[0,1]
	v_pk_mul_f32 v[48:49], v[100:101], v[20:21] op_sel_hi:[1,0] neg_lo:[0,1] neg_hi:[0,1]
	v_pk_mul_f32 v[50:51], v[100:101], v[38:39] op_sel_hi:[1,0] neg_lo:[0,1] neg_hi:[0,1]
	v_pk_mul_f32 v[52:53], v[102:103], v[20:21] op_sel_hi:[1,0] neg_lo:[0,1] neg_hi:[0,1]
	v_pk_mul_f32 v[54:55], v[102:103], v[38:39] op_sel_hi:[1,0] neg_lo:[0,1] neg_hi:[0,1]
	v_pk_mul_f32 v[56:57], v[104:105], v[20:21] op_sel_hi:[1,0] neg_lo:[0,1] neg_hi:[0,1]
	v_pk_mul_f32 v[58:59], v[104:105], v[38:39] op_sel_hi:[1,0] neg_lo:[0,1] neg_hi:[0,1]
	v_pk_fma_f32 v[34:35], v[82:83], v[106:107], v[34:35] op_sel_hi:[1,0,1]
	v_pk_fma_f32 v[36:37], v[82:83], v[106:107], v[36:37] op_sel:[0,1,0]
	v_pk_fma_f32 v[48:49], v[84:85], v[106:107], v[48:49] op_sel_hi:[1,0,1]
	v_pk_fma_f32 v[50:51], v[84:85], v[106:107], v[50:51] op_sel:[0,1,0]
	v_pk_fma_f32 v[52:53], v[86:87], v[106:107], v[52:53] op_sel_hi:[1,0,1]
	v_pk_fma_f32 v[54:55], v[86:87], v[106:107], v[54:55] op_sel:[0,1,0]
	v_pk_fma_f32 v[56:57], v[88:89], v[106:107], v[56:57] op_sel_hi:[1,0,1]
	v_pk_fma_f32 v[58:59], v[88:89], v[106:107], v[58:59] op_sel:[0,1,0]
	v_pk_fma_f32 v[24:25], v[74:75], v[24:25], v[34:35]
	v_pk_fma_f32 v[44:45], v[74:75], v[44:45], v[36:37]
	v_pk_fma_f32 v[46:47], v[76:77], v[46:47], v[48:49]
	v_pk_fma_f32 v[42:43], v[76:77], v[42:43], v[50:51]
	v_pk_fma_f32 v[60:61], v[78:79], v[60:61], v[52:53]
	v_pk_fma_f32 v[40:41], v[78:79], v[40:41], v[54:55]
	v_pk_fma_f32 v[28:29], v[80:81], v[28:29], v[56:57]
	v_pk_fma_f32 v[26:27], v[80:81], v[26:27], v[58:59]
	v_pk_fma_f32 v[22:23], v[66:67], v[24:25], 0 op_sel_hi:[1,1,0]
	v_pk_fma_f32 v[30:31], v[66:67], v[44:45], 0 op_sel_hi:[1,1,0]
	v_pk_fma_f32 v[22:23], v[68:69], v[46:47], v[22:23]
	v_pk_fma_f32 v[30:31], v[68:69], v[42:43], v[30:31]
	v_pk_fma_f32 v[22:23], v[70:71], v[60:61], v[22:23]
	v_pk_fma_f32 v[30:31], v[70:71], v[40:41], v[30:31]
	v_pk_fma_f32 v[22:23], v[72:73], v[28:29], v[22:23]
	v_pk_fma_f32 v[30:31], v[72:73], v[26:27], v[30:31]
	v_add_f32_e32 v32, v22, v23
	v_add_f32_e32 v33, v30, v31
	ds_read_b128 v[66:69], v172 offset:1536
	ds_read_b128 v[70:73], v172 offset:1552
	ds_read_b128 v[74:77], v172 offset:5632
	ds_read_b128 v[78:81], v172 offset:5648
	ds_read_b128 v[82:85], v172 offset:9728
	ds_read_b128 v[86:89], v172 offset:9744
	ds_read_b128 v[90:93], v172 offset:17920
	ds_read_b128 v[94:97], v172 offset:17936
	ds_read_b128 v[98:101], v172 offset:22016
	ds_read_b128 v[102:105], v172 offset:22032
	ds_read_b64 v[106:107], v216 offset:1536
	s_waitcnt lgkmcnt(12)
; DEVINL float oct_sum(float v) { v += DPPF(v, 0xB1); v += DPPF(v, 0x4E); v += DPPF(v, 0x141); return v; }
; DEVINL f32x2 rw_step(f32x2 (&S0)[4], f32x2 (&S1)[4], const RwOps& o) {
;     f32x2 a0 = {0.f, 0.f}, a1 = {0.f, 0.f};
; #pragma unroll
;     for (int p = 0; p < 4; ++p) { const f32x2 kk2 = {o.kk[p >> 1][(p & 1) * 2], o.kk[p >> 1][(p & 1) * 2 + 1]}; a0 += S0[p] * kk2; a1 += S1[p] * kk2; }
;     const float sa0 = oct_sum(a0[0] + a0[1]), sa1 = oct_sum(a1[0] + a1[1]);
;     const f32x2 n0 = {-sa0, -sa0}, n1 = {-sa1, -sa1}, v0 = {o.v[0], o.v[0]}, v1 = {o.v[1], o.v[1]};
;     f32x2 y0 = {0.f, 0.f}, y1 = {0.f, 0.f};
; #pragma unroll
;     for (int p = 0; p < 4; ++p) {
;         const int q = p >> 1, e = (p & 1) * 2;
;         const f32x2 k2 = {o.k[q][e], o.k[q][e + 1]}, b2 = {o.b[q][e], o.b[q][e + 1]}, w2 = {o.w[q][e], o.w[q][e + 1]}, r2 = {o.r[q][e], o.r[q][e + 1]};
;         S0[p] = S0[p] * w2 + (v0 * k2 + n0 * b2);
;         S1[p] = S1[p] * w2 + (v1 * k2 + n1 * b2);
;         y0 += S0[p] * r2; y1 += S1[p] * r2;
;     }
;     f32x2 y = {oct_sum(y0[0] + y0[1]), oct_sum(y1[0] + y1[1])};
;     return y;
; }
; DEVINL void rwkv_scan(const Ctx& c, int layer, int b, int hd, const unsigned* cnt3, int nP, float* lds) {
;     ...
;                 for (int tt = 0; tt < TC; ++tt) {
;                     if (tt + 2 < TC) rw_load_ops(ops[(tt + 2) % 3], buf, tt + 2, jo, i0);
;                     const f32x2 y = rw_step(S0, S1, ops[tt % 3]);
;                     *(f32x2*)(syw + tt * 64 + i0) = y;
	v_pk_fma_f32 v[16:17], v[24:25], v[198:199], 0 op_sel_hi:[1,1,0]
	v_pk_fma_f32 v[18:19], v[44:45], v[198:199], 0 op_sel_hi:[1,1,0]
	v_pk_fma_f32 v[16:17], v[46:47], v[200:201], v[16:17]
	v_pk_fma_f32 v[18:19], v[42:43], v[200:201], v[18:19]
	v_pk_fma_f32 v[16:17], v[60:61], v[202:203], v[16:17]
	v_pk_fma_f32 v[18:19], v[40:41], v[202:203], v[18:19]
	v_pk_fma_f32 v[16:17], v[28:29], v[204:205], v[16:17]
	v_pk_fma_f32 v[18:19], v[26:27], v[204:205], v[18:19]
	v_add_f32_e32 v20, v16, v17
	v_add_f32_e32 v21, v18, v19
	v_add_f32_dpp v32, v32, v32 quad_perm:[1,0,3,2] row_mask:0xf bank_mask:0xf bound_ctrl:1
	v_add_f32_dpp v33, v33, v33 quad_perm:[1,0,3,2] row_mask:0xf bank_mask:0xf bound_ctrl:1
	v_add_f32_dpp v20, v20, v20 quad_perm:[1,0,3,2] row_mask:0xf bank_mask:0xf bound_ctrl:1
	v_add_f32_dpp v21, v21, v21 quad_perm:[1,0,3,2] row_mask:0xf bank_mask:0xf bound_ctrl:1
	v_add_f32_dpp v32, v32, v32 quad_perm:[2,3,0,1] row_mask:0xf bank_mask:0xf bound_ctrl:1
	v_add_f32_dpp v33, v33, v33 quad_perm:[2,3,0,1] row_mask:0xf bank_mask:0xf bound_ctrl:1
	v_add_f32_dpp v20, v20, v20 quad_perm:[2,3,0,1] row_mask:0xf bank_mask:0xf bound_ctrl:1
	v_add_f32_dpp v21, v21, v21 quad_perm:[2,3,0,1] row_mask:0xf bank_mask:0xf bound_ctrl:1
	v_add_f32_dpp v32, v32, v32 row_half_mirror row_mask:0xf bank_mask:0xf bound_ctrl:1
	v_add_f32_dpp v33, v33, v33 row_half_mirror row_mask:0xf bank_mask:0xf bound_ctrl:1
	v_add_f32_dpp v20, v20, v20 row_half_mirror row_mask:0xf bank_mask:0xf bound_ctrl:1
	v_add_f32_dpp v38, v21, v21 row_half_mirror row_mask:0xf bank_mask:0xf bound_ctrl:1
	ds_write_b64 v64, v[32:33] offset:1024
	v_pk_mul_f32 v[34:35], v[206:207], v[20:21] op_sel_hi:[1,0] neg_lo:[0,1] neg_hi:[0,1]
	v_pk_mul_f32 v[36:37], v[206:207], v[38:39] op_sel_hi:[1,0] neg_lo:[0,1] neg_hi:[0,1]
	v_pk_mul_f32 v[48:49], v[208:209], v[20:21] op_sel_hi:[1,0] neg_lo:[0,1] neg_hi:[0,1]
	v_pk_mul_f32 v[50:51], v[208:209], v[38:39] op_sel_hi:[1,0] neg_lo:[0,1] neg_hi:[0,1]
	v_pk_mul_f32 v[52:53], v[210:211], v[20:21] op_sel_hi:[1,0] neg_lo:[0,1] neg_hi:[0,1]
	v_pk_mul_f32 v[54:55], v[210:211], v[38:39] op_sel_hi:[1,0] neg_lo:[0,1] neg_hi:[0,1]
	v_pk_mul_f32 v[56:57], v[212:213], v[20:21] op_sel_hi:[1,0] neg_lo:[0,1] neg_hi:[0,1]
	v_pk_mul_f32 v[58:59], v[212:213], v[38:39] op_sel_hi:[1,0] neg_lo:[0,1] neg_hi:[0,1]
	v_pk_fma_f32 v[34:35], v[190:191], v[214:215], v[34:35] op_sel_hi:[1,0,1]
	v_pk_fma_f32 v[36:37], v[190:191], v[214:215], v[36:37] op_sel:[0,1,0]
	v_pk_fma_f32 v[48:49], v[192:193], v[214:215], v[48:49] op_sel_hi:[1,0,1]
	v_pk_fma_f32 v[50:51], v[192:193], v[214:215], v[50:51] op_sel:[0,1,0]
	v_pk_fma_f32 v[52:53], v[194:195], v[214:215], v[52:53] op_sel_hi:[1,0,1]
	v_pk_fma_f32 v[54:55], v[194:195], v[214:215], v[54:55] op_sel:[0,1,0]
	v_pk_fma_f32 v[56:57], v[196:197], v[214:215], v[56:57] op_sel_hi:[1,0,1]
	v_pk_fma_f32 v[58:59], v[196:197], v[214:215], v[58:59] op_sel:[0,1,0]
	v_pk_fma_f32 v[24:25], v[182:183], v[24:25], v[34:35]
	v_pk_fma_f32 v[44:45], v[182:183], v[44:45], v[36:37]
	v_pk_fma_f32 v[46:47], v[184:185], v[46:47], v[48:49]
	v_pk_fma_f32 v[42:43], v[184:185], v[42:43], v[50:51]
	v_pk_fma_f32 v[60:61], v[186:187], v[60:61], v[52:53]
	v_pk_fma_f32 v[40:41], v[186:187], v[40:41], v[54:55]
	v_pk_fma_f32 v[28:29], v[188:189], v[28:29], v[56:57]
	v_pk_fma_f32 v[26:27], v[188:189], v[26:27], v[58:59]
	v_pk_fma_f32 v[22:23], v[174:175], v[24:25], 0 op_sel_hi:[1,1,0]
	v_pk_fma_f32 v[30:31], v[174:175], v[44:45], 0 op_sel_hi:[1,1,0]
	v_pk_fma_f32 v[22:23], v[176:177], v[46:47], v[22:23]
	v_pk_fma_f32 v[30:31], v[176:177], v[42:43], v[30:31]
	v_pk_fma_f32 v[22:23], v[178:179], v[60:61], v[22:23]
	v_pk_fma_f32 v[30:31], v[178:179], v[40:41], v[30:31]
	v_pk_fma_f32 v[22:23], v[180:181], v[28:29], v[22:23]
	v_pk_fma_f32 v[30:31], v[180:181], v[26:27], v[30:31]
	v_add_f32_e32 v32, v22, v23
	v_add_f32_e32 v33, v30, v31
	ds_read_b128 v[174:177], v172 offset:1792
	ds_read_b128 v[178:181], v172 offset:1808
	ds_read_b128 v[182:185], v172 offset:5888
	ds_read_b128 v[186:189], v172 offset:5904
	ds_read_b128 v[190:193], v172 offset:9984
	ds_read_b128 v[194:197], v172 offset:10000
	ds_read_b128 v[198:201], v172 offset:18176
	ds_read_b128 v[202:205], v172 offset:18192
	ds_read_b128 v[206:209], v172 offset:22272
	ds_read_b128 v[210:213], v172 offset:22288
	ds_read_b64 v[214:215], v216 offset:1792
	s_waitcnt lgkmcnt(12)
; DEVINL float oct_sum(float v) { v += DPPF(v, 0xB1); v += DPPF(v, 0x4E); v += DPPF(v, 0x141); return v; }
; DEVINL f32x2 rw_step(f32x2 (&S0)[4], f32x2 (&S1)[4], const RwOps& o) {
;     f32x2 a0 = {0.f, 0.f}, a1 = {0.f, 0.f};
; #pragma unroll
;     for (int p = 0; p < 4; ++p) { const f32x2 kk2 = {o.kk[p >> 1][(p & 1) * 2], o.kk[p >> 1][(p & 1) * 2 + 1]}; a0 += S0[p] * kk2; a1 += S1[p] * kk2; }
;     const float sa0 = oct_sum(a0[0] + a0[1]), sa1 = oct_sum(a1[0] + a1[1]);
;     const f32x2 n0 = {-sa0, -sa0}, n1 = {-sa1, -sa1}, v0 = {o.v[0], o.v[0]}, v1 = {o.v[1], o.v[1]};
;     f32x2 y0 = {0.f, 0.f}, y1 = {0.f, 0.f};
; #pragma unroll
;     for (int p = 0; p < 4; ++p) {
;         const int q = p >> 1, e = (p & 1) * 2;
;         const f32x2 k2 = {o.k[q][e], o.k[q][e + 1]}, b2 = {o.b[q][e], o.b[q][e + 1]}, w2 = {o.w[q][e], o.w[q][e + 1]}, r2 = {o.r[q][e], o.r[q][e + 1]};
;         S0[p] = S0[p] * w2 + (v0 * k2 + n0 * b2);
;         S1[p] = S1[p] * w2 + (v1 * k2 + n1 * b2);
;         y0 += S0[p] * r2; y1 += S1[p] * r2;
;     }
;     f32x2 y = {oct_sum(y0[0] + y0[1]), oct_sum(y1[0] + y1[1])};
;     return y;
; }
; DEVINL void rwkv_scan(const Ctx& c, int layer, int b, int hd, const unsigned* cnt3, int nP, float* lds) {
;     ...
;                 for (int tt = 0; tt < TC; ++tt) {
;                     if (tt + 2 < TC) rw_load_ops(ops[(tt + 2) % 3], buf, tt + 2, jo, i0);
;                     const f32x2 y = rw_step(S0, S1, ops[tt % 3]);
;                     *(f32x2*)(syw + tt * 64 + i0) = y;
	v_pk_fma_f32 v[16:17], v[24:25], v[90:91], 0 op_sel_hi:[1,1,0]
	v_pk_fma_f32 v[18:19], v[44:45], v[90:91], 0 op_sel_hi:[1,1,0]
	v_pk_fma_f32 v[16:17], v[46:47], v[92:93], v[16:17]
	v_pk_fma_f32 v[18:19], v[42:43], v[92:93], v[18:19]
	v_pk_fma_f32 v[16:17], v[60:61], v[94:95], v[16:17]
	v_pk_fma_f32 v[18:19], v[40:41], v[94:95], v[18:19]
	v_pk_fma_f32 v[16:17], v[28:29], v[96:97], v[16:17]
	v_pk_fma_f32 v[18:19], v[26:27], v[96:97], v[18:19]
	v_add_f32_e32 v20, v16, v17
	v_add_f32_e32 v21, v18, v19
	v_add_f32_dpp v32, v32, v32 quad_perm:[1,0,3,2] row_mask:0xf bank_mask:0xf bound_ctrl:1
	v_add_f32_dpp v33, v33, v33 quad_perm:[1,0,3,2] row_mask:0xf bank_mask:0xf bound_ctrl:1
	v_add_f32_dpp v20, v20, v20 quad_perm:[1,0,3,2] row_mask:0xf bank_mask:0xf bound_ctrl:1
	v_add_f32_dpp v21, v21, v21 quad_perm:[1,0,3,2] row_mask:0xf bank_mask:0xf bound_ctrl:1
	v_add_f32_dpp v32, v32, v32 quad_perm:[2,3,0,1] row_mask:0xf bank_mask:0xf bound_ctrl:1
	v_add_f32_dpp v33, v33, v33 quad_perm:[2,3,0,1] row_mask:0xf bank_mask:0xf bound_ctrl:1
	v_add_f32_dpp v20, v20, v20 quad_perm:[2,3,0,1] row_mask:0xf bank_mask:0xf bound_ctrl:1
	v_add_f32_dpp v21, v21, v21 quad_perm:[2,3,0,1] row_mask:0xf bank_mask:0xf bound_ctrl:1
	v_add_f32_dpp v32, v32, v32 row_half_mirror row_mask:0xf bank_mask:0xf bound_ctrl:1
	v_add_f32_dpp v33, v33, v33 row_half_mirror row_mask:0xf bank_mask:0xf bound_ctrl:1
	v_add_f32_dpp v20, v20, v20 row_half_mirror row_mask:0xf bank_mask:0xf bound_ctrl:1
	v_add_f32_dpp v38, v21, v21 row_half_mirror row_mask:0xf bank_mask:0xf bound_ctrl:1
	ds_write_b64 v64, v[32:33] offset:1280
	v_pk_mul_f32 v[34:35], v[98:99], v[20:21] op_sel_hi:[1,0] neg_lo:[0,1] neg_hi:[0,1]
	v_pk_mul_f32 v[36:37], v[98:99], v[38:39] op_sel_hi:[1,0] neg_lo:[0,1] neg_hi:[0,1]
	v_pk_mul_f32 v[48:49], v[100:101], v[20:21] op_sel_hi:[1,0] neg_lo:[0,1] neg_hi:[0,1]
	v_pk_mul_f32 v[50:51], v[100:101], v[38:39] op_sel_hi:[1,0] neg_lo:[0,1] neg_hi:[0,1]
	v_pk_mul_f32 v[52:53], v[102:103], v[20:21] op_sel_hi:[1,0] neg_lo:[0,1] neg_hi:[0,1]
	v_pk_mul_f32 v[54:55], v[102:103], v[38:39] op_sel_hi:[1,0] neg_lo:[0,1] neg_hi:[0,1]
	v_pk_mul_f32 v[56:57], v[104:105], v[20:21] op_sel_hi:[1,0] neg_lo:[0,1] neg_hi:[0,1]
	v_pk_mul_f32 v[58:59], v[104:105], v[38:39] op_sel_hi:[1,0] neg_lo:[0,1] neg_hi:[0,1]
	v_pk_fma_f32 v[34:35], v[82:83], v[106:107], v[34:35] op_sel_hi:[1,0,1]
	v_pk_fma_f32 v[36:37], v[82:83], v[106:107], v[36:37] op_sel:[0,1,0]
	v_pk_fma_f32 v[48:49], v[84:85], v[106:107], v[48:49] op_sel_hi:[1,0,1]
	v_pk_fma_f32 v[50:51], v[84:85], v[106:107], v[50:51] op_sel:[0,1,0]
	v_pk_fma_f32 v[52:53], v[86:87], v[106:107], v[52:53] op_sel_hi:[1,0,1]
	v_pk_fma_f32 v[54:55], v[86:87], v[106:107], v[54:55] op_sel:[0,1,0]
	v_pk_fma_f32 v[56:57], v[88:89], v[106:107], v[56:57] op_sel_hi:[1,0,1]
	v_pk_fma_f32 v[58:59], v[88:89], v[106:107], v[58:59] op_sel:[0,1,0]
	v_pk_fma_f32 v[24:25], v[74:75], v[24:25], v[34:35]
	v_pk_fma_f32 v[44:45], v[74:75], v[44:45], v[36:37]
	v_pk_fma_f32 v[46:47], v[76:77], v[46:47], v[48:49]
	v_pk_fma_f32 v[42:43], v[76:77], v[42:43], v[50:51]
	v_pk_fma_f32 v[60:61], v[78:79], v[60:61], v[52:53]
	v_pk_fma_f32 v[40:41], v[78:79], v[40:41], v[54:55]
	v_pk_fma_f32 v[28:29], v[80:81], v[28:29], v[56:57]
	v_pk_fma_f32 v[26:27], v[80:81], v[26:27], v[58:59]
	v_pk_fma_f32 v[22:23], v[66:67], v[24:25], 0 op_sel_hi:[1,1,0]
	v_pk_fma_f32 v[30:31], v[66:67], v[44:45], 0 op_sel_hi:[1,1,0]
	v_pk_fma_f32 v[22:23], v[68:69], v[46:47], v[22:23]
	v_pk_fma_f32 v[30:31], v[68:69], v[42:43], v[30:31]
	v_pk_fma_f32 v[22:23], v[70:71], v[60:61], v[22:23]
	v_pk_fma_f32 v[30:31], v[70:71], v[40:41], v[30:31]
	v_pk_fma_f32 v[22:23], v[72:73], v[28:29], v[22:23]
	v_pk_fma_f32 v[30:31], v[72:73], v[26:27], v[30:31]
	v_add_f32_e32 v32, v22, v23
	v_add_f32_e32 v33, v30, v31
	ds_read_b128 v[66:69], v172 offset:2048
	ds_read_b128 v[70:73], v172 offset:2064
	ds_read_b128 v[74:77], v172 offset:6144
	ds_read_b128 v[78:81], v172 offset:6160
	ds_read_b128 v[82:85], v172 offset:10240
	ds_read_b128 v[86:89], v172 offset:10256
	ds_read_b128 v[90:93], v172 offset:18432
	ds_read_b128 v[94:97], v172 offset:18448
	ds_read_b128 v[98:101], v172 offset:22528
	ds_read_b128 v[102:105], v172 offset:22544
	ds_read_b64 v[106:107], v216 offset:2048
	s_waitcnt lgkmcnt(12)
; DEVINL float oct_sum(float v) { v += DPPF(v, 0xB1); v += DPPF(v, 0x4E); v += DPPF(v, 0x141); return v; }
; DEVINL f32x2 rw_step(f32x2 (&S0)[4], f32x2 (&S1)[4], const RwOps& o) {
;     f32x2 a0 = {0.f, 0.f}, a1 = {0.f, 0.f};
; #pragma unroll
;     for (int p = 0; p < 4; ++p) { const f32x2 kk2 = {o.kk[p >> 1][(p & 1) * 2], o.kk[p >> 1][(p & 1) * 2 + 1]}; a0 += S0[p] * kk2; a1 += S1[p] * kk2; }
;     const float sa0 = oct_sum(a0[0] + a0[1]), sa1 = oct_sum(a1[0] + a1[1]);
;     const f32x2 n0 = {-sa0, -sa0}, n1 = {-sa1, -sa1}, v0 = {o.v[0], o.v[0]}, v1 = {o.v[1], o.v[1]};
;     f32x2 y0 = {0.f, 0.f}, y1 = {0.f, 0.f};
; #pragma unroll
;     for (int p = 0; p < 4; ++p) {
;         const int q = p >> 1, e = (p & 1) * 2;
;         const f32x2 k2 = {o.k[q][e], o.k[q][e + 1]}, b2 = {o.b[q][e], o.b[q][e + 1]}, w2 = {o.w[q][e], o.w[q][e + 1]}, r2 = {o.r[q][e], o.r[q][e + 1]};
;         S0[p] = S0[p] * w2 + (v0 * k2 + n0 * b2);
;         S1[p] = S1[p] * w2 + (v1 * k2 + n1 * b2);
;         y0 += S0[p] * r2; y1 += S1[p] * r2;
;     }
;     f32x2 y = {oct_sum(y0[0] + y0[1]), oct_sum(y1[0] + y1[1])};
;     return y;
; }
; DEVINL void rwkv_scan(const Ctx& c, int layer, int b, int hd, const unsigned* cnt3, int nP, float* lds) {
;     ...
;                 for (int tt = 0; tt < TC; ++tt) {
;                     if (tt + 2 < TC) rw_load_ops(ops[(tt + 2) % 3], buf, tt + 2, jo, i0);
;                     const f32x2 y = rw_step(S0, S1, ops[tt % 3]);
;                     *(f32x2*)(syw + tt * 64 + i0) = y;
	v_pk_fma_f32 v[16:17], v[24:25], v[198:199], 0 op_sel_hi:[1,1,0]
	v_pk_fma_f32 v[18:19], v[44:45], v[198:199], 0 op_sel_hi:[1,1,0]
	v_pk_fma_f32 v[16:17], v[46:47], v[200:201], v[16:17]
	v_pk_fma_f32 v[18:19], v[42:43], v[200:201], v[18:19]
	v_pk_fma_f32 v[16:17], v[60:61], v[202:203], v[16:17]
	v_pk_fma_f32 v[18:19], v[40:41], v[202:203], v[18:19]
	v_pk_fma_f32 v[16:17], v[28:29], v[204:205], v[16:17]
	v_pk_fma_f32 v[18:19], v[26:27], v[204:205], v[18:19]
	v_add_f32_e32 v20, v16, v17
	v_add_f32_e32 v21, v18, v19
	v_add_f32_dpp v32, v32, v32 quad_perm:[1,0,3,2] row_mask:0xf bank_mask:0xf bound_ctrl:1
	v_add_f32_dpp v33, v33, v33 quad_perm:[1,0,3,2] row_mask:0xf bank_mask:0xf bound_ctrl:1
	v_add_f32_dpp v20, v20, v20 quad_perm:[1,0,3,2] row_mask:0xf bank_mask:0xf bound_ctrl:1
	v_add_f32_dpp v21, v21, v21 quad_perm:[1,0,3,2] row_mask:0xf bank_mask:0xf bound_ctrl:1
	v_add_f32_dpp v32, v32, v32 quad_perm:[2,3,0,1] row_mask:0xf bank_mask:0xf bound_ctrl:1
	v_add_f32_dpp v33, v33, v33 quad_perm:[2,3,0,1] row_mask:0xf bank_mask:0xf bound_ctrl:1
	v_add_f32_dpp v20, v20, v20 quad_perm:[2,3,0,1] row_mask:0xf bank_mask:0xf bound_ctrl:1
	v_add_f32_dpp v21, v21, v21 quad_perm:[2,3,0,1] row_mask:0xf bank_mask:0xf bound_ctrl:1
	v_add_f32_dpp v32, v32, v32 row_half_mirror row_mask:0xf bank_mask:0xf bound_ctrl:1
	v_add_f32_dpp v33, v33, v33 row_half_mirror row_mask:0xf bank_mask:0xf bound_ctrl:1
	v_add_f32_dpp v20, v20, v20 row_half_mirror row_mask:0xf bank_mask:0xf bound_ctrl:1
	v_add_f32_dpp v38, v21, v21 row_half_mirror row_mask:0xf bank_mask:0xf bound_ctrl:1
	ds_write_b64 v64, v[32:33] offset:1536
	v_pk_mul_f32 v[34:35], v[206:207], v[20:21] op_sel_hi:[1,0] neg_lo:[0,1] neg_hi:[0,1]
	v_pk_mul_f32 v[36:37], v[206:207], v[38:39] op_sel_hi:[1,0] neg_lo:[0,1] neg_hi:[0,1]
	v_pk_mul_f32 v[48:49], v[208:209], v[20:21] op_sel_hi:[1,0] neg_lo:[0,1] neg_hi:[0,1]
	v_pk_mul_f32 v[50:51], v[208:209], v[38:39] op_sel_hi:[1,0] neg_lo:[0,1] neg_hi:[0,1]
	v_pk_mul_f32 v[52:53], v[210:211], v[20:21] op_sel_hi:[1,0] neg_lo:[0,1] neg_hi:[0,1]
	v_pk_mul_f32 v[54:55], v[210:211], v[38:39] op_sel_hi:[1,0] neg_lo:[0,1] neg_hi:[0,1]
	v_pk_mul_f32 v[56:57], v[212:213], v[20:21] op_sel_hi:[1,0] neg_lo:[0,1] neg_hi:[0,1]
	v_pk_mul_f32 v[58:59], v[212:213], v[38:39] op_sel_hi:[1,0] neg_lo:[0,1] neg_hi:[0,1]
	v_pk_fma_f32 v[34:35], v[190:191], v[214:215], v[34:35] op_sel_hi:[1,0,1]
	v_pk_fma_f32 v[36:37], v[190:191], v[214:215], v[36:37] op_sel:[0,1,0]
	v_pk_fma_f32 v[48:49], v[192:193], v[214:215], v[48:49] op_sel_hi:[1,0,1]
	v_pk_fma_f32 v[50:51], v[192:193], v[214:215], v[50:51] op_sel:[0,1,0]
	v_pk_fma_f32 v[52:53], v[194:195], v[214:215], v[52:53] op_sel_hi:[1,0,1]
	v_pk_fma_f32 v[54:55], v[194:195], v[214:215], v[54:55] op_sel:[0,1,0]
	v_pk_fma_f32 v[56:57], v[196:197], v[214:215], v[56:57] op_sel_hi:[1,0,1]
	v_pk_fma_f32 v[58:59], v[196:197], v[214:215], v[58:59] op_sel:[0,1,0]
	v_pk_fma_f32 v[24:25], v[182:183], v[24:25], v[34:35]
	v_pk_fma_f32 v[44:45], v[182:183], v[44:45], v[36:37]
	v_pk_fma_f32 v[46:47], v[184:185], v[46:47], v[48:49]
	v_pk_fma_f32 v[42:43], v[184:185], v[42:43], v[50:51]
	v_pk_fma_f32 v[60:61], v[186:187], v[60:61], v[52:53]
	v_pk_fma_f32 v[40:41], v[186:187], v[40:41], v[54:55]
	v_pk_fma_f32 v[28:29], v[188:189], v[28:29], v[56:57]
	v_pk_fma_f32 v[26:27], v[188:189], v[26:27], v[58:59]
	v_pk_fma_f32 v[22:23], v[174:175], v[24:25], 0 op_sel_hi:[1,1,0]
	v_pk_fma_f32 v[30:31], v[174:175], v[44:45], 0 op_sel_hi:[1,1,0]
	v_pk_fma_f32 v[22:23], v[176:177], v[46:47], v[22:23]
	v_pk_fma_f32 v[30:31], v[176:177], v[42:43], v[30:31]
	v_pk_fma_f32 v[22:23], v[178:179], v[60:61], v[22:23]
	v_pk_fma_f32 v[30:31], v[178:179], v[40:41], v[30:31]
	v_pk_fma_f32 v[22:23], v[180:181], v[28:29], v[22:23]
	v_pk_fma_f32 v[30:31], v[180:181], v[26:27], v[30:31]
	v_add_f32_e32 v32, v22, v23
	v_add_f32_e32 v33, v30, v31
	ds_read_b128 v[174:177], v172 offset:2304
	ds_read_b128 v[178:181], v172 offset:2320
	ds_read_b128 v[182:185], v172 offset:6400
	ds_read_b128 v[186:189], v172 offset:6416
	ds_read_b128 v[190:193], v172 offset:10496
	ds_read_b128 v[194:197], v172 offset:10512
	ds_read_b128 v[198:201], v172 offset:18688
	ds_read_b128 v[202:205], v172 offset:18704
	ds_read_b128 v[206:209], v172 offset:22784
	ds_read_b128 v[210:213], v172 offset:22800
	ds_read_b64 v[214:215], v216 offset:2304
	s_waitcnt lgkmcnt(12)
; DEVINL float oct_sum(float v) { v += DPPF(v, 0xB1); v += DPPF(v, 0x4E); v += DPPF(v, 0x141); return v; }
; DEVINL f32x2 rw_step(f32x2 (&S0)[4], f32x2 (&S1)[4], const RwOps& o) {
;     f32x2 a0 = {0.f, 0.f}, a1 = {0.f, 0.f};
; #pragma unroll
;     for (int p = 0; p < 4; ++p) { const f32x2 kk2 = {o.kk[p >> 1][(p & 1) * 2], o.kk[p >> 1][(p & 1) * 2 + 1]}; a0 += S0[p] * kk2; a1 += S1[p] * kk2; }
;     const float sa0 = oct_sum(a0[0] + a0[1]), sa1 = oct_sum(a1[0] + a1[1]);
;     const f32x2 n0 = {-sa0, -sa0}, n1 = {-sa1, -sa1}, v0 = {o.v[0], o.v[0]}, v1 = {o.v[1], o.v[1]};
;     f32x2 y0 = {0.f, 0.f}, y1 = {0.f, 0.f};
; #pragma unroll
;     for (int p = 0; p < 4; ++p) {
;         const int q = p >> 1, e = (p & 1) * 2;
;         const f32x2 k2 = {o.k[q][e], o.k[q][e + 1]}, b2 = {o.b[q][e], o.b[q][e + 1]}, w2 = {o.w[q][e], o.w[q][e + 1]}, r2 = {o.r[q][e], o.r[q][e + 1]};
;         S0[p] = S0[p] * w2 + (v0 * k2 + n0 * b2);
;         S1[p] = S1[p] * w2 + (v1 * k2 + n1 * b2);
;         y0 += S0[p] * r2; y1 += S1[p] * r2;
;     }
;     f32x2 y = {oct_sum(y0[0] + y0[1]), oct_sum(y1[0] + y1[1])};
;     return y;
; }
; DEVINL void rwkv_scan(const Ctx& c, int layer, int b, int hd, const unsigned* cnt3, int nP, float* lds) {
;     ...
;                 for (int tt = 0; tt < TC; ++tt) {
;                     if (tt + 2 < TC) rw_load_ops(ops[(tt + 2) % 3], buf, tt + 2, jo, i0);
;                     const f32x2 y = rw_step(S0, S1, ops[tt % 3]);
;                     *(f32x2*)(syw + tt * 64 + i0) = y;
	v_pk_fma_f32 v[16:17], v[24:25], v[90:91], 0 op_sel_hi:[1,1,0]
	v_pk_fma_f32 v[18:19], v[44:45], v[90:91], 0 op_sel_hi:[1,1,0]
	v_pk_fma_f32 v[16:17], v[46:47], v[92:93], v[16:17]
	v_pk_fma_f32 v[18:19], v[42:43], v[92:93], v[18:19]
	v_pk_fma_f32 v[16:17], v[60:61], v[94:95], v[16:17]
	v_pk_fma_f32 v[18:19], v[40:41], v[94:95], v[18:19]
	v_pk_fma_f32 v[16:17], v[28:29], v[96:97], v[16:17]
	v_pk_fma_f32 v[18:19], v[26:27], v[96:97], v[18:19]
	v_add_f32_e32 v20, v16, v17
	v_add_f32_e32 v21, v18, v19
	v_add_f32_dpp v32, v32, v32 quad_perm:[1,0,3,2] row_mask:0xf bank_mask:0xf bound_ctrl:1
	v_add_f32_dpp v33, v33, v33 quad_perm:[1,0,3,2] row_mask:0xf bank_mask:0xf bound_ctrl:1
	v_add_f32_dpp v20, v20, v20 quad_perm:[1,0,3,2] row_mask:0xf bank_mask:0xf bound_ctrl:1
	v_add_f32_dpp v21, v21, v21 quad_perm:[1,0,3,2] row_mask:0xf bank_mask:0xf bound_ctrl:1
	v_add_f32_dpp v32, v32, v32 quad_perm:[2,3,0,1] row_mask:0xf bank_mask:0xf bound_ctrl:1
	v_add_f32_dpp v33, v33, v33 quad_perm:[2,3,0,1] row_mask:0xf bank_mask:0xf bound_ctrl:1
	v_add_f32_dpp v20, v20, v20 quad_perm:[2,3,0,1] row_mask:0xf bank_mask:0xf bound_ctrl:1
	v_add_f32_dpp v21, v21, v21 quad_perm:[2,3,0,1] row_mask:0xf bank_mask:0xf bound_ctrl:1
	v_add_f32_dpp v32, v32, v32 row_half_mirror row_mask:0xf bank_mask:0xf bound_ctrl:1
	v_add_f32_dpp v33, v33, v33 row_half_mirror row_mask:0xf bank_mask:0xf bound_ctrl:1
	v_add_f32_dpp v20, v20, v20 row_half_mirror row_mask:0xf bank_mask:0xf bound_ctrl:1
	v_add_f32_dpp v38, v21, v21 row_half_mirror row_mask:0xf bank_mask:0xf bound_ctrl:1
	ds_write_b64 v64, v[32:33] offset:1792
	v_pk_mul_f32 v[34:35], v[98:99], v[20:21] op_sel_hi:[1,0] neg_lo:[0,1] neg_hi:[0,1]
	v_pk_mul_f32 v[36:37], v[98:99], v[38:39] op_sel_hi:[1,0] neg_lo:[0,1] neg_hi:[0,1]
	v_pk_mul_f32 v[48:49], v[100:101], v[20:21] op_sel_hi:[1,0] neg_lo:[0,1] neg_hi:[0,1]
	v_pk_mul_f32 v[50:51], v[100:101], v[38:39] op_sel_hi:[1,0] neg_lo:[0,1] neg_hi:[0,1]
	v_pk_mul_f32 v[52:53], v[102:103], v[20:21] op_sel_hi:[1,0] neg_lo:[0,1] neg_hi:[0,1]
	v_pk_mul_f32 v[54:55], v[102:103], v[38:39] op_sel_hi:[1,0] neg_lo:[0,1] neg_hi:[0,1]
	v_pk_mul_f32 v[56:57], v[104:105], v[20:21] op_sel_hi:[1,0] neg_lo:[0,1] neg_hi:[0,1]
	v_pk_mul_f32 v[58:59], v[104:105], v[38:39] op_sel_hi:[1,0] neg_lo:[0,1] neg_hi:[0,1]
	v_pk_fma_f32 v[34:35], v[82:83], v[106:107], v[34:35] op_sel_hi:[1,0,1]
	v_pk_fma_f32 v[36:37], v[82:83], v[106:107], v[36:37] op_sel:[0,1,0]
	v_pk_fma_f32 v[48:49], v[84:85], v[106:107], v[48:49] op_sel_hi:[1,0,1]
	v_pk_fma_f32 v[50:51], v[84:85], v[106:107], v[50:51] op_sel:[0,1,0]
	v_pk_fma_f32 v[52:53], v[86:87], v[106:107], v[52:53] op_sel_hi:[1,0,1]
	v_pk_fma_f32 v[54:55], v[86:87], v[106:107], v[54:55] op_sel:[0,1,0]
	v_pk_fma_f32 v[56:57], v[88:89], v[106:107], v[56:57] op_sel_hi:[1,0,1]
	v_pk_fma_f32 v[58:59], v[88:89], v[106:107], v[58:59] op_sel:[0,1,0]
	v_pk_fma_f32 v[24:25], v[74:75], v[24:25], v[34:35]
	v_pk_fma_f32 v[44:45], v[74:75], v[44:45], v[36:37]
	v_pk_fma_f32 v[46:47], v[76:77], v[46:47], v[48:49]
	v_pk_fma_f32 v[42:43], v[76:77], v[42:43], v[50:51]
	v_pk_fma_f32 v[60:61], v[78:79], v[60:61], v[52:53]
	v_pk_fma_f32 v[40:41], v[78:79], v[40:41], v[54:55]
	v_pk_fma_f32 v[28:29], v[80:81], v[28:29], v[56:57]
	v_pk_fma_f32 v[26:27], v[80:81], v[26:27], v[58:59]
	v_pk_fma_f32 v[22:23], v[66:67], v[24:25], 0 op_sel_hi:[1,1,0]
	v_pk_fma_f32 v[30:31], v[66:67], v[44:45], 0 op_sel_hi:[1,1,0]
	v_pk_fma_f32 v[22:23], v[68:69], v[46:47], v[22:23]
	v_pk_fma_f32 v[30:31], v[68:69], v[42:43], v[30:31]
	v_pk_fma_f32 v[22:23], v[70:71], v[60:61], v[22:23]
	v_pk_fma_f32 v[30:31], v[70:71], v[40:41], v[30:31]
	v_pk_fma_f32 v[22:23], v[72:73], v[28:29], v[22:23]
	v_pk_fma_f32 v[30:31], v[72:73], v[26:27], v[30:31]
	v_add_f32_e32 v32, v22, v23
	v_add_f32_e32 v33, v30, v31
	ds_read_b128 v[66:69], v172 offset:2560
	ds_read_b128 v[70:73], v172 offset:2576
	ds_read_b128 v[74:77], v172 offset:6656
	ds_read_b128 v[78:81], v172 offset:6672
	ds_read_b128 v[82:85], v172 offset:10752
	ds_read_b128 v[86:89], v172 offset:10768
	ds_read_b128 v[90:93], v172 offset:18944
	ds_read_b128 v[94:97], v172 offset:18960
	ds_read_b128 v[98:101], v172 offset:23040
	ds_read_b128 v[102:105], v172 offset:23056
	ds_read_b64 v[106:107], v216 offset:2560
	s_waitcnt lgkmcnt(12)
; DEVINL float oct_sum(float v) { v += DPPF(v, 0xB1); v += DPPF(v, 0x4E); v += DPPF(v, 0x141); return v; }
; DEVINL f32x2 rw_step(f32x2 (&S0)[4], f32x2 (&S1)[4], const RwOps& o) {
;     f32x2 a0 = {0.f, 0.f}, a1 = {0.f, 0.f};
; #pragma unroll
;     for (int p = 0; p < 4; ++p) { const f32x2 kk2 = {o.kk[p >> 1][(p & 1) * 2], o.kk[p >> 1][(p & 1) * 2 + 1]}; a0 += S0[p] * kk2; a1 += S1[p] * kk2; }
;     const float sa0 = oct_sum(a0[0] + a0[1]), sa1 = oct_sum(a1[0] + a1[1]);
;     const f32x2 n0 = {-sa0, -sa0}, n1 = {-sa1, -sa1}, v0 = {o.v[0], o.v[0]}, v1 = {o.v[1], o.v[1]};
;     f32x2 y0 = {0.f, 0.f}, y1 = {0.f, 0.f};
; #pragma unroll
;     for (int p = 0; p < 4; ++p) {
;         const int q = p >> 1, e = (p & 1) * 2;
;         const f32x2 k2 = {o.k[q][e], o.k[q][e + 1]}, b2 = {o.b[q][e], o.b[q][e + 1]}, w2 = {o.w[q][e], o.w[q][e + 1]}, r2 = {o.r[q][e], o.r[q][e + 1]};
;         S0[p] = S0[p] * w2 + (v0 * k2 + n0 * b2);
;         S1[p] = S1[p] * w2 + (v1 * k2 + n1 * b2);
;         y0 += S0[p] * r2; y1 += S1[p] * r2;
;     }
;     f32x2 y = {oct_sum(y0[0] + y0[1]), oct_sum(y1[0] + y1[1])};
;     return y;
; }
; DEVINL void rwkv_scan(const Ctx& c, int layer, int b, int hd, const unsigned* cnt3, int nP, float* lds) {
;     ...
;                 for (int tt = 0; tt < TC; ++tt) {
;                     if (tt + 2 < TC) rw_load_ops(ops[(tt + 2) % 3], buf, tt + 2, jo, i0);
;                     const f32x2 y = rw_step(S0, S1, ops[tt % 3]);
;                     *(f32x2*)(syw + tt * 64 + i0) = y;
	v_pk_fma_f32 v[16:17], v[24:25], v[198:199], 0 op_sel_hi:[1,1,0]
	v_pk_fma_f32 v[18:19], v[44:45], v[198:199], 0 op_sel_hi:[1,1,0]
	v_pk_fma_f32 v[16:17], v[46:47], v[200:201], v[16:17]
	v_pk_fma_f32 v[18:19], v[42:43], v[200:201], v[18:19]
	v_pk_fma_f32 v[16:17], v[60:61], v[202:203], v[16:17]
	v_pk_fma_f32 v[18:19], v[40:41], v[202:203], v[18:19]
	v_pk_fma_f32 v[16:17], v[28:29], v[204:205], v[16:17]
	v_pk_fma_f32 v[18:19], v[26:27], v[204:205], v[18:19]
	v_add_f32_e32 v20, v16, v17
	v_add_f32_e32 v21, v18, v19
	v_add_f32_dpp v32, v32, v32 quad_perm:[1,0,3,2] row_mask:0xf bank_mask:0xf bound_ctrl:1
	v_add_f32_dpp v33, v33, v33 quad_perm:[1,0,3,2] row_mask:0xf bank_mask:0xf bound_ctrl:1
	v_add_f32_dpp v20, v20, v20 quad_perm:[1,0,3,2] row_mask:0xf bank_mask:0xf bound_ctrl:1
	v_add_f32_dpp v21, v21, v21 quad_perm:[1,0,3,2] row_mask:0xf bank_mask:0xf bound_ctrl:1
	v_add_f32_dpp v32, v32, v32 quad_perm:[2,3,0,1] row_mask:0xf bank_mask:0xf bound_ctrl:1
	v_add_f32_dpp v33, v33, v33 quad_perm:[2,3,0,1] row_mask:0xf bank_mask:0xf bound_ctrl:1
	v_add_f32_dpp v20, v20, v20 quad_perm:[2,3,0,1] row_mask:0xf bank_mask:0xf bound_ctrl:1
	v_add_f32_dpp v21, v21, v21 quad_perm:[2,3,0,1] row_mask:0xf bank_mask:0xf bound_ctrl:1
	v_add_f32_dpp v32, v32, v32 row_half_mirror row_mask:0xf bank_mask:0xf bound_ctrl:1
	v_add_f32_dpp v33, v33, v33 row_half_mirror row_mask:0xf bank_mask:0xf bound_ctrl:1
	v_add_f32_dpp v20, v20, v20 row_half_mirror row_mask:0xf bank_mask:0xf bound_ctrl:1
	v_add_f32_dpp v38, v21, v21 row_half_mirror row_mask:0xf bank_mask:0xf bound_ctrl:1
	ds_write_b64 v64, v[32:33] offset:2048
	v_pk_mul_f32 v[34:35], v[206:207], v[20:21] op_sel_hi:[1,0] neg_lo:[0,1] neg_hi:[0,1]
	v_pk_mul_f32 v[36:37], v[206:207], v[38:39] op_sel_hi:[1,0] neg_lo:[0,1] neg_hi:[0,1]
	v_pk_mul_f32 v[48:49], v[208:209], v[20:21] op_sel_hi:[1,0] neg_lo:[0,1] neg_hi:[0,1]
	v_pk_mul_f32 v[50:51], v[208:209], v[38:39] op_sel_hi:[1,0] neg_lo:[0,1] neg_hi:[0,1]
	v_pk_mul_f32 v[52:53], v[210:211], v[20:21] op_sel_hi:[1,0] neg_lo:[0,1] neg_hi:[0,1]
	v_pk_mul_f32 v[54:55], v[210:211], v[38:39] op_sel_hi:[1,0] neg_lo:[0,1] neg_hi:[0,1]
	v_pk_mul_f32 v[56:57], v[212:213], v[20:21] op_sel_hi:[1,0] neg_lo:[0,1] neg_hi:[0,1]
	v_pk_mul_f32 v[58:59], v[212:213], v[38:39] op_sel_hi:[1,0] neg_lo:[0,1] neg_hi:[0,1]
	v_pk_fma_f32 v[34:35], v[190:191], v[214:215], v[34:35] op_sel_hi:[1,0,1]
	v_pk_fma_f32 v[36:37], v[190:191], v[214:215], v[36:37] op_sel:[0,1,0]
	v_pk_fma_f32 v[48:49], v[192:193], v[214:215], v[48:49] op_sel_hi:[1,0,1]
	v_pk_fma_f32 v[50:51], v[192:193], v[214:215], v[50:51] op_sel:[0,1,0]
	v_pk_fma_f32 v[52:53], v[194:195], v[214:215], v[52:53] op_sel_hi:[1,0,1]
	v_pk_fma_f32 v[54:55], v[194:195], v[214:215], v[54:55] op_sel:[0,1,0]
	v_pk_fma_f32 v[56:57], v[196:197], v[214:215], v[56:57] op_sel_hi:[1,0,1]
	v_pk_fma_f32 v[58:59], v[196:197], v[214:215], v[58:59] op_sel:[0,1,0]
	v_pk_fma_f32 v[24:25], v[182:183], v[24:25], v[34:35]
	v_pk_fma_f32 v[44:45], v[182:183], v[44:45], v[36:37]
	v_pk_fma_f32 v[46:47], v[184:185], v[46:47], v[48:49]
	v_pk_fma_f32 v[42:43], v[184:185], v[42:43], v[50:51]
	v_pk_fma_f32 v[60:61], v[186:187], v[60:61], v[52:53]
	v_pk_fma_f32 v[40:41], v[186:187], v[40:41], v[54:55]
	v_pk_fma_f32 v[28:29], v[188:189], v[28:29], v[56:57]
	v_pk_fma_f32 v[26:27], v[188:189], v[26:27], v[58:59]
	v_pk_fma_f32 v[22:23], v[174:175], v[24:25], 0 op_sel_hi:[1,1,0]
	v_pk_fma_f32 v[30:31], v[174:175], v[44:45], 0 op_sel_hi:[1,1,0]
	v_pk_fma_f32 v[22:23], v[176:177], v[46:47], v[22:23]
	v_pk_fma_f32 v[30:31], v[176:177], v[42:43], v[30:31]
	v_pk_fma_f32 v[22:23], v[178:179], v[60:61], v[22:23]
	v_pk_fma_f32 v[30:31], v[178:179], v[40:41], v[30:31]
	v_pk_fma_f32 v[22:23], v[180:181], v[28:29], v[22:23]
	v_pk_fma_f32 v[30:31], v[180:181], v[26:27], v[30:31]
	v_add_f32_e32 v32, v22, v23
	v_add_f32_e32 v33, v30, v31
	ds_read_b128 v[174:177], v172 offset:2816
	ds_read_b128 v[178:181], v172 offset:2832
	ds_read_b128 v[182:185], v172 offset:6912
	ds_read_b128 v[186:189], v172 offset:6928
	ds_read_b128 v[190:193], v172 offset:11008
	ds_read_b128 v[194:197], v172 offset:11024
	ds_read_b128 v[198:201], v172 offset:19200
	ds_read_b128 v[202:205], v172 offset:19216
	ds_read_b128 v[206:209], v172 offset:23296
	ds_read_b128 v[210:213], v172 offset:23312
	ds_read_b64 v[214:215], v216 offset:2816
	s_waitcnt lgkmcnt(12)
; DEVINL float oct_sum(float v) { v += DPPF(v, 0xB1); v += DPPF(v, 0x4E); v += DPPF(v, 0x141); return v; }
; DEVINL f32x2 rw_step(f32x2 (&S0)[4], f32x2 (&S1)[4], const RwOps& o) {
;     f32x2 a0 = {0.f, 0.f}, a1 = {0.f, 0.f};
; #pragma unroll
;     for (int p = 0; p < 4; ++p) { const f32x2 kk2 = {o.kk[p >> 1][(p & 1) * 2], o.kk[p >> 1][(p & 1) * 2 + 1]}; a0 += S0[p] * kk2; a1 += S1[p] * kk2; }
;     const float sa0 = oct_sum(a0[0] + a0[1]), sa1 = oct_sum(a1[0] + a1[1]);
;     const f32x2 n0 = {-sa0, -sa0}, n1 = {-sa1, -sa1}, v0 = {o.v[0], o.v[0]}, v1 = {o.v[1], o.v[1]};
;     f32x2 y0 = {0.f, 0.f}, y1 = {0.f, 0.f};
; #pragma unroll
;     for (int p = 0; p < 4; ++p) {
;         const int q = p >> 1, e = (p & 1) * 2;
;         const f32x2 k2 = {o.k[q][e], o.k[q][e + 1]}, b2 = {o.b[q][e], o.b[q][e + 1]}, w2 = {o.w[q][e], o.w[q][e + 1]}, r2 = {o.r[q][e], o.r[q][e + 1]};
;         S0[p] = S0[p] * w2 + (v0 * k2 + n0 * b2);
;         S1[p] = S1[p] * w2 + (v1 * k2 + n1 * b2);
;         y0 += S0[p] * r2; y1 += S1[p] * r2;
;     }
;     f32x2 y = {oct_sum(y0[0] + y0[1]), oct_sum(y1[0] + y1[1])};
;     return y;
; }
; DEVINL void rwkv_scan(const Ctx& c, int layer, int b, int hd, const unsigned* cnt3, int nP, float* lds) {
;     ...
;                 for (int tt = 0; tt < TC; ++tt) {
;                     if (tt + 2 < TC) rw_load_ops(ops[(tt + 2) % 3], buf, tt + 2, jo, i0);
;                     const f32x2 y = rw_step(S0, S1, ops[tt % 3]);
;                     *(f32x2*)(syw + tt * 64 + i0) = y;
	v_pk_fma_f32 v[16:17], v[24:25], v[90:91], 0 op_sel_hi:[1,1,0]
	v_pk_fma_f32 v[18:19], v[44:45], v[90:91], 0 op_sel_hi:[1,1,0]
	v_pk_fma_f32 v[16:17], v[46:47], v[92:93], v[16:17]
	v_pk_fma_f32 v[18:19], v[42:43], v[92:93], v[18:19]
	v_pk_fma_f32 v[16:17], v[60:61], v[94:95], v[16:17]
	v_pk_fma_f32 v[18:19], v[40:41], v[94:95], v[18:19]
	v_pk_fma_f32 v[16:17], v[28:29], v[96:97], v[16:17]
	v_pk_fma_f32 v[18:19], v[26:27], v[96:97], v[18:19]
	v_add_f32_e32 v20, v16, v17
	v_add_f32_e32 v21, v18, v19
	v_add_f32_dpp v32, v32, v32 quad_perm:[1,0,3,2] row_mask:0xf bank_mask:0xf bound_ctrl:1
	v_add_f32_dpp v33, v33, v33 quad_perm:[1,0,3,2] row_mask:0xf bank_mask:0xf bound_ctrl:1
	v_add_f32_dpp v20, v20, v20 quad_perm:[1,0,3,2] row_mask:0xf bank_mask:0xf bound_ctrl:1
	v_add_f32_dpp v21, v21, v21 quad_perm:[1,0,3,2] row_mask:0xf bank_mask:0xf bound_ctrl:1
	v_add_f32_dpp v32, v32, v32 quad_perm:[2,3,0,1] row_mask:0xf bank_mask:0xf bound_ctrl:1
	v_add_f32_dpp v33, v33, v33 quad_perm:[2,3,0,1] row_mask:0xf bank_mask:0xf bound_ctrl:1
	v_add_f32_dpp v20, v20, v20 quad_perm:[2,3,0,1] row_mask:0xf bank_mask:0xf bound_ctrl:1
	v_add_f32_dpp v21, v21, v21 quad_perm:[2,3,0,1] row_mask:0xf bank_mask:0xf bound_ctrl:1
	v_add_f32_dpp v32, v32, v32 row_half_mirror row_mask:0xf bank_mask:0xf bound_ctrl:1
	v_add_f32_dpp v33, v33, v33 row_half_mirror row_mask:0xf bank_mask:0xf bound_ctrl:1
	v_add_f32_dpp v20, v20, v20 row_half_mirror row_mask:0xf bank_mask:0xf bound_ctrl:1
	v_add_f32_dpp v38, v21, v21 row_half_mirror row_mask:0xf bank_mask:0xf bound_ctrl:1
	ds_write_b64 v64, v[32:33] offset:2304
	v_pk_mul_f32 v[34:35], v[98:99], v[20:21] op_sel_hi:[1,0] neg_lo:[0,1] neg_hi:[0,1]
	v_pk_mul_f32 v[36:37], v[98:99], v[38:39] op_sel_hi:[1,0] neg_lo:[0,1] neg_hi:[0,1]
	v_pk_mul_f32 v[48:49], v[100:101], v[20:21] op_sel_hi:[1,0] neg_lo:[0,1] neg_hi:[0,1]
	v_pk_mul_f32 v[50:51], v[100:101], v[38:39] op_sel_hi:[1,0] neg_lo:[0,1] neg_hi:[0,1]
	v_pk_mul_f32 v[52:53], v[102:103], v[20:21] op_sel_hi:[1,0] neg_lo:[0,1] neg_hi:[0,1]
	v_pk_mul_f32 v[54:55], v[102:103], v[38:39] op_sel_hi:[1,0] neg_lo:[0,1] neg_hi:[0,1]
	v_pk_mul_f32 v[56:57], v[104:105], v[20:21] op_sel_hi:[1,0] neg_lo:[0,1] neg_hi:[0,1]
	v_pk_mul_f32 v[58:59], v[104:105], v[38:39] op_sel_hi:[1,0] neg_lo:[0,1] neg_hi:[0,1]
	v_pk_fma_f32 v[34:35], v[82:83], v[106:107], v[34:35] op_sel_hi:[1,0,1]
	v_pk_fma_f32 v[36:37], v[82:83], v[106:107], v[36:37] op_sel:[0,1,0]
	v_pk_fma_f32 v[48:49], v[84:85], v[106:107], v[48:49] op_sel_hi:[1,0,1]
	v_pk_fma_f32 v[50:51], v[84:85], v[106:107], v[50:51] op_sel:[0,1,0]
	v_pk_fma_f32 v[52:53], v[86:87], v[106:107], v[52:53] op_sel_hi:[1,0,1]
	v_pk_fma_f32 v[54:55], v[86:87], v[106:107], v[54:55] op_sel:[0,1,0]
	v_pk_fma_f32 v[56:57], v[88:89], v[106:107], v[56:57] op_sel_hi:[1,0,1]
	v_pk_fma_f32 v[58:59], v[88:89], v[106:107], v[58:59] op_sel:[0,1,0]
	v_pk_fma_f32 v[24:25], v[74:75], v[24:25], v[34:35]
	v_pk_fma_f32 v[44:45], v[74:75], v[44:45], v[36:37]
	v_pk_fma_f32 v[46:47], v[76:77], v[46:47], v[48:49]
	v_pk_fma_f32 v[42:43], v[76:77], v[42:43], v[50:51]
	v_pk_fma_f32 v[60:61], v[78:79], v[60:61], v[52:53]
	v_pk_fma_f32 v[40:41], v[78:79], v[40:41], v[54:55]
	v_pk_fma_f32 v[28:29], v[80:81], v[28:29], v[56:57]
	v_pk_fma_f32 v[26:27], v[80:81], v[26:27], v[58:59]
	v_pk_fma_f32 v[22:23], v[66:67], v[24:25], 0 op_sel_hi:[1,1,0]
	v_pk_fma_f32 v[30:31], v[66:67], v[44:45], 0 op_sel_hi:[1,1,0]
	v_pk_fma_f32 v[22:23], v[68:69], v[46:47], v[22:23]
	v_pk_fma_f32 v[30:31], v[68:69], v[42:43], v[30:31]
	v_pk_fma_f32 v[22:23], v[70:71], v[60:61], v[22:23]
	v_pk_fma_f32 v[30:31], v[70:71], v[40:41], v[30:31]
	v_pk_fma_f32 v[22:23], v[72:73], v[28:29], v[22:23]
	v_pk_fma_f32 v[30:31], v[72:73], v[26:27], v[30:31]
	v_add_f32_e32 v32, v22, v23
	v_add_f32_e32 v33, v30, v31
	ds_read_b128 v[66:69], v172 offset:3072
	ds_read_b128 v[70:73], v172 offset:3088
	ds_read_b128 v[74:77], v172 offset:7168
	ds_read_b128 v[78:81], v172 offset:7184
	ds_read_b128 v[82:85], v172 offset:11264
	ds_read_b128 v[86:89], v172 offset:11280
	ds_read_b128 v[90:93], v172 offset:19456
	ds_read_b128 v[94:97], v172 offset:19472
	ds_read_b128 v[98:101], v172 offset:23552
	ds_read_b128 v[102:105], v172 offset:23568
	ds_read_b64 v[106:107], v216 offset:3072
	s_waitcnt lgkmcnt(12)
; DEVINL float oct_sum(float v) { v += DPPF(v, 0xB1); v += DPPF(v, 0x4E); v += DPPF(v, 0x141); return v; }
; DEVINL f32x2 rw_step(f32x2 (&S0)[4], f32x2 (&S1)[4], const RwOps& o) {
;     f32x2 a0 = {0.f, 0.f}, a1 = {0.f, 0.f};
; #pragma unroll
;     for (int p = 0; p < 4; ++p) { const f32x2 kk2 = {o.kk[p >> 1][(p & 1) * 2], o.kk[p >> 1][(p & 1) * 2 + 1]}; a0 += S0[p] * kk2; a1 += S1[p] * kk2; }
;     const float sa0 = oct_sum(a0[0] + a0[1]), sa1 = oct_sum(a1[0] + a1[1]);
;     const f32x2 n0 = {-sa0, -sa0}, n1 = {-sa1, -sa1}, v0 = {o.v[0], o.v[0]}, v1 = {o.v[1], o.v[1]};
;     f32x2 y0 = {0.f, 0.f}, y1 = {0.f, 0.f};
; #pragma unroll
;     for (int p = 0; p < 4; ++p) {
;         const int q = p >> 1, e = (p & 1) * 2;
;         const f32x2 k2 = {o.k[q][e], o.k[q][e + 1]}, b2 = {o.b[q][e], o.b[q][e + 1]}, w2 = {o.w[q][e], o.w[q][e + 1]}, r2 = {o.r[q][e], o.r[q][e + 1]};
;         S0[p] = S0[p] * w2 + (v0 * k2 + n0 * b2);
;         S1[p] = S1[p] * w2 + (v1 * k2 + n1 * b2);
;         y0 += S0[p] * r2; y1 += S1[p] * r2;
;     }
;     f32x2 y = {oct_sum(y0[0] + y0[1]), oct_sum(y1[0] + y1[1])};
;     return y;
; }
; DEVINL void rwkv_scan(const Ctx& c, int layer, int b, int hd, const unsigned* cnt3, int nP, float* lds) {
;     ...
;                 for (int tt = 0; tt < TC; ++tt) {
;                     if (tt + 2 < TC) rw_load_ops(ops[(tt + 2) % 3], buf, tt + 2, jo, i0);
;                     const f32x2 y = rw_step(S0, S1, ops[tt % 3]);
;                     *(f32x2*)(syw + tt * 64 + i0) = y;
	v_pk_fma_f32 v[16:17], v[24:25], v[198:199], 0 op_sel_hi:[1,1,0]
	v_pk_fma_f32 v[18:19], v[44:45], v[198:199], 0 op_sel_hi:[1,1,0]
	v_pk_fma_f32 v[16:17], v[46:47], v[200:201], v[16:17]
	v_pk_fma_f32 v[18:19], v[42:43], v[200:201], v[18:19]
	v_pk_fma_f32 v[16:17], v[60:61], v[202:203], v[16:17]
	v_pk_fma_f32 v[18:19], v[40:41], v[202:203], v[18:19]
	v_pk_fma_f32 v[16:17], v[28:29], v[204:205], v[16:17]
	v_pk_fma_f32 v[18:19], v[26:27], v[204:205], v[18:19]
	v_add_f32_e32 v20, v16, v17
	v_add_f32_e32 v21, v18, v19
	v_add_f32_dpp v32, v32, v32 quad_perm:[1,0,3,2] row_mask:0xf bank_mask:0xf bound_ctrl:1
	v_add_f32_dpp v33, v33, v33 quad_perm:[1,0,3,2] row_mask:0xf bank_mask:0xf bound_ctrl:1
	v_add_f32_dpp v20, v20, v20 quad_perm:[1,0,3,2] row_mask:0xf bank_mask:0xf bound_ctrl:1
	v_add_f32_dpp v21, v21, v21 quad_perm:[1,0,3,2] row_mask:0xf bank_mask:0xf bound_ctrl:1
	v_add_f32_dpp v32, v32, v32 quad_perm:[2,3,0,1] row_mask:0xf bank_mask:0xf bound_ctrl:1
	v_add_f32_dpp v33, v33, v33 quad_perm:[2,3,0,1] row_mask:0xf bank_mask:0xf bound_ctrl:1
	v_add_f32_dpp v20, v20, v20 quad_perm:[2,3,0,1] row_mask:0xf bank_mask:0xf bound_ctrl:1
	v_add_f32_dpp v21, v21, v21 quad_perm:[2,3,0,1] row_mask:0xf bank_mask:0xf bound_ctrl:1
	v_add_f32_dpp v32, v32, v32 row_half_mirror row_mask:0xf bank_mask:0xf bound_ctrl:1
	v_add_f32_dpp v33, v33, v33 row_half_mirror row_mask:0xf bank_mask:0xf bound_ctrl:1
	v_add_f32_dpp v20, v20, v20 row_half_mirror row_mask:0xf bank_mask:0xf bound_ctrl:1
	v_add_f32_dpp v38, v21, v21 row_half_mirror row_mask:0xf bank_mask:0xf bound_ctrl:1
	ds_write_b64 v64, v[32:33] offset:2560
	v_pk_mul_f32 v[34:35], v[206:207], v[20:21] op_sel_hi:[1,0] neg_lo:[0,1] neg_hi:[0,1]
	v_pk_mul_f32 v[36:37], v[206:207], v[38:39] op_sel_hi:[1,0] neg_lo:[0,1] neg_hi:[0,1]
	v_pk_mul_f32 v[48:49], v[208:209], v[20:21] op_sel_hi:[1,0] neg_lo:[0,1] neg_hi:[0,1]
	v_pk_mul_f32 v[50:51], v[208:209], v[38:39] op_sel_hi:[1,0] neg_lo:[0,1] neg_hi:[0,1]
	v_pk_mul_f32 v[52:53], v[210:211], v[20:21] op_sel_hi:[1,0] neg_lo:[0,1] neg_hi:[0,1]
	v_pk_mul_f32 v[54:55], v[210:211], v[38:39] op_sel_hi:[1,0] neg_lo:[0,1] neg_hi:[0,1]
	v_pk_mul_f32 v[56:57], v[212:213], v[20:21] op_sel_hi:[1,0] neg_lo:[0,1] neg_hi:[0,1]
	v_pk_mul_f32 v[58:59], v[212:213], v[38:39] op_sel_hi:[1,0] neg_lo:[0,1] neg_hi:[0,1]
	v_pk_fma_f32 v[34:35], v[190:191], v[214:215], v[34:35] op_sel_hi:[1,0,1]
	v_pk_fma_f32 v[36:37], v[190:191], v[214:215], v[36:37] op_sel:[0,1,0]
	v_pk_fma_f32 v[48:49], v[192:193], v[214:215], v[48:49] op_sel_hi:[1,0,1]
	v_pk_fma_f32 v[50:51], v[192:193], v[214:215], v[50:51] op_sel:[0,1,0]
	v_pk_fma_f32 v[52:53], v[194:195], v[214:215], v[52:53] op_sel_hi:[1,0,1]
	v_pk_fma_f32 v[54:55], v[194:195], v[214:215], v[54:55] op_sel:[0,1,0]
	v_pk_fma_f32 v[56:57], v[196:197], v[214:215], v[56:57] op_sel_hi:[1,0,1]
	v_pk_fma_f32 v[58:59], v[196:197], v[214:215], v[58:59] op_sel:[0,1,0]
	v_pk_fma_f32 v[24:25], v[182:183], v[24:25], v[34:35]
	v_pk_fma_f32 v[44:45], v[182:183], v[44:45], v[36:37]
	v_pk_fma_f32 v[46:47], v[184:185], v[46:47], v[48:49]
	v_pk_fma_f32 v[42:43], v[184:185], v[42:43], v[50:51]
	v_pk_fma_f32 v[60:61], v[186:187], v[60:61], v[52:53]
	v_pk_fma_f32 v[40:41], v[186:187], v[40:41], v[54:55]
	v_pk_fma_f32 v[28:29], v[188:189], v[28:29], v[56:57]
	v_pk_fma_f32 v[26:27], v[188:189], v[26:27], v[58:59]
	v_pk_fma_f32 v[22:23], v[174:175], v[24:25], 0 op_sel_hi:[1,1,0]
	v_pk_fma_f32 v[30:31], v[174:175], v[44:45], 0 op_sel_hi:[1,1,0]
	v_pk_fma_f32 v[22:23], v[176:177], v[46:47], v[22:23]
	v_pk_fma_f32 v[30:31], v[176:177], v[42:43], v[30:31]
	v_pk_fma_f32 v[22:23], v[178:179], v[60:61], v[22:23]
	v_pk_fma_f32 v[30:31], v[178:179], v[40:41], v[30:31]
	v_pk_fma_f32 v[22:23], v[180:181], v[28:29], v[22:23]
	v_pk_fma_f32 v[30:31], v[180:181], v[26:27], v[30:31]
	v_add_f32_e32 v32, v22, v23
	v_add_f32_e32 v33, v30, v31
	ds_read_b128 v[174:177], v172 offset:3328
	ds_read_b128 v[178:181], v172 offset:3344
	ds_read_b128 v[182:185], v172 offset:7424
	ds_read_b128 v[186:189], v172 offset:7440
	ds_read_b128 v[190:193], v172 offset:11520
	ds_read_b128 v[194:197], v172 offset:11536
	ds_read_b128 v[198:201], v172 offset:19712
	ds_read_b128 v[202:205], v172 offset:19728
	ds_read_b128 v[206:209], v172 offset:23808
	ds_read_b128 v[210:213], v172 offset:23824
	ds_read_b64 v[214:215], v216 offset:3328
	s_waitcnt lgkmcnt(12)
; DEVINL float oct_sum(float v) { v += DPPF(v, 0xB1); v += DPPF(v, 0x4E); v += DPPF(v, 0x141); return v; }
; DEVINL f32x2 rw_step(f32x2 (&S0)[4], f32x2 (&S1)[4], const RwOps& o) {
;     f32x2 a0 = {0.f, 0.f}, a1 = {0.f, 0.f};
; #pragma unroll
;     for (int p = 0; p < 4; ++p) { const f32x2 kk2 = {o.kk[p >> 1][(p & 1) * 2], o.kk[p >> 1][(p & 1) * 2 + 1]}; a0 += S0[p] * kk2; a1 += S1[p] * kk2; }
;     const float sa0 = oct_sum(a0[0] + a0[1]), sa1 = oct_sum(a1[0] + a1[1]);
;     const f32x2 n0 = {-sa0, -sa0}, n1 = {-sa1, -sa1}, v0 = {o.v[0], o.v[0]}, v1 = {o.v[1], o.v[1]};
;     f32x2 y0 = {0.f, 0.f}, y1 = {0.f, 0.f};
; #pragma unroll
;     for (int p = 0; p < 4; ++p) {
;         const int q = p >> 1, e = (p & 1) * 2;
;         const f32x2 k2 = {o.k[q][e], o.k[q][e + 1]}, b2 = {o.b[q][e], o.b[q][e + 1]}, w2 = {o.w[q][e], o.w[q][e + 1]}, r2 = {o.r[q][e], o.r[q][e + 1]};
;         S0[p] = S0[p] * w2 + (v0 * k2 + n0 * b2);
;         S1[p] = S1[p] * w2 + (v1 * k2 + n1 * b2);
;         y0 += S0[p] * r2; y1 += S1[p] * r2;
;     }
;     f32x2 y = {oct_sum(y0[0] + y0[1]), oct_sum(y1[0] + y1[1])};
;     return y;
; }
; DEVINL void rwkv_scan(const Ctx& c, int layer, int b, int hd, const unsigned* cnt3, int nP, float* lds) {
;     ...
;                 for (int tt = 0; tt < TC; ++tt) {
;                     if (tt + 2 < TC) rw_load_ops(ops[(tt + 2) % 3], buf, tt + 2, jo, i0);
;                     const f32x2 y = rw_step(S0, S1, ops[tt % 3]);
;                     *(f32x2*)(syw + tt * 64 + i0) = y;
	v_pk_fma_f32 v[16:17], v[24:25], v[90:91], 0 op_sel_hi:[1,1,0]
	v_pk_fma_f32 v[18:19], v[44:45], v[90:91], 0 op_sel_hi:[1,1,0]
	v_pk_fma_f32 v[16:17], v[46:47], v[92:93], v[16:17]
	v_pk_fma_f32 v[18:19], v[42:43], v[92:93], v[18:19]
	v_pk_fma_f32 v[16:17], v[60:61], v[94:95], v[16:17]
	v_pk_fma_f32 v[18:19], v[40:41], v[94:95], v[18:19]
	v_pk_fma_f32 v[16:17], v[28:29], v[96:97], v[16:17]
	v_pk_fma_f32 v[18:19], v[26:27], v[96:97], v[18:19]
	v_add_f32_e32 v20, v16, v17
	v_add_f32_e32 v21, v18, v19
	v_add_f32_dpp v32, v32, v32 quad_perm:[1,0,3,2] row_mask:0xf bank_mask:0xf bound_ctrl:1
	v_add_f32_dpp v33, v33, v33 quad_perm:[1,0,3,2] row_mask:0xf bank_mask:0xf bound_ctrl:1
	v_add_f32_dpp v20, v20, v20 quad_perm:[1,0,3,2] row_mask:0xf bank_mask:0xf bound_ctrl:1
	v_add_f32_dpp v21, v21, v21 quad_perm:[1,0,3,2] row_mask:0xf bank_mask:0xf bound_ctrl:1
	v_add_f32_dpp v32, v32, v32 quad_perm:[2,3,0,1] row_mask:0xf bank_mask:0xf bound_ctrl:1
	v_add_f32_dpp v33, v33, v33 quad_perm:[2,3,0,1] row_mask:0xf bank_mask:0xf bound_ctrl:1
	v_add_f32_dpp v20, v20, v20 quad_perm:[2,3,0,1] row_mask:0xf bank_mask:0xf bound_ctrl:1
	v_add_f32_dpp v21, v21, v21 quad_perm:[2,3,0,1] row_mask:0xf bank_mask:0xf bound_ctrl:1
	v_add_f32_dpp v32, v32, v32 row_half_mirror row_mask:0xf bank_mask:0xf bound_ctrl:1
	v_add_f32_dpp v33, v33, v33 row_half_mirror row_mask:0xf bank_mask:0xf bound_ctrl:1
	v_add_f32_dpp v20, v20, v20 row_half_mirror row_mask:0xf bank_mask:0xf bound_ctrl:1
	v_add_f32_dpp v38, v21, v21 row_half_mirror row_mask:0xf bank_mask:0xf bound_ctrl:1
	ds_write_b64 v64, v[32:33] offset:2816
	v_pk_mul_f32 v[34:35], v[98:99], v[20:21] op_sel_hi:[1,0] neg_lo:[0,1] neg_hi:[0,1]
	v_pk_mul_f32 v[36:37], v[98:99], v[38:39] op_sel_hi:[1,0] neg_lo:[0,1] neg_hi:[0,1]
	v_pk_mul_f32 v[48:49], v[100:101], v[20:21] op_sel_hi:[1,0] neg_lo:[0,1] neg_hi:[0,1]
	v_pk_mul_f32 v[50:51], v[100:101], v[38:39] op_sel_hi:[1,0] neg_lo:[0,1] neg_hi:[0,1]
	v_pk_mul_f32 v[52:53], v[102:103], v[20:21] op_sel_hi:[1,0] neg_lo:[0,1] neg_hi:[0,1]
	v_pk_mul_f32 v[54:55], v[102:103], v[38:39] op_sel_hi:[1,0] neg_lo:[0,1] neg_hi:[0,1]
	v_pk_mul_f32 v[56:57], v[104:105], v[20:21] op_sel_hi:[1,0] neg_lo:[0,1] neg_hi:[0,1]
	v_pk_mul_f32 v[58:59], v[104:105], v[38:39] op_sel_hi:[1,0] neg_lo:[0,1] neg_hi:[0,1]
	v_pk_fma_f32 v[34:35], v[82:83], v[106:107], v[34:35] op_sel_hi:[1,0,1]
	v_pk_fma_f32 v[36:37], v[82:83], v[106:107], v[36:37] op_sel:[0,1,0]
	v_pk_fma_f32 v[48:49], v[84:85], v[106:107], v[48:49] op_sel_hi:[1,0,1]
	v_pk_fma_f32 v[50:51], v[84:85], v[106:107], v[50:51] op_sel:[0,1,0]
	v_pk_fma_f32 v[52:53], v[86:87], v[106:107], v[52:53] op_sel_hi:[1,0,1]
	v_pk_fma_f32 v[54:55], v[86:87], v[106:107], v[54:55] op_sel:[0,1,0]
	v_pk_fma_f32 v[56:57], v[88:89], v[106:107], v[56:57] op_sel_hi:[1,0,1]
	v_pk_fma_f32 v[58:59], v[88:89], v[106:107], v[58:59] op_sel:[0,1,0]
	v_pk_fma_f32 v[24:25], v[74:75], v[24:25], v[34:35]
	v_pk_fma_f32 v[44:45], v[74:75], v[44:45], v[36:37]
	v_pk_fma_f32 v[46:47], v[76:77], v[46:47], v[48:49]
	v_pk_fma_f32 v[42:43], v[76:77], v[42:43], v[50:51]
	v_pk_fma_f32 v[60:61], v[78:79], v[60:61], v[52:53]
	v_pk_fma_f32 v[40:41], v[78:79], v[40:41], v[54:55]
	v_pk_fma_f32 v[28:29], v[80:81], v[28:29], v[56:57]
	v_pk_fma_f32 v[26:27], v[80:81], v[26:27], v[58:59]
	v_pk_fma_f32 v[22:23], v[66:67], v[24:25], 0 op_sel_hi:[1,1,0]
	v_pk_fma_f32 v[30:31], v[66:67], v[44:45], 0 op_sel_hi:[1,1,0]
	v_pk_fma_f32 v[22:23], v[68:69], v[46:47], v[22:23]
	v_pk_fma_f32 v[30:31], v[68:69], v[42:43], v[30:31]
	v_pk_fma_f32 v[22:23], v[70:71], v[60:61], v[22:23]
	v_pk_fma_f32 v[30:31], v[70:71], v[40:41], v[30:31]
	v_pk_fma_f32 v[22:23], v[72:73], v[28:29], v[22:23]
	v_pk_fma_f32 v[30:31], v[72:73], v[26:27], v[30:31]
	v_add_f32_e32 v32, v22, v23
	v_add_f32_e32 v33, v30, v31
	ds_read_b128 v[66:69], v172 offset:3584
	ds_read_b128 v[70:73], v172 offset:3600
	ds_read_b128 v[74:77], v172 offset:7680
	ds_read_b128 v[78:81], v172 offset:7696
	ds_read_b128 v[82:85], v172 offset:11776
	ds_read_b128 v[86:89], v172 offset:11792
	ds_read_b128 v[90:93], v172 offset:19968
	ds_read_b128 v[94:97], v172 offset:19984
	ds_read_b128 v[98:101], v172 offset:24064
	ds_read_b128 v[102:105], v172 offset:24080
	ds_read_b64 v[106:107], v216 offset:3584
	s_waitcnt lgkmcnt(12)
; DEVINL float oct_sum(float v) { v += DPPF(v, 0xB1); v += DPPF(v, 0x4E); v += DPPF(v, 0x141); return v; }
; DEVINL f32x2 rw_step(f32x2 (&S0)[4], f32x2 (&S1)[4], const RwOps& o) {
;     f32x2 a0 = {0.f, 0.f}, a1 = {0.f, 0.f};
; #pragma unroll
;     for (int p = 0; p < 4; ++p) { const f32x2 kk2 = {o.kk[p >> 1][(p & 1) * 2], o.kk[p >> 1][(p & 1) * 2 + 1]}; a0 += S0[p] * kk2; a1 += S1[p] * kk2; }
;     const float sa0 = oct_sum(a0[0] + a0[1]), sa1 = oct_sum(a1[0] + a1[1]);
;     const f32x2 n0 = {-sa0, -sa0}, n1 = {-sa1, -sa1}, v0 = {o.v[0], o.v[0]}, v1 = {o.v[1], o.v[1]};
;     f32x2 y0 = {0.f, 0.f}, y1 = {0.f, 0.f};
; #pragma unroll
;     for (int p = 0; p < 4; ++p) {
;         const int q = p >> 1, e = (p & 1) * 2;
;         const f32x2 k2 = {o.k[q][e], o.k[q][e + 1]}, b2 = {o.b[q][e], o.b[q][e + 1]}, w2 = {o.w[q][e], o.w[q][e + 1]}, r2 = {o.r[q][e], o.r[q][e + 1]};
;         S0[p] = S0[p] * w2 + (v0 * k2 + n0 * b2);
;         S1[p] = S1[p] * w2 + (v1 * k2 + n1 * b2);
;         y0 += S0[p] * r2; y1 += S1[p] * r2;
;     }
;     f32x2 y = {oct_sum(y0[0] + y0[1]), oct_sum(y1[0] + y1[1])};
;     return y;
; }
; DEVINL void rwkv_scan(const Ctx& c, int layer, int b, int hd, const unsigned* cnt3, int nP, float* lds) {
;     ...
;                 for (int tt = 0; tt < TC; ++tt) {
;                     if (tt + 2 < TC) rw_load_ops(ops[(tt + 2) % 3], buf, tt + 2, jo, i0);
;                     const f32x2 y = rw_step(S0, S1, ops[tt % 3]);
;                     *(f32x2*)(syw + tt * 64 + i0) = y;
	v_pk_fma_f32 v[16:17], v[24:25], v[198:199], 0 op_sel_hi:[1,1,0]
	v_pk_fma_f32 v[18:19], v[44:45], v[198:199], 0 op_sel_hi:[1,1,0]
	v_pk_fma_f32 v[16:17], v[46:47], v[200:201], v[16:17]
	v_pk_fma_f32 v[18:19], v[42:43], v[200:201], v[18:19]
	v_pk_fma_f32 v[16:17], v[60:61], v[202:203], v[16:17]
	v_pk_fma_f32 v[18:19], v[40:41], v[202:203], v[18:19]
	v_pk_fma_f32 v[16:17], v[28:29], v[204:205], v[16:17]
	v_pk_fma_f32 v[18:19], v[26:27], v[204:205], v[18:19]
	v_add_f32_e32 v20, v16, v17
	v_add_f32_e32 v21, v18, v19
	v_add_f32_dpp v32, v32, v32 quad_perm:[1,0,3,2] row_mask:0xf bank_mask:0xf bound_ctrl:1
	v_add_f32_dpp v33, v33, v33 quad_perm:[1,0,3,2] row_mask:0xf bank_mask:0xf bound_ctrl:1
	v_add_f32_dpp v20, v20, v20 quad_perm:[1,0,3,2] row_mask:0xf bank_mask:0xf bound_ctrl:1
	v_add_f32_dpp v21, v21, v21 quad_perm:[1,0,3,2] row_mask:0xf bank_mask:0xf bound_ctrl:1
	v_add_f32_dpp v32, v32, v32 quad_perm:[2,3,0,1] row_mask:0xf bank_mask:0xf bound_ctrl:1
	v_add_f32_dpp v33, v33, v33 quad_perm:[2,3,0,1] row_mask:0xf bank_mask:0xf bound_ctrl:1
	v_add_f32_dpp v20, v20, v20 quad_perm:[2,3,0,1] row_mask:0xf bank_mask:0xf bound_ctrl:1
	v_add_f32_dpp v21, v21, v21 quad_perm:[2,3,0,1] row_mask:0xf bank_mask:0xf bound_ctrl:1
	v_add_f32_dpp v32, v32, v32 row_half_mirror row_mask:0xf bank_mask:0xf bound_ctrl:1
	v_add_f32_dpp v33, v33, v33 row_half_mirror row_mask:0xf bank_mask:0xf bound_ctrl:1
	v_add_f32_dpp v20, v20, v20 row_half_mirror row_mask:0xf bank_mask:0xf bound_ctrl:1
	v_add_f32_dpp v38, v21, v21 row_half_mirror row_mask:0xf bank_mask:0xf bound_ctrl:1
	ds_write_b64 v64, v[32:33] offset:3072
	v_pk_mul_f32 v[34:35], v[206:207], v[20:21] op_sel_hi:[1,0] neg_lo:[0,1] neg_hi:[0,1]
	v_pk_mul_f32 v[36:37], v[206:207], v[38:39] op_sel_hi:[1,0] neg_lo:[0,1] neg_hi:[0,1]
	v_pk_mul_f32 v[48:49], v[208:209], v[20:21] op_sel_hi:[1,0] neg_lo:[0,1] neg_hi:[0,1]
	v_pk_mul_f32 v[50:51], v[208:209], v[38:39] op_sel_hi:[1,0] neg_lo:[0,1] neg_hi:[0,1]
	v_pk_mul_f32 v[52:53], v[210:211], v[20:21] op_sel_hi:[1,0] neg_lo:[0,1] neg_hi:[0,1]
	v_pk_mul_f32 v[54:55], v[210:211], v[38:39] op_sel_hi:[1,0] neg_lo:[0,1] neg_hi:[0,1]
	v_pk_mul_f32 v[56:57], v[212:213], v[20:21] op_sel_hi:[1,0] neg_lo:[0,1] neg_hi:[0,1]
	v_pk_mul_f32 v[58:59], v[212:213], v[38:39] op_sel_hi:[1,0] neg_lo:[0,1] neg_hi:[0,1]
	v_pk_fma_f32 v[34:35], v[190:191], v[214:215], v[34:35] op_sel_hi:[1,0,1]
	v_pk_fma_f32 v[36:37], v[190:191], v[214:215], v[36:37] op_sel:[0,1,0]
	v_pk_fma_f32 v[48:49], v[192:193], v[214:215], v[48:49] op_sel_hi:[1,0,1]
	v_pk_fma_f32 v[50:51], v[192:193], v[214:215], v[50:51] op_sel:[0,1,0]
	v_pk_fma_f32 v[52:53], v[194:195], v[214:215], v[52:53] op_sel_hi:[1,0,1]
	v_pk_fma_f32 v[54:55], v[194:195], v[214:215], v[54:55] op_sel:[0,1,0]
	v_pk_fma_f32 v[56:57], v[196:197], v[214:215], v[56:57] op_sel_hi:[1,0,1]
	v_pk_fma_f32 v[58:59], v[196:197], v[214:215], v[58:59] op_sel:[0,1,0]
	v_pk_fma_f32 v[24:25], v[182:183], v[24:25], v[34:35]
	v_pk_fma_f32 v[44:45], v[182:183], v[44:45], v[36:37]
	v_pk_fma_f32 v[46:47], v[184:185], v[46:47], v[48:49]
	v_pk_fma_f32 v[42:43], v[184:185], v[42:43], v[50:51]
	v_pk_fma_f32 v[60:61], v[186:187], v[60:61], v[52:53]
	v_pk_fma_f32 v[40:41], v[186:187], v[40:41], v[54:55]
	v_pk_fma_f32 v[28:29], v[188:189], v[28:29], v[56:57]
	v_pk_fma_f32 v[26:27], v[188:189], v[26:27], v[58:59]
	v_pk_fma_f32 v[22:23], v[174:175], v[24:25], 0 op_sel_hi:[1,1,0]
	v_pk_fma_f32 v[30:31], v[174:175], v[44:45], 0 op_sel_hi:[1,1,0]
	v_pk_fma_f32 v[22:23], v[176:177], v[46:47], v[22:23]
	v_pk_fma_f32 v[30:31], v[176:177], v[42:43], v[30:31]
	v_pk_fma_f32 v[22:23], v[178:179], v[60:61], v[22:23]
	v_pk_fma_f32 v[30:31], v[178:179], v[40:41], v[30:31]
	v_pk_fma_f32 v[22:23], v[180:181], v[28:29], v[22:23]
	v_pk_fma_f32 v[30:31], v[180:181], v[26:27], v[30:31]
	v_add_f32_e32 v32, v22, v23
	v_add_f32_e32 v33, v30, v31
	ds_read_b128 v[174:177], v172 offset:3840
	ds_read_b128 v[178:181], v172 offset:3856
	ds_read_b128 v[182:185], v172 offset:7936
	ds_read_b128 v[186:189], v172 offset:7952
	ds_read_b128 v[190:193], v172 offset:12032
	ds_read_b128 v[194:197], v172 offset:12048
	ds_read_b128 v[198:201], v172 offset:20224
	ds_read_b128 v[202:205], v172 offset:20240
	ds_read_b128 v[206:209], v172 offset:24320
	ds_read_b128 v[210:213], v172 offset:24336
	ds_read_b64 v[214:215], v216 offset:3840
	s_waitcnt lgkmcnt(12)
; DEVINL float oct_sum(float v) { v += DPPF(v, 0xB1); v += DPPF(v, 0x4E); v += DPPF(v, 0x141); return v; }
; DEVINL f32x2 rw_step(f32x2 (&S0)[4], f32x2 (&S1)[4], const RwOps& o) {
;     f32x2 a0 = {0.f, 0.f}, a1 = {0.f, 0.f};
; #pragma unroll
;     for (int p = 0; p < 4; ++p) { const f32x2 kk2 = {o.kk[p >> 1][(p & 1) * 2], o.kk[p >> 1][(p & 1) * 2 + 1]}; a0 += S0[p] * kk2; a1 += S1[p] * kk2; }
;     const float sa0 = oct_sum(a0[0] + a0[1]), sa1 = oct_sum(a1[0] + a1[1]);
;     const f32x2 n0 = {-sa0, -sa0}, n1 = {-sa1, -sa1}, v0 = {o.v[0], o.v[0]}, v1 = {o.v[1], o.v[1]};
;     f32x2 y0 = {0.f, 0.f}, y1 = {0.f, 0.f};
; #pragma unroll
;     for (int p = 0; p < 4; ++p) {
;         const int q = p >> 1, e = (p & 1) * 2;
;         const f32x2 k2 = {o.k[q][e], o.k[q][e + 1]}, b2 = {o.b[q][e], o.b[q][e + 1]}, w2 = {o.w[q][e], o.w[q][e + 1]}, r2 = {o.r[q][e], o.r[q][e + 1]};
;         S0[p] = S0[p] * w2 + (v0 * k2 + n0 * b2);
;         S1[p] = S1[p] * w2 + (v1 * k2 + n1 * b2);
;         y0 += S0[p] * r2; y1 += S1[p] * r2;
;     }
;     f32x2 y = {oct_sum(y0[0] + y0[1]), oct_sum(y1[0] + y1[1])};
;     return y;
; }
; DEVINL void rwkv_scan(const Ctx& c, int layer, int b, int hd, const unsigned* cnt3, int nP, float* lds) {
;     ...
;                 for (int tt = 0; tt < TC; ++tt) {
;                     if (tt + 2 < TC) rw_load_ops(ops[(tt + 2) % 3], buf, tt + 2, jo, i0);
;                     const f32x2 y = rw_step(S0, S1, ops[tt % 3]);
;                     *(f32x2*)(syw + tt * 64 + i0) = y;
	v_pk_fma_f32 v[16:17], v[24:25], v[90:91], 0 op_sel_hi:[1,1,0]
	v_pk_fma_f32 v[18:19], v[44:45], v[90:91], 0 op_sel_hi:[1,1,0]
	v_pk_fma_f32 v[16:17], v[46:47], v[92:93], v[16:17]
	v_pk_fma_f32 v[18:19], v[42:43], v[92:93], v[18:19]
	v_pk_fma_f32 v[16:17], v[60:61], v[94:95], v[16:17]
	v_pk_fma_f32 v[18:19], v[40:41], v[94:95], v[18:19]
	v_pk_fma_f32 v[16:17], v[28:29], v[96:97], v[16:17]
	v_pk_fma_f32 v[18:19], v[26:27], v[96:97], v[18:19]
	v_add_f32_e32 v20, v16, v17
	v_add_f32_e32 v21, v18, v19
	v_add_f32_dpp v32, v32, v32 quad_perm:[1,0,3,2] row_mask:0xf bank_mask:0xf bound_ctrl:1
	v_add_f32_dpp v33, v33, v33 quad_perm:[1,0,3,2] row_mask:0xf bank_mask:0xf bound_ctrl:1
	v_add_f32_dpp v20, v20, v20 quad_perm:[1,0,3,2] row_mask:0xf bank_mask:0xf bound_ctrl:1
	v_add_f32_dpp v21, v21, v21 quad_perm:[1,0,3,2] row_mask:0xf bank_mask:0xf bound_ctrl:1
	v_add_f32_dpp v32, v32, v32 quad_perm:[2,3,0,1] row_mask:0xf bank_mask:0xf bound_ctrl:1
	v_add_f32_dpp v33, v33, v33 quad_perm:[2,3,0,1] row_mask:0xf bank_mask:0xf bound_ctrl:1
	v_add_f32_dpp v20, v20, v20 quad_perm:[2,3,0,1] row_mask:0xf bank_mask:0xf bound_ctrl:1
	v_add_f32_dpp v21, v21, v21 quad_perm:[2,3,0,1] row_mask:0xf bank_mask:0xf bound_ctrl:1
	v_add_f32_dpp v32, v32, v32 row_half_mirror row_mask:0xf bank_mask:0xf bound_ctrl:1
	v_add_f32_dpp v33, v33, v33 row_half_mirror row_mask:0xf bank_mask:0xf bound_ctrl:1
	v_add_f32_dpp v20, v20, v20 row_half_mirror row_mask:0xf bank_mask:0xf bound_ctrl:1
	v_add_f32_dpp v38, v21, v21 row_half_mirror row_mask:0xf bank_mask:0xf bound_ctrl:1
	ds_write_b64 v64, v[32:33] offset:3328
	v_pk_mul_f32 v[34:35], v[98:99], v[20:21] op_sel_hi:[1,0] neg_lo:[0,1] neg_hi:[0,1]
	v_pk_mul_f32 v[36:37], v[98:99], v[38:39] op_sel_hi:[1,0] neg_lo:[0,1] neg_hi:[0,1]
	v_pk_mul_f32 v[48:49], v[100:101], v[20:21] op_sel_hi:[1,0] neg_lo:[0,1] neg_hi:[0,1]
	v_pk_mul_f32 v[50:51], v[100:101], v[38:39] op_sel_hi:[1,0] neg_lo:[0,1] neg_hi:[0,1]
	v_pk_mul_f32 v[52:53], v[102:103], v[20:21] op_sel_hi:[1,0] neg_lo:[0,1] neg_hi:[0,1]
	v_pk_mul_f32 v[54:55], v[102:103], v[38:39] op_sel_hi:[1,0] neg_lo:[0,1] neg_hi:[0,1]
	v_pk_mul_f32 v[56:57], v[104:105], v[20:21] op_sel_hi:[1,0] neg_lo:[0,1] neg_hi:[0,1]
	v_pk_mul_f32 v[58:59], v[104:105], v[38:39] op_sel_hi:[1,0] neg_lo:[0,1] neg_hi:[0,1]
	v_pk_fma_f32 v[34:35], v[82:83], v[106:107], v[34:35] op_sel_hi:[1,0,1]
	v_pk_fma_f32 v[36:37], v[82:83], v[106:107], v[36:37] op_sel:[0,1,0]
	v_pk_fma_f32 v[48:49], v[84:85], v[106:107], v[48:49] op_sel_hi:[1,0,1]
	v_pk_fma_f32 v[50:51], v[84:85], v[106:107], v[50:51] op_sel:[0,1,0]
	v_pk_fma_f32 v[52:53], v[86:87], v[106:107], v[52:53] op_sel_hi:[1,0,1]
	v_pk_fma_f32 v[54:55], v[86:87], v[106:107], v[54:55] op_sel:[0,1,0]
	v_pk_fma_f32 v[56:57], v[88:89], v[106:107], v[56:57] op_sel_hi:[1,0,1]
	v_pk_fma_f32 v[58:59], v[88:89], v[106:107], v[58:59] op_sel:[0,1,0]
	v_pk_fma_f32 v[24:25], v[74:75], v[24:25], v[34:35]
	v_pk_fma_f32 v[44:45], v[74:75], v[44:45], v[36:37]
	v_pk_fma_f32 v[46:47], v[76:77], v[46:47], v[48:49]
	v_pk_fma_f32 v[42:43], v[76:77], v[42:43], v[50:51]
	v_pk_fma_f32 v[60:61], v[78:79], v[60:61], v[52:53]
	v_pk_fma_f32 v[40:41], v[78:79], v[40:41], v[54:55]
	v_pk_fma_f32 v[28:29], v[80:81], v[28:29], v[56:57]
	v_pk_fma_f32 v[26:27], v[80:81], v[26:27], v[58:59]
	v_pk_fma_f32 v[22:23], v[66:67], v[24:25], 0 op_sel_hi:[1,1,0]
	v_pk_fma_f32 v[30:31], v[66:67], v[44:45], 0 op_sel_hi:[1,1,0]
	v_pk_fma_f32 v[22:23], v[68:69], v[46:47], v[22:23]
	v_pk_fma_f32 v[30:31], v[68:69], v[42:43], v[30:31]
	v_pk_fma_f32 v[22:23], v[70:71], v[60:61], v[22:23]
	v_pk_fma_f32 v[30:31], v[70:71], v[40:41], v[30:31]
	v_pk_fma_f32 v[22:23], v[72:73], v[28:29], v[22:23]
	v_pk_fma_f32 v[30:31], v[72:73], v[26:27], v[30:31]
	v_add_f32_e32 v32, v22, v23
	v_add_f32_e32 v33, v30, v31
	s_waitcnt lgkmcnt(1)
; DEVINL float oct_sum(float v) { v += DPPF(v, 0xB1); v += DPPF(v, 0x4E); v += DPPF(v, 0x141); return v; }
; DEVINL f32x2 rw_step(f32x2 (&S0)[4], f32x2 (&S1)[4], const RwOps& o) {
;     f32x2 a0 = {0.f, 0.f}, a1 = {0.f, 0.f};
; #pragma unroll
;     for (int p = 0; p < 4; ++p) { const f32x2 kk2 = {o.kk[p >> 1][(p & 1) * 2], o.kk[p >> 1][(p & 1) * 2 + 1]}; a0 += S0[p] * kk2; a1 += S1[p] * kk2; }
;     const float sa0 = oct_sum(a0[0] + a0[1]), sa1 = oct_sum(a1[0] + a1[1]);
;     const f32x2 n0 = {-sa0, -sa0}, n1 = {-sa1, -sa1}, v0 = {o.v[0], o.v[0]}, v1 = {o.v[1], o.v[1]};
;     f32x2 y0 = {0.f, 0.f}, y1 = {0.f, 0.f};
; #pragma unroll
;     for (int p = 0; p < 4; ++p) {
;         const int q = p >> 1, e = (p & 1) * 2;
;         const f32x2 k2 = {o.k[q][e], o.k[q][e + 1]}, b2 = {o.b[q][e], o.b[q][e + 1]}, w2 = {o.w[q][e], o.w[q][e + 1]}, r2 = {o.r[q][e], o.r[q][e + 1]};
;         S0[p] = S0[p] * w2 + (v0 * k2 + n0 * b2);
;         S1[p] = S1[p] * w2 + (v1 * k2 + n1 * b2);
;         y0 += S0[p] * r2; y1 += S1[p] * r2;
;     }
;     f32x2 y = {oct_sum(y0[0] + y0[1]), oct_sum(y1[0] + y1[1])};
;     return y;
; }
; DEVINL void rwkv_scan(const Ctx& c, int layer, int b, int hd, const unsigned* cnt3, int nP, float* lds) {
;     ...
;                 for (int tt = 0; tt < TC; ++tt) {
;                     if (tt + 2 < TC) rw_load_ops(ops[(tt + 2) % 3], buf, tt + 2, jo, i0);
;                     const f32x2 y = rw_step(S0, S1, ops[tt % 3]);
;                     *(f32x2*)(syw + tt * 64 + i0) = y;
	v_pk_fma_f32 v[16:17], v[24:25], v[198:199], 0 op_sel_hi:[1,1,0]
	v_pk_fma_f32 v[18:19], v[44:45], v[198:199], 0 op_sel_hi:[1,1,0]
	v_pk_fma_f32 v[16:17], v[46:47], v[200:201], v[16:17]
	v_pk_fma_f32 v[18:19], v[42:43], v[200:201], v[18:19]
	v_pk_fma_f32 v[16:17], v[60:61], v[202:203], v[16:17]
	v_pk_fma_f32 v[18:19], v[40:41], v[202:203], v[18:19]
	v_pk_fma_f32 v[16:17], v[28:29], v[204:205], v[16:17]
	v_pk_fma_f32 v[18:19], v[26:27], v[204:205], v[18:19]
	v_add_f32_e32 v20, v16, v17
	v_add_f32_e32 v21, v18, v19
	v_add_f32_dpp v32, v32, v32 quad_perm:[1,0,3,2] row_mask:0xf bank_mask:0xf bound_ctrl:1
	v_add_f32_dpp v33, v33, v33 quad_perm:[1,0,3,2] row_mask:0xf bank_mask:0xf bound_ctrl:1
	v_add_f32_dpp v20, v20, v20 quad_perm:[1,0,3,2] row_mask:0xf bank_mask:0xf bound_ctrl:1
	v_add_f32_dpp v21, v21, v21 quad_perm:[1,0,3,2] row_mask:0xf bank_mask:0xf bound_ctrl:1
	v_add_f32_dpp v32, v32, v32 quad_perm:[2,3,0,1] row_mask:0xf bank_mask:0xf bound_ctrl:1
	v_add_f32_dpp v33, v33, v33 quad_perm:[2,3,0,1] row_mask:0xf bank_mask:0xf bound_ctrl:1
	v_add_f32_dpp v20, v20, v20 quad_perm:[2,3,0,1] row_mask:0xf bank_mask:0xf bound_ctrl:1
	v_add_f32_dpp v21, v21, v21 quad_perm:[2,3,0,1] row_mask:0xf bank_mask:0xf bound_ctrl:1
	v_add_f32_dpp v32, v32, v32 row_half_mirror row_mask:0xf bank_mask:0xf bound_ctrl:1
	v_add_f32_dpp v33, v33, v33 row_half_mirror row_mask:0xf bank_mask:0xf bound_ctrl:1
	v_add_f32_dpp v20, v20, v20 row_half_mirror row_mask:0xf bank_mask:0xf bound_ctrl:1
	v_add_f32_dpp v38, v21, v21 row_half_mirror row_mask:0xf bank_mask:0xf bound_ctrl:1
	ds_write_b64 v64, v[32:33] offset:3584
	v_pk_mul_f32 v[34:35], v[206:207], v[20:21] op_sel_hi:[1,0] neg_lo:[0,1] neg_hi:[0,1]
	v_pk_mul_f32 v[36:37], v[206:207], v[38:39] op_sel_hi:[1,0] neg_lo:[0,1] neg_hi:[0,1]
	v_pk_mul_f32 v[48:49], v[208:209], v[20:21] op_sel_hi:[1,0] neg_lo:[0,1] neg_hi:[0,1]
	v_pk_mul_f32 v[50:51], v[208:209], v[38:39] op_sel_hi:[1,0] neg_lo:[0,1] neg_hi:[0,1]
	v_pk_mul_f32 v[52:53], v[210:211], v[20:21] op_sel_hi:[1,0] neg_lo:[0,1] neg_hi:[0,1]
	v_pk_mul_f32 v[54:55], v[210:211], v[38:39] op_sel_hi:[1,0] neg_lo:[0,1] neg_hi:[0,1]
	v_pk_mul_f32 v[56:57], v[212:213], v[20:21] op_sel_hi:[1,0] neg_lo:[0,1] neg_hi:[0,1]
	v_pk_mul_f32 v[58:59], v[212:213], v[38:39] op_sel_hi:[1,0] neg_lo:[0,1] neg_hi:[0,1]
	v_pk_fma_f32 v[34:35], v[190:191], v[214:215], v[34:35] op_sel_hi:[1,0,1]
	v_pk_fma_f32 v[36:37], v[190:191], v[214:215], v[36:37] op_sel:[0,1,0]
	v_pk_fma_f32 v[48:49], v[192:193], v[214:215], v[48:49] op_sel_hi:[1,0,1]
	v_pk_fma_f32 v[50:51], v[192:193], v[214:215], v[50:51] op_sel:[0,1,0]
	v_pk_fma_f32 v[52:53], v[194:195], v[214:215], v[52:53] op_sel_hi:[1,0,1]
	v_pk_fma_f32 v[54:55], v[194:195], v[214:215], v[54:55] op_sel:[0,1,0]
	v_pk_fma_f32 v[56:57], v[196:197], v[214:215], v[56:57] op_sel_hi:[1,0,1]
	v_pk_fma_f32 v[58:59], v[196:197], v[214:215], v[58:59] op_sel:[0,1,0]
	v_pk_fma_f32 v[24:25], v[182:183], v[24:25], v[34:35]
	v_pk_fma_f32 v[44:45], v[182:183], v[44:45], v[36:37]
	v_pk_fma_f32 v[46:47], v[184:185], v[46:47], v[48:49]
	v_pk_fma_f32 v[42:43], v[184:185], v[42:43], v[50:51]
	v_pk_fma_f32 v[60:61], v[186:187], v[60:61], v[52:53]
	v_pk_fma_f32 v[40:41], v[186:187], v[40:41], v[54:55]
	v_pk_fma_f32 v[28:29], v[188:189], v[28:29], v[56:57]
	v_pk_fma_f32 v[26:27], v[188:189], v[26:27], v[58:59]
	v_pk_fma_f32 v[22:23], v[174:175], v[24:25], 0 op_sel_hi:[1,1,0]
	v_pk_fma_f32 v[30:31], v[174:175], v[44:45], 0 op_sel_hi:[1,1,0]
	v_pk_fma_f32 v[22:23], v[176:177], v[46:47], v[22:23]
	v_pk_fma_f32 v[30:31], v[176:177], v[42:43], v[30:31]
	v_pk_fma_f32 v[22:23], v[178:179], v[60:61], v[22:23]
	v_pk_fma_f32 v[30:31], v[178:179], v[40:41], v[30:31]
	v_pk_fma_f32 v[22:23], v[180:181], v[28:29], v[22:23]
	v_pk_fma_f32 v[30:31], v[180:181], v[26:27], v[30:31]
	v_add_f32_e32 v32, v22, v23
	v_add_f32_e32 v33, v30, v31
	s_nop 1
	v_add_f32_dpp v32, v32, v32 quad_perm:[1,0,3,2] row_mask:0xf bank_mask:0xf bound_ctrl:1
	v_add_f32_dpp v33, v33, v33 quad_perm:[1,0,3,2] row_mask:0xf bank_mask:0xf bound_ctrl:1
	s_nop 0
	v_add_f32_dpp v32, v32, v32 quad_perm:[2,3,0,1] row_mask:0xf bank_mask:0xf bound_ctrl:1
	v_add_f32_dpp v33, v33, v33 quad_perm:[2,3,0,1] row_mask:0xf bank_mask:0xf bound_ctrl:1
	s_nop 0
	v_add_f32_dpp v32, v32, v32 row_half_mirror row_mask:0xf bank_mask:0xf bound_ctrl:1
	v_add_f32_dpp v33, v33, v33 row_half_mirror row_mask:0xf bank_mask:0xf bound_ctrl:1
	s_nop 0
	ds_write_b64 v64, v[32:33] offset:3840
	s_branch .LBB0_316

;     DEVINL bf16_t* Y() const { return (bf16_t*)(ws + OFF_Y); }
; DEVINL void rwkv_scan(const Ctx& c, int layer, int b, int hd, const unsigned* cnt3, int nP, float* lds) {
;     ...
;     for (int ch = 0; ch <= NCH; ++ch) {
;         if (w < 4) {
;             if (ch < NCH) {
;                 const float* buf = lds + (ch % 3) * STG;
;                 float* syw = sy + (ch & 1) * TC * 64;
;                 RwOps ops[3];
;                 rw_load_ops(ops[0], buf, 0, jo, i0);
;                 rw_load_ops(ops[1], buf, 1, jo, i0);
; #pragma unroll
;                 for (int tt = 0; tt < TC; ++tt) {
;                     if (tt + 2 < TC) rw_load_ops(ops[(tt + 2) % 3], buf, tt + 2, jo, i0);
;                     const f32x2 y = rw_step(S0, S1, ops[tt % 3]);
;                     *(f32x2*)(syw + tt * 64 + i0) = y;
;                 }
;             }
;         } else {
;             const int ht = tid - 256, hw = w - 4;
;             if (ch + 1 < NCH) rw_stage_write(raw, lds + ((ch + 1) % 3) * STG, ht);
;             if (ch + 2 < NCH) {
;                 const unsigned need = (unsigned)(layer * 16 + (ch + 2) / (7 * nP) + 1);
;                 if (need > have) { rw_wait_ready(cnt3, need, nP); have = need; }
;                 rw_stage_load(raw, rwbase, b * L + (ch + 2) * TC, hd, ht);
;             }
;             if (ch >= 1) {
;                 const int pc = ch - 1, t0 = b * L + pc * TC;
;                 const float* buf = lds + (pc % 3) * STG;
;                 const float* syr = sy + (pc & 1) * TC * 64;
; #pragma unroll
;                 for (int k4 = 0; k4 < TC / 4; ++k4) {
;                     const int tt = hw + 4 * k4, e = tt * 64 + lane;
;                     const float y = syr[e];
;                     const size_t idx = (size_t)(t0 + tt) * 512 + hd * 64 + lane;
;                     const float gate = buf[6 * TC * 64 + e];
;                     const float s1 = wave_sum_dpp(y), s2 = wave_sum_dpp(y * y), s3 = wave_sum_dpp(buf[e] * buf[2 * TC * 64 + e] * rkv);
;                     const float mean = s1 * (1.f / 64.f);
;                     const float var = fmaxf(s2 * (1.f / 64.f) - mean * mean, 0.f);
;                     const float yn = (y - mean) * rsqrtf(var + 64e-5f) * lng + lnb;
;                     Y[idx] = f2bf((yn + s3 * buf[3 * TC * 64 + e]) * gate);
;                 }
;             }
;         }
;         __syncthreads();
;     }
; }
.LBB0_351:
	s_setprio 0
	s_movk_i32 s39, 0x80
